# MMA segment edges: s_setprio 1 before the opening barrier, redundant lgkmcnt(0) and mid-block toggles removed, s_setprio 0 after the closing barrier (on top of v17)
# speedup vs baseline: 1.0136x; 1.0136x over previous
; #define PG8_STAGE(bufoff, gbase, voff) do { _Pragma("unroll") for (int _i = 0; _i < 2; ++_i) \
;         __builtin_amdgcn_global_load_lds((const unsigned*)((const char*)(gbase) + (voff)[_i]), (PG8_LAS unsigned*)(lds + (bufoff) + ldsw + _i * 8192), 16, 0, 0); } while (0)
; #define PG8_LDA(dst, b, h) do { _Pragma("unroll") for (int m = 0; m < 4; ++m) _Pragma("unroll") for (int k = 0; k < 2; ++k) dst[m][k] = *(const PG8_LAS bf16x8*)(lds + PG8_SA(b, h) + aoff + m * 2048 + k * 1024); } while (0)
; #define PG8_LDB(dst, b, h) do { _Pragma("unroll") for (int n = 0; n < 2; ++n) _Pragma("unroll") for (int k = 0; k < 2; ++k) dst[n][k] = *(const PG8_LAS bf16x8*)(lds + PG8_SB(b, h) + boff + n * 2048 + k * 1024); } while (0)
; #define PG8_WAIT_V(n) asm volatile("s_waitcnt vmcnt(" #n ")" ::: "memory")
; #define PG8_WAIT_L(n) asm volatile("s_waitcnt lgkmcnt(" #n ")" ::: "memory")
; #define PG8_BAR __builtin_amdgcn_s_barrier()
; #define PG8_SCHED __builtin_amdgcn_sched_barrier(0)
; template <class Epi, class Sched, bool ALIGN_EPI = false, bool SP2 = false>
; __device__ __forceinline__ void gemm_phase(PG8_LAS unsigned char* lds, const Gemm g, const Sched& S, const Epi& E) {
;     ...
;         const bool has_next = S.next(ui + 1, nxt);
;         const char* nA = has_next ? (const char*)g.A + (size_t)nxt.pm * tstep : cA; const char* nB = has_next ? (const char*)g.Bt + (size_t)nxt.pn * tstep : cB;
;         for (int t = 0; t < nt; t += 2) {
;             const bool last = (t == nt - 2);
;             const char* a1 = cA + (size_t)(t + 1) * kstep;
;             const char* a2 = last ? nA : cA + (size_t)(t + 2) * kstep; const char* b2 = last ? nB : cB + (size_t)(t + 2) * kstep;
;             const char* a3 = a2 + kstep; const char* b3 = b2 + kstep;
;             if (last && has_next) S.a_ready(nxt);
;             if constexpr (SP2) {
;             PG8_LDB(B0, 0, 0); PG8_LDB(B1, 0, 1); PG8_SCHED; PG8_LDA(At, 0, 0); PG8_STAGE(PG8_SA(1, 1), a1 + hstep, voffA);
;             PG8_WAIT_V(8); PG8_WAIT_L(0); PG8_BAR; PG8_MMA(0, 0, At, B0); PG8_MMA(0, 1, At, B1); PG8_BAR; PG8_SCHED;
;             PG8_LDA(At, 0, 1); PG8_STAGE(PG8_SB(0, 0), b2, voffB); PG8_STAGE(PG8_SB(0, 1), b2 + hstep, voffB); PG8_STAGE(PG8_SA(0, 0), a2, voffA);
;             PG8_WAIT_V(8); PG8_WAIT_L(0); PG8_BAR; PG8_MMA(1, 0, At, B0); PG8_MMA(1, 1, At, B1); PG8_BAR; PG8_SCHED;
.LBB0_224:
	s_ashr_i32 s15, s14, 31
	s_lshl_b64 s[16:17], s[14:15], 19
	s_add_u32 s16, s34, s16
	s_addc_u32 s17, s35, s17
	s_and_b64 s[18:19], s[2:3], exec
	s_cselect_b32 s5, s17, s23
	s_cselect_b32 s15, s16, s22
	s_ashr_i32 s13, s12, 31
	s_lshl_b64 s[18:19], s[12:13], 19
	s_add_u32 s18, s38, s18
	s_addc_u32 s19, s39, s19
	s_and_b64 s[26:27], s[2:3], exec
	s_cselect_b32 s13, s19, s25
	s_cselect_b32 s21, s18, s24
	s_add_u32 s22, s22, 0x40080
	s_addc_u32 s23, s23, 0
	s_add_u32 s49, s24, 0x100
	s_addc_u32 s50, s25, 0
	s_mov_b32 s51, -2
	s_add_u32 s24, s22, 0xfffc0080
	s_addc_u32 s25, s23, -1
	s_add_i32 s52, 0, 0x10000
	s_cmp_eq_u32 s51, 12
	s_cselect_b32 s27, s5, s25
	s_cselect_b32 s26, s15, s24
	v_add_u32_e32 v138, s52, v149
	s_cselect_b32 s25, s13, s50
	s_cselect_b32 s24, s21, s49
	s_add_i32 s55, 0, 0x14000
	ds_read_b128 v[144:147], v138
	ds_read_b128 v[154:157], v138 offset:1024
	ds_read_b128 v[158:161], v138 offset:2048
	ds_read_b128 v[162:165], v138 offset:3072
	v_add_u32_e32 v138, s55, v149
	ds_read_b128 v[166:169], v138
	ds_read_b128 v[170:173], v138 offset:1024
	ds_read_b128 v[174:177], v138 offset:2048
	ds_read_b128 v[178:181], v138 offset:3072
	v_lshl_add_u64 v[138:139], s[22:23], 0, v[136:137]
	s_add_i32 m0, s41, 0xc000
	ds_read_b128 v[182:185], v152
	ds_read_b128 v[186:189], v152 offset:1024
	ds_read_b128 v[190:193], v152 offset:2048
	ds_read_b128 v[194:197], v152 offset:3072
	ds_read_b128 v[198:201], v152 offset:4096
	ds_read_b128 v[202:205], v152 offset:5120
	ds_read_b128 v[224:227], v152 offset:6144
	ds_read_b128 v[228:231], v152 offset:7168
	global_load_lds_dwordx4 v[138:139], off
	v_lshl_add_u64 v[138:139], s[22:23], 0, v[142:143]
	s_add_i32 m0, s41, 0xe000
	s_nop 0
	global_load_lds_dwordx4 v[138:139], off
	s_waitcnt vmcnt(8)
	s_waitcnt lgkmcnt(0)
	s_setprio 1
	s_barrier
	v_mfma_f32_16x16x32_bf16 v[126:129], v[144:147], v[182:185], 0
	v_mfma_f32_16x16x32_bf16 v[122:125], v[158:161], v[182:185], 0
	v_mfma_f32_16x16x32_bf16 v[110:113], v[144:147], v[190:193], 0
	v_mfma_f32_16x16x32_bf16 v[106:109], v[158:161], v[190:193], 0
	v_mfma_f32_16x16x32_bf16 v[94:97], v[144:147], v[198:201], 0
	v_mfma_f32_16x16x32_bf16 v[90:93], v[158:161], v[198:201], 0
	v_mfma_f32_16x16x32_bf16 v[78:81], v[144:147], v[224:227], 0
	v_mfma_f32_16x16x32_bf16 v[74:77], v[158:161], v[224:227], 0
	v_mfma_f32_16x16x32_bf16 v[126:129], v[154:157], v[186:189], v[126:129]
	v_mfma_f32_16x16x32_bf16 v[122:125], v[162:165], v[186:189], v[122:125]
	v_mfma_f32_16x16x32_bf16 v[110:113], v[154:157], v[194:197], v[110:113]
	v_mfma_f32_16x16x32_bf16 v[106:109], v[162:165], v[194:197], v[106:109]
	v_mfma_f32_16x16x32_bf16 v[94:97], v[154:157], v[202:205], v[94:97]
	v_mfma_f32_16x16x32_bf16 v[90:93], v[162:165], v[202:205], v[90:93]
	v_mfma_f32_16x16x32_bf16 v[78:81], v[154:157], v[228:231], v[78:81]
	v_mfma_f32_16x16x32_bf16 v[74:77], v[162:165], v[228:231], v[74:77]
	v_mfma_f32_16x16x32_bf16 v[118:121], v[166:169], v[182:185], 0
	v_mfma_f32_16x16x32_bf16 v[114:117], v[174:177], v[182:185], 0
	v_mfma_f32_16x16x32_bf16 v[102:105], v[166:169], v[190:193], 0
	v_mfma_f32_16x16x32_bf16 v[98:101], v[174:177], v[190:193], 0
	v_mfma_f32_16x16x32_bf16 v[86:89], v[166:169], v[198:201], 0
	v_mfma_f32_16x16x32_bf16 v[82:85], v[174:177], v[198:201], 0
	v_mfma_f32_16x16x32_bf16 v[70:73], v[166:169], v[224:227], 0
	v_mfma_f32_16x16x32_bf16 v[66:69], v[174:177], v[224:227], 0
	v_mfma_f32_16x16x32_bf16 v[118:121], v[170:173], v[186:189], v[118:121]
	v_mfma_f32_16x16x32_bf16 v[114:117], v[178:181], v[186:189], v[114:117]
	v_mfma_f32_16x16x32_bf16 v[102:105], v[170:173], v[194:197], v[102:105]
	v_mfma_f32_16x16x32_bf16 v[98:101], v[178:181], v[194:197], v[98:101]
	v_mfma_f32_16x16x32_bf16 v[86:89], v[170:173], v[202:205], v[86:89]
	v_mfma_f32_16x16x32_bf16 v[82:85], v[178:181], v[202:205], v[82:85]
	v_mfma_f32_16x16x32_bf16 v[70:73], v[170:173], v[228:231], v[70:73]
	v_mfma_f32_16x16x32_bf16 v[66:69], v[178:181], v[228:231], v[66:69]
	s_barrier
	s_setprio 0
	s_add_i32 s52, s52, s31
	v_lshl_add_u64 v[138:139], s[24:25], 0, v[0:1]
	s_mov_b32 m0, s52
	ds_read_b128 v[182:185], v152 offset:16384
	ds_read_b128 v[186:189], v152 offset:17408
	ds_read_b128 v[190:193], v152 offset:18432
	ds_read_b128 v[194:197], v152 offset:19456
	ds_read_b128 v[198:201], v152 offset:20480
	ds_read_b128 v[202:205], v152 offset:21504
	ds_read_b128 v[224:227], v152 offset:22528
	ds_read_b128 v[228:231], v152 offset:23552
	global_load_lds_dwordx4 v[138:139], off
	s_add_i32 m0, s52, 0x2000
	s_add_u32 s52, s24, 0x40000
	v_lshl_add_u64 v[140:141], s[24:25], 0, v[134:135]
	s_addc_u32 s53, s25, 0
	s_add_i32 s55, s55, s31
	global_load_lds_dwordx4 v[140:141], off
	v_lshl_add_u64 v[232:233], s[52:53], 0, v[0:1]
	s_mov_b32 m0, s55
	v_lshl_add_u64 v[234:235], s[26:27], 0, v[132:133]
	global_load_lds_dwordx4 v[232:233], off
	v_lshl_add_u64 v[232:233], s[52:53], 0, v[134:135]
	s_add_i32 m0, s55, 0x2000
	s_nop 0
	global_load_lds_dwordx4 v[232:233], off
	v_lshl_add_u64 v[232:233], s[26:27], 0, v[130:131]
	s_mov_b32 m0, s41
	s_nop 0
	global_load_lds_dwordx4 v[232:233], off
	s_mov_b32 m0, s42
	s_nop 0
	global_load_lds_dwordx4 v[234:235], off
	s_waitcnt vmcnt(8)
	s_waitcnt lgkmcnt(0)
	s_setprio 1
	s_barrier
; #define PG8_STAGE(bufoff, gbase, voff) do { _Pragma("unroll") for (int _i = 0; _i < 2; ++_i) \
;         __builtin_amdgcn_global_load_lds((const unsigned*)((const char*)(gbase) + (voff)[_i]), (PG8_LAS unsigned*)(lds + (bufoff) + ldsw + _i * 8192), 16, 0, 0); } while (0)
; #define PG8_LDA(dst, b, h) do { _Pragma("unroll") for (int m = 0; m < 4; ++m) _Pragma("unroll") for (int k = 0; k < 2; ++k) dst[m][k] = *(const PG8_LAS bf16x8*)(lds + PG8_SA(b, h) + aoff + m * 2048 + k * 1024); } while (0)
; #define PG8_LDB(dst, b, h) do { _Pragma("unroll") for (int n = 0; n < 2; ++n) _Pragma("unroll") for (int k = 0; k < 2; ++k) dst[n][k] = *(const PG8_LAS bf16x8*)(lds + PG8_SB(b, h) + boff + n * 2048 + k * 1024); } while (0)
; #define PG8_MMA(ai, bj, At, Bt) do { __builtin_amdgcn_s_setprio(1); _Pragma("unroll") for (int m = 0; m < 4; ++m) _Pragma("unroll") for (int n = 0; n < 2; ++n) _Pragma("unroll") for (int k = 0; k < 2; ++k) \
;         acc[ai][bj][m][n] = __builtin_amdgcn_mfma_f32_16x16x32_bf16(Bt[n][k], At[m][k], acc[ai][bj][m][n], 0, 0, 0); __builtin_amdgcn_s_setprio(0); } while (0)
; #define PG8_WAIT_V(n) asm volatile("s_waitcnt vmcnt(" #n ")" ::: "memory")
; #define PG8_WAIT_L(n) asm volatile("s_waitcnt lgkmcnt(" #n ")" ::: "memory")
; #define PG8_BAR __builtin_amdgcn_s_barrier()
; #define PG8_SCHED __builtin_amdgcn_sched_barrier(0)
; template <class Epi, class Sched, bool ALIGN_EPI = false, bool SP2 = false>
; __device__ __forceinline__ void gemm_phase(PG8_LAS unsigned char* lds, const Gemm g, const Sched& S, const Epi& E) {
;     ...
;             PG8_WAIT_V(8); PG8_WAIT_L(0); PG8_BAR; PG8_MMA(1, 0, At, B0); PG8_MMA(1, 1, At, B1); PG8_BAR; PG8_SCHED;
;             PG8_LDB(B0, 1, 0); PG8_LDB(B1, 1, 1); PG8_SCHED; PG8_LDA(At, 1, 0); PG8_STAGE(PG8_SA(0, 1), a2 + hstep, voffA);
;             PG8_WAIT_V(8); PG8_WAIT_L(0); PG8_BAR; PG8_MMA(0, 0, At, B0); PG8_MMA(0, 1, At, B1); PG8_BAR; PG8_SCHED;
	v_mfma_f32_16x16x32_bf16 v[62:65], v[144:147], v[182:185], 0
	v_mfma_f32_16x16x32_bf16 v[58:61], v[158:161], v[182:185], 0
	v_mfma_f32_16x16x32_bf16 v[46:49], v[144:147], v[190:193], 0
	v_mfma_f32_16x16x32_bf16 v[42:45], v[158:161], v[190:193], 0
	v_mfma_f32_16x16x32_bf16 v[30:33], v[144:147], v[198:201], 0
	v_mfma_f32_16x16x32_bf16 v[26:29], v[158:161], v[198:201], 0
	v_mfma_f32_16x16x32_bf16 v[14:17], v[144:147], v[224:227], 0
	v_mfma_f32_16x16x32_bf16 v[10:13], v[158:161], v[224:227], 0
	v_mfma_f32_16x16x32_bf16 v[62:65], v[154:157], v[186:189], v[62:65]
	v_mfma_f32_16x16x32_bf16 v[58:61], v[162:165], v[186:189], v[58:61]
	v_mfma_f32_16x16x32_bf16 v[46:49], v[154:157], v[194:197], v[46:49]
	v_mfma_f32_16x16x32_bf16 v[42:45], v[162:165], v[194:197], v[42:45]
	v_mfma_f32_16x16x32_bf16 v[30:33], v[154:157], v[202:205], v[30:33]
	v_mfma_f32_16x16x32_bf16 v[26:29], v[162:165], v[202:205], v[26:29]
	v_mfma_f32_16x16x32_bf16 v[14:17], v[154:157], v[228:231], v[14:17]
	v_mfma_f32_16x16x32_bf16 v[10:13], v[162:165], v[228:231], v[10:13]
	v_mfma_f32_16x16x32_bf16 v[54:57], v[166:169], v[182:185], 0
	v_mfma_f32_16x16x32_bf16 v[50:53], v[174:177], v[182:185], 0
	v_mfma_f32_16x16x32_bf16 v[38:41], v[166:169], v[190:193], 0
	v_mfma_f32_16x16x32_bf16 v[34:37], v[174:177], v[190:193], 0
	v_mfma_f32_16x16x32_bf16 v[22:25], v[166:169], v[198:201], 0
	v_mfma_f32_16x16x32_bf16 v[18:21], v[174:177], v[198:201], 0
	v_mfma_f32_16x16x32_bf16 v[6:9], v[166:169], v[224:227], 0
	v_mfma_f32_16x16x32_bf16 v[2:5], v[174:177], v[224:227], 0
	v_mfma_f32_16x16x32_bf16 v[54:57], v[170:173], v[186:189], v[54:57]
	v_mfma_f32_16x16x32_bf16 v[50:53], v[178:181], v[186:189], v[50:53]
	v_mfma_f32_16x16x32_bf16 v[38:41], v[170:173], v[194:197], v[38:41]
	v_mfma_f32_16x16x32_bf16 v[34:37], v[178:181], v[194:197], v[34:37]
	v_mfma_f32_16x16x32_bf16 v[22:25], v[170:173], v[202:205], v[22:25]
	v_mfma_f32_16x16x32_bf16 v[18:21], v[178:181], v[202:205], v[18:21]
	v_mfma_f32_16x16x32_bf16 v[6:9], v[170:173], v[228:231], v[6:9]
	v_mfma_f32_16x16x32_bf16 v[2:5], v[178:181], v[228:231], v[2:5]
	s_barrier
	s_setprio 0
	s_add_i32 s52, 0, 0x18000
	v_add_u32_e32 v153, s52, v149
	s_add_i32 s53, 0, 0x1c000
	ds_read_b128 v[144:147], v153
	ds_read_b128 v[154:157], v153 offset:1024
	ds_read_b128 v[158:161], v153 offset:2048
	ds_read_b128 v[162:165], v153 offset:3072
	v_add_u32_e32 v153, s53, v149
	ds_read_b128 v[166:169], v153
	ds_read_b128 v[170:173], v153 offset:1024
	ds_read_b128 v[174:177], v153 offset:2048
	ds_read_b128 v[178:181], v153 offset:3072
	s_add_u32 s26, s26, 0x40000
	s_addc_u32 s27, s27, 0
	s_mov_b32 m0, s43
	v_lshl_add_u64 v[236:237], s[26:27], 0, v[130:131]
	ds_read_b128 v[182:185], v152 offset:32768
	ds_read_b128 v[186:189], v152 offset:33792
	ds_read_b128 v[190:193], v152 offset:34816
	ds_read_b128 v[194:197], v152 offset:35840
	ds_read_b128 v[198:201], v152 offset:36864
	ds_read_b128 v[202:205], v152 offset:37888
	ds_read_b128 v[224:227], v152 offset:38912
	ds_read_b128 v[228:231], v152 offset:39936
	global_load_lds_dwordx4 v[236:237], off
	v_lshl_add_u64 v[236:237], s[26:27], 0, v[132:133]
	s_mov_b32 m0, s44
	s_nop 0
	global_load_lds_dwordx4 v[236:237], off
	s_waitcnt vmcnt(8)
	s_waitcnt lgkmcnt(0)
	s_setprio 1
	s_barrier
	v_mfma_f32_16x16x32_bf16 v[126:129], v[144:147], v[182:185], v[126:129]
	v_mfma_f32_16x16x32_bf16 v[122:125], v[158:161], v[182:185], v[122:125]
	v_mfma_f32_16x16x32_bf16 v[110:113], v[144:147], v[190:193], v[110:113]
	v_mfma_f32_16x16x32_bf16 v[106:109], v[158:161], v[190:193], v[106:109]
	v_mfma_f32_16x16x32_bf16 v[94:97], v[144:147], v[198:201], v[94:97]
	v_mfma_f32_16x16x32_bf16 v[90:93], v[158:161], v[198:201], v[90:93]
	v_mfma_f32_16x16x32_bf16 v[78:81], v[144:147], v[224:227], v[78:81]
	v_mfma_f32_16x16x32_bf16 v[74:77], v[158:161], v[224:227], v[74:77]
	v_mfma_f32_16x16x32_bf16 v[126:129], v[154:157], v[186:189], v[126:129]
	v_mfma_f32_16x16x32_bf16 v[122:125], v[162:165], v[186:189], v[122:125]
	v_mfma_f32_16x16x32_bf16 v[110:113], v[154:157], v[194:197], v[110:113]
	v_mfma_f32_16x16x32_bf16 v[106:109], v[162:165], v[194:197], v[106:109]
	v_mfma_f32_16x16x32_bf16 v[94:97], v[154:157], v[202:205], v[94:97]
	v_mfma_f32_16x16x32_bf16 v[90:93], v[162:165], v[202:205], v[90:93]
	v_mfma_f32_16x16x32_bf16 v[78:81], v[154:157], v[228:231], v[78:81]
	v_mfma_f32_16x16x32_bf16 v[74:77], v[162:165], v[228:231], v[74:77]
	v_mfma_f32_16x16x32_bf16 v[118:121], v[166:169], v[182:185], v[118:121]
	v_mfma_f32_16x16x32_bf16 v[114:117], v[174:177], v[182:185], v[114:117]
	v_mfma_f32_16x16x32_bf16 v[102:105], v[166:169], v[190:193], v[102:105]
	v_mfma_f32_16x16x32_bf16 v[98:101], v[174:177], v[190:193], v[98:101]
	v_mfma_f32_16x16x32_bf16 v[86:89], v[166:169], v[198:201], v[86:89]
	v_mfma_f32_16x16x32_bf16 v[82:85], v[174:177], v[198:201], v[82:85]
	v_mfma_f32_16x16x32_bf16 v[70:73], v[166:169], v[224:227], v[70:73]
	v_mfma_f32_16x16x32_bf16 v[66:69], v[174:177], v[224:227], v[66:69]
	v_mfma_f32_16x16x32_bf16 v[118:121], v[170:173], v[186:189], v[118:121]
	v_mfma_f32_16x16x32_bf16 v[114:117], v[178:181], v[186:189], v[114:117]
	v_mfma_f32_16x16x32_bf16 v[102:105], v[170:173], v[194:197], v[102:105]
	v_mfma_f32_16x16x32_bf16 v[98:101], v[178:181], v[194:197], v[98:101]
	v_mfma_f32_16x16x32_bf16 v[86:89], v[170:173], v[202:205], v[86:89]
	v_mfma_f32_16x16x32_bf16 v[82:85], v[178:181], v[202:205], v[82:85]
	v_mfma_f32_16x16x32_bf16 v[70:73], v[170:173], v[228:231], v[70:73]
	v_mfma_f32_16x16x32_bf16 v[66:69], v[178:181], v[228:231], v[66:69]
	s_barrier
; #define PG8_STAGE(bufoff, gbase, voff) do { _Pragma("unroll") for (int _i = 0; _i < 2; ++_i) \
;         __builtin_amdgcn_global_load_lds((const unsigned*)((const char*)(gbase) + (voff)[_i]), (PG8_LAS unsigned*)(lds + (bufoff) + ldsw + _i * 8192), 16, 0, 0); } while (0)
; #define PG8_LDA(dst, b, h) do { _Pragma("unroll") for (int m = 0; m < 4; ++m) _Pragma("unroll") for (int k = 0; k < 2; ++k) dst[m][k] = *(const PG8_LAS bf16x8*)(lds + PG8_SA(b, h) + aoff + m * 2048 + k * 1024); } while (0)
; #define PG8_LDB(dst, b, h) do { _Pragma("unroll") for (int n = 0; n < 2; ++n) _Pragma("unroll") for (int k = 0; k < 2; ++k) dst[n][k] = *(const PG8_LAS bf16x8*)(lds + PG8_SB(b, h) + boff + n * 2048 + k * 1024); } while (0)
; #define PG8_MMA(ai, bj, At, Bt) do { __builtin_amdgcn_s_setprio(1); _Pragma("unroll") for (int m = 0; m < 4; ++m) _Pragma("unroll") for (int n = 0; n < 2; ++n) _Pragma("unroll") for (int k = 0; k < 2; ++k) \
;         acc[ai][bj][m][n] = __builtin_amdgcn_mfma_f32_16x16x32_bf16(Bt[n][k], At[m][k], acc[ai][bj][m][n], 0, 0, 0); __builtin_amdgcn_s_setprio(0); } while (0)
; #define PG8_WAIT_V(n) asm volatile("s_waitcnt vmcnt(" #n ")" ::: "memory")
; #define PG8_WAIT_L(n) asm volatile("s_waitcnt lgkmcnt(" #n ")" ::: "memory")
; #define PG8_BAR __builtin_amdgcn_s_barrier()
; #define PG8_SCHED __builtin_amdgcn_sched_barrier(0)
; template <class Epi, class Sched, bool ALIGN_EPI = false, bool SP2 = false>
; __device__ __forceinline__ void gemm_phase(PG8_LAS unsigned char* lds, const Gemm g, const Sched& S, const Epi& E) {
;     ...
;         for (int t = 0; t < nt; t += 2) {
;             const bool last = (t == nt - 2);
;             const char* a1 = cA + (size_t)(t + 1) * kstep;
;             const char* a2 = last ? nA : cA + (size_t)(t + 2) * kstep; const char* b2 = last ? nB : cB + (size_t)(t + 2) * kstep;
;             const char* a3 = a2 + kstep; const char* b3 = b2 + kstep;
;             if (last && has_next) S.a_ready(nxt);
;             if constexpr (SP2) {
;             PG8_LDB(B0, 0, 0); PG8_LDB(B1, 0, 1); PG8_SCHED; PG8_LDA(At, 0, 0); PG8_STAGE(PG8_SA(1, 1), a1 + hstep, voffA);
;     ...
;             PG8_LDA(At, 1, 1); PG8_STAGE(PG8_SB(1, 0), b3, voffB); PG8_STAGE(PG8_SB(1, 1), b3 + hstep, voffB); PG8_STAGE(PG8_SA(1, 0), a3, voffA);
;             PG8_WAIT_V(8); PG8_WAIT_L(0); PG8_BAR; PG8_MMA(1, 0, At, B0); PG8_MMA(1, 1, At, B1); PG8_BAR; PG8_SCHED;
	s_setprio 0
	s_add_i32 s26, s52, s31
	v_lshl_add_u64 v[138:139], v[138:139], 0, s[86:87]
	s_mov_b32 m0, s26
	ds_read_b128 v[182:185], v152 offset:49152
	ds_read_b128 v[186:189], v152 offset:50176
	ds_read_b128 v[190:193], v152 offset:51200
	ds_read_b128 v[194:197], v152 offset:52224
	ds_read_b128 v[198:201], v152 offset:53248
	ds_read_b128 v[202:205], v152 offset:54272
	ds_read_b128 v[224:227], v152 offset:55296
	ds_read_b128 v[228:231], v152 offset:56320
	global_load_lds_dwordx4 v[138:139], off
	s_add_i32 m0, s26, 0x2000
	s_add_u32 s24, s24, 0x40080
	v_lshl_add_u64 v[138:139], v[140:141], 0, s[86:87]
	s_addc_u32 s25, s25, 0
	s_add_i32 s26, s53, s31
	global_load_lds_dwordx4 v[138:139], off
	v_lshl_add_u64 v[138:139], s[24:25], 0, v[0:1]
	s_mov_b32 m0, s26
	s_nop 0
	global_load_lds_dwordx4 v[138:139], off
	v_lshl_add_u64 v[138:139], s[24:25], 0, v[134:135]
	s_add_i32 m0, s26, 0x2000
	s_nop 0
	global_load_lds_dwordx4 v[138:139], off
	v_lshl_add_u64 v[138:139], v[232:233], 0, s[86:87]
	s_mov_b32 m0, s45
	s_nop 0
	global_load_lds_dwordx4 v[138:139], off
	v_lshl_add_u64 v[138:139], v[234:235], 0, s[86:87]
	s_mov_b32 m0, s46
	s_nop 0
	global_load_lds_dwordx4 v[138:139], off
	s_waitcnt vmcnt(8)
	s_waitcnt lgkmcnt(0)
	s_setprio 1
	s_barrier
	v_mfma_f32_16x16x32_bf16 v[62:65], v[144:147], v[182:185], v[62:65]
	v_mfma_f32_16x16x32_bf16 v[58:61], v[158:161], v[182:185], v[58:61]
	v_mfma_f32_16x16x32_bf16 v[46:49], v[144:147], v[190:193], v[46:49]
	v_mfma_f32_16x16x32_bf16 v[42:45], v[158:161], v[190:193], v[42:45]
	v_mfma_f32_16x16x32_bf16 v[30:33], v[144:147], v[198:201], v[30:33]
	v_mfma_f32_16x16x32_bf16 v[26:29], v[158:161], v[198:201], v[26:29]
	v_mfma_f32_16x16x32_bf16 v[14:17], v[144:147], v[224:227], v[14:17]
	v_mfma_f32_16x16x32_bf16 v[10:13], v[158:161], v[224:227], v[10:13]
	v_mfma_f32_16x16x32_bf16 v[62:65], v[154:157], v[186:189], v[62:65]
	v_mfma_f32_16x16x32_bf16 v[58:61], v[162:165], v[186:189], v[58:61]
	v_mfma_f32_16x16x32_bf16 v[46:49], v[154:157], v[194:197], v[46:49]
	v_mfma_f32_16x16x32_bf16 v[42:45], v[162:165], v[194:197], v[42:45]
	v_mfma_f32_16x16x32_bf16 v[30:33], v[154:157], v[202:205], v[30:33]
	v_mfma_f32_16x16x32_bf16 v[26:29], v[162:165], v[202:205], v[26:29]
	v_mfma_f32_16x16x32_bf16 v[14:17], v[154:157], v[228:231], v[14:17]
	v_mfma_f32_16x16x32_bf16 v[10:13], v[162:165], v[228:231], v[10:13]
	v_mfma_f32_16x16x32_bf16 v[54:57], v[166:169], v[182:185], v[54:57]
	v_mfma_f32_16x16x32_bf16 v[50:53], v[174:177], v[182:185], v[50:53]
	v_mfma_f32_16x16x32_bf16 v[38:41], v[166:169], v[190:193], v[38:41]
	v_mfma_f32_16x16x32_bf16 v[34:37], v[174:177], v[190:193], v[34:37]
	v_mfma_f32_16x16x32_bf16 v[22:25], v[166:169], v[198:201], v[22:25]
	v_mfma_f32_16x16x32_bf16 v[18:21], v[174:177], v[198:201], v[18:21]
	v_mfma_f32_16x16x32_bf16 v[6:9], v[166:169], v[224:227], v[6:9]
	v_mfma_f32_16x16x32_bf16 v[2:5], v[174:177], v[224:227], v[2:5]
	v_mfma_f32_16x16x32_bf16 v[54:57], v[170:173], v[186:189], v[54:57]
	v_mfma_f32_16x16x32_bf16 v[50:53], v[178:181], v[186:189], v[50:53]
	v_mfma_f32_16x16x32_bf16 v[38:41], v[170:173], v[194:197], v[38:41]
	v_mfma_f32_16x16x32_bf16 v[34:37], v[178:181], v[194:197], v[34:37]
	v_mfma_f32_16x16x32_bf16 v[22:25], v[170:173], v[202:205], v[22:25]
	v_mfma_f32_16x16x32_bf16 v[18:21], v[178:181], v[202:205], v[18:21]
	v_mfma_f32_16x16x32_bf16 v[6:9], v[170:173], v[228:231], v[6:9]
	v_mfma_f32_16x16x32_bf16 v[2:5], v[178:181], v[228:231], v[2:5]
	s_barrier
	s_setprio 0
	s_add_i32 s51, s51, 2
	s_add_u32 s22, s22, 0x100
	s_addc_u32 s23, s23, 0
	s_add_u32 s49, s49, 0x100
	s_addc_u32 s50, s50, 0
	s_cmp_gt_u32 s51, 13
	s_cbranch_scc1 .Lpeel_exit_sw
.LBB0_225:
	s_add_u32 s24, s22, 0xfffc0080
	s_addc_u32 s25, s23, -1
	s_add_i32 s52, 0, 0x10000
	s_cmp_eq_u32 s51, 12
	s_cselect_b32 s27, s5, s25
	s_cselect_b32 s26, s15, s24
	v_add_u32_e32 v138, s52, v149
	s_cselect_b32 s25, s13, s50
	s_cselect_b32 s24, s21, s49
	s_add_i32 s55, 0, 0x14000
	ds_read_b128 v[144:147], v138
	ds_read_b128 v[154:157], v138 offset:1024
	ds_read_b128 v[158:161], v138 offset:2048
	ds_read_b128 v[162:165], v138 offset:3072
	v_add_u32_e32 v138, s55, v149
	ds_read_b128 v[166:169], v138
	ds_read_b128 v[170:173], v138 offset:1024
	ds_read_b128 v[174:177], v138 offset:2048
	ds_read_b128 v[178:181], v138 offset:3072
	v_lshl_add_u64 v[138:139], s[22:23], 0, v[136:137]
	s_add_i32 m0, s41, 0xc000
	ds_read_b128 v[182:185], v152
	ds_read_b128 v[186:189], v152 offset:1024
	ds_read_b128 v[190:193], v152 offset:2048
	ds_read_b128 v[194:197], v152 offset:3072
	ds_read_b128 v[198:201], v152 offset:4096
	ds_read_b128 v[202:205], v152 offset:5120
	ds_read_b128 v[224:227], v152 offset:6144
	ds_read_b128 v[228:231], v152 offset:7168
	global_load_lds_dwordx4 v[138:139], off
	v_lshl_add_u64 v[138:139], s[22:23], 0, v[142:143]
	s_add_i32 m0, s41, 0xe000
	s_nop 0
	global_load_lds_dwordx4 v[138:139], off
	s_waitcnt vmcnt(8)
	s_waitcnt lgkmcnt(0)
	s_setprio 1
	s_barrier
; #define PG8_STAGE(bufoff, gbase, voff) do { _Pragma("unroll") for (int _i = 0; _i < 2; ++_i) \
;         __builtin_amdgcn_global_load_lds((const unsigned*)((const char*)(gbase) + (voff)[_i]), (PG8_LAS unsigned*)(lds + (bufoff) + ldsw + _i * 8192), 16, 0, 0); } while (0)
; #define PG8_LDA(dst, b, h) do { _Pragma("unroll") for (int m = 0; m < 4; ++m) _Pragma("unroll") for (int k = 0; k < 2; ++k) dst[m][k] = *(const PG8_LAS bf16x8*)(lds + PG8_SA(b, h) + aoff + m * 2048 + k * 1024); } while (0)
; #define PG8_MMA(ai, bj, At, Bt) do { __builtin_amdgcn_s_setprio(1); _Pragma("unroll") for (int m = 0; m < 4; ++m) _Pragma("unroll") for (int n = 0; n < 2; ++n) _Pragma("unroll") for (int k = 0; k < 2; ++k) \
;         acc[ai][bj][m][n] = __builtin_amdgcn_mfma_f32_16x16x32_bf16(Bt[n][k], At[m][k], acc[ai][bj][m][n], 0, 0, 0); __builtin_amdgcn_s_setprio(0); } while (0)
; #define PG8_WAIT_V(n) asm volatile("s_waitcnt vmcnt(" #n ")" ::: "memory")
; #define PG8_WAIT_L(n) asm volatile("s_waitcnt lgkmcnt(" #n ")" ::: "memory")
; #define PG8_BAR __builtin_amdgcn_s_barrier()
; #define PG8_SCHED __builtin_amdgcn_sched_barrier(0)
; template <class Epi, class Sched, bool ALIGN_EPI = false, bool SP2 = false>
; __device__ __forceinline__ void gemm_phase(PG8_LAS unsigned char* lds, const Gemm g, const Sched& S, const Epi& E) {
;     ...
;             PG8_WAIT_V(8); PG8_WAIT_L(0); PG8_BAR; PG8_MMA(0, 0, At, B0); PG8_MMA(0, 1, At, B1); PG8_BAR; PG8_SCHED;
;             PG8_LDA(At, 0, 1); PG8_STAGE(PG8_SB(0, 0), b2, voffB); PG8_STAGE(PG8_SB(0, 1), b2 + hstep, voffB); PG8_STAGE(PG8_SA(0, 0), a2, voffA);
;             PG8_WAIT_V(8); PG8_WAIT_L(0); PG8_BAR; PG8_MMA(1, 0, At, B0); PG8_MMA(1, 1, At, B1); PG8_BAR; PG8_SCHED;
	v_mfma_f32_16x16x32_bf16 v[126:129], v[144:147], v[182:185], v[126:129]
	v_mfma_f32_16x16x32_bf16 v[122:125], v[158:161], v[182:185], v[122:125]
	v_mfma_f32_16x16x32_bf16 v[110:113], v[144:147], v[190:193], v[110:113]
	v_mfma_f32_16x16x32_bf16 v[106:109], v[158:161], v[190:193], v[106:109]
	v_mfma_f32_16x16x32_bf16 v[94:97], v[144:147], v[198:201], v[94:97]
	v_mfma_f32_16x16x32_bf16 v[90:93], v[158:161], v[198:201], v[90:93]
	v_mfma_f32_16x16x32_bf16 v[78:81], v[144:147], v[224:227], v[78:81]
	v_mfma_f32_16x16x32_bf16 v[74:77], v[158:161], v[224:227], v[74:77]
	v_mfma_f32_16x16x32_bf16 v[126:129], v[154:157], v[186:189], v[126:129]
	v_mfma_f32_16x16x32_bf16 v[122:125], v[162:165], v[186:189], v[122:125]
	v_mfma_f32_16x16x32_bf16 v[110:113], v[154:157], v[194:197], v[110:113]
	v_mfma_f32_16x16x32_bf16 v[106:109], v[162:165], v[194:197], v[106:109]
	v_mfma_f32_16x16x32_bf16 v[94:97], v[154:157], v[202:205], v[94:97]
	v_mfma_f32_16x16x32_bf16 v[90:93], v[162:165], v[202:205], v[90:93]
	v_mfma_f32_16x16x32_bf16 v[78:81], v[154:157], v[228:231], v[78:81]
	v_mfma_f32_16x16x32_bf16 v[74:77], v[162:165], v[228:231], v[74:77]
	v_mfma_f32_16x16x32_bf16 v[118:121], v[166:169], v[182:185], v[118:121]
	v_mfma_f32_16x16x32_bf16 v[114:117], v[174:177], v[182:185], v[114:117]
	v_mfma_f32_16x16x32_bf16 v[102:105], v[166:169], v[190:193], v[102:105]
	v_mfma_f32_16x16x32_bf16 v[98:101], v[174:177], v[190:193], v[98:101]
	v_mfma_f32_16x16x32_bf16 v[86:89], v[166:169], v[198:201], v[86:89]
	v_mfma_f32_16x16x32_bf16 v[82:85], v[174:177], v[198:201], v[82:85]
	v_mfma_f32_16x16x32_bf16 v[70:73], v[166:169], v[224:227], v[70:73]
	v_mfma_f32_16x16x32_bf16 v[66:69], v[174:177], v[224:227], v[66:69]
	v_mfma_f32_16x16x32_bf16 v[118:121], v[170:173], v[186:189], v[118:121]
	v_mfma_f32_16x16x32_bf16 v[114:117], v[178:181], v[186:189], v[114:117]
	v_mfma_f32_16x16x32_bf16 v[102:105], v[170:173], v[194:197], v[102:105]
	v_mfma_f32_16x16x32_bf16 v[98:101], v[178:181], v[194:197], v[98:101]
	v_mfma_f32_16x16x32_bf16 v[86:89], v[170:173], v[202:205], v[86:89]
	v_mfma_f32_16x16x32_bf16 v[82:85], v[178:181], v[202:205], v[82:85]
	v_mfma_f32_16x16x32_bf16 v[70:73], v[170:173], v[228:231], v[70:73]
	v_mfma_f32_16x16x32_bf16 v[66:69], v[178:181], v[228:231], v[66:69]
	s_barrier
	s_setprio 0
	s_add_i32 s52, s52, s31
	v_lshl_add_u64 v[138:139], s[24:25], 0, v[0:1]
	s_mov_b32 m0, s52
	ds_read_b128 v[182:185], v152 offset:16384
	ds_read_b128 v[186:189], v152 offset:17408
	ds_read_b128 v[190:193], v152 offset:18432
	ds_read_b128 v[194:197], v152 offset:19456
	ds_read_b128 v[198:201], v152 offset:20480
	ds_read_b128 v[202:205], v152 offset:21504
	ds_read_b128 v[224:227], v152 offset:22528
	ds_read_b128 v[228:231], v152 offset:23552
	global_load_lds_dwordx4 v[138:139], off
	s_add_i32 m0, s52, 0x2000
	s_add_u32 s52, s24, 0x40000
	v_lshl_add_u64 v[140:141], s[24:25], 0, v[134:135]
	s_addc_u32 s53, s25, 0
	s_add_i32 s55, s55, s31
	global_load_lds_dwordx4 v[140:141], off
	v_lshl_add_u64 v[232:233], s[52:53], 0, v[0:1]
	s_mov_b32 m0, s55
	v_lshl_add_u64 v[234:235], s[26:27], 0, v[132:133]
	global_load_lds_dwordx4 v[232:233], off
	v_lshl_add_u64 v[232:233], s[52:53], 0, v[134:135]
	s_add_i32 m0, s55, 0x2000
	s_nop 0
	global_load_lds_dwordx4 v[232:233], off
	v_lshl_add_u64 v[232:233], s[26:27], 0, v[130:131]
	s_mov_b32 m0, s41
	s_nop 0
	global_load_lds_dwordx4 v[232:233], off
	s_mov_b32 m0, s42
	s_nop 0
	global_load_lds_dwordx4 v[234:235], off
	s_waitcnt vmcnt(8)
	s_waitcnt lgkmcnt(0)
	s_setprio 1
	s_barrier
	v_mfma_f32_16x16x32_bf16 v[62:65], v[144:147], v[182:185], v[62:65]
	v_mfma_f32_16x16x32_bf16 v[58:61], v[158:161], v[182:185], v[58:61]
	v_mfma_f32_16x16x32_bf16 v[46:49], v[144:147], v[190:193], v[46:49]
	v_mfma_f32_16x16x32_bf16 v[42:45], v[158:161], v[190:193], v[42:45]
	v_mfma_f32_16x16x32_bf16 v[30:33], v[144:147], v[198:201], v[30:33]
	v_mfma_f32_16x16x32_bf16 v[26:29], v[158:161], v[198:201], v[26:29]
	v_mfma_f32_16x16x32_bf16 v[14:17], v[144:147], v[224:227], v[14:17]
	v_mfma_f32_16x16x32_bf16 v[10:13], v[158:161], v[224:227], v[10:13]
	v_mfma_f32_16x16x32_bf16 v[62:65], v[154:157], v[186:189], v[62:65]
	v_mfma_f32_16x16x32_bf16 v[58:61], v[162:165], v[186:189], v[58:61]
	v_mfma_f32_16x16x32_bf16 v[46:49], v[154:157], v[194:197], v[46:49]
	v_mfma_f32_16x16x32_bf16 v[42:45], v[162:165], v[194:197], v[42:45]
	v_mfma_f32_16x16x32_bf16 v[30:33], v[154:157], v[202:205], v[30:33]
	v_mfma_f32_16x16x32_bf16 v[26:29], v[162:165], v[202:205], v[26:29]
	v_mfma_f32_16x16x32_bf16 v[14:17], v[154:157], v[228:231], v[14:17]
	v_mfma_f32_16x16x32_bf16 v[10:13], v[162:165], v[228:231], v[10:13]
	v_mfma_f32_16x16x32_bf16 v[54:57], v[166:169], v[182:185], v[54:57]
	v_mfma_f32_16x16x32_bf16 v[50:53], v[174:177], v[182:185], v[50:53]
	v_mfma_f32_16x16x32_bf16 v[38:41], v[166:169], v[190:193], v[38:41]
	v_mfma_f32_16x16x32_bf16 v[34:37], v[174:177], v[190:193], v[34:37]
	v_mfma_f32_16x16x32_bf16 v[22:25], v[166:169], v[198:201], v[22:25]
	v_mfma_f32_16x16x32_bf16 v[18:21], v[174:177], v[198:201], v[18:21]
	v_mfma_f32_16x16x32_bf16 v[6:9], v[166:169], v[224:227], v[6:9]
	v_mfma_f32_16x16x32_bf16 v[2:5], v[174:177], v[224:227], v[2:5]
	v_mfma_f32_16x16x32_bf16 v[54:57], v[170:173], v[186:189], v[54:57]
	v_mfma_f32_16x16x32_bf16 v[50:53], v[178:181], v[186:189], v[50:53]
	v_mfma_f32_16x16x32_bf16 v[38:41], v[170:173], v[194:197], v[38:41]
	v_mfma_f32_16x16x32_bf16 v[34:37], v[178:181], v[194:197], v[34:37]
	v_mfma_f32_16x16x32_bf16 v[22:25], v[170:173], v[202:205], v[22:25]
	v_mfma_f32_16x16x32_bf16 v[18:21], v[178:181], v[202:205], v[18:21]
	v_mfma_f32_16x16x32_bf16 v[6:9], v[170:173], v[228:231], v[6:9]
	v_mfma_f32_16x16x32_bf16 v[2:5], v[178:181], v[228:231], v[2:5]
	s_barrier
; #define PG8_STAGE(bufoff, gbase, voff) do { _Pragma("unroll") for (int _i = 0; _i < 2; ++_i) \
;         __builtin_amdgcn_global_load_lds((const unsigned*)((const char*)(gbase) + (voff)[_i]), (PG8_LAS unsigned*)(lds + (bufoff) + ldsw + _i * 8192), 16, 0, 0); } while (0)
; #define PG8_LDA(dst, b, h) do { _Pragma("unroll") for (int m = 0; m < 4; ++m) _Pragma("unroll") for (int k = 0; k < 2; ++k) dst[m][k] = *(const PG8_LAS bf16x8*)(lds + PG8_SA(b, h) + aoff + m * 2048 + k * 1024); } while (0)
; #define PG8_LDB(dst, b, h) do { _Pragma("unroll") for (int n = 0; n < 2; ++n) _Pragma("unroll") for (int k = 0; k < 2; ++k) dst[n][k] = *(const PG8_LAS bf16x8*)(lds + PG8_SB(b, h) + boff + n * 2048 + k * 1024); } while (0)
; #define PG8_MMA(ai, bj, At, Bt) do { __builtin_amdgcn_s_setprio(1); _Pragma("unroll") for (int m = 0; m < 4; ++m) _Pragma("unroll") for (int n = 0; n < 2; ++n) _Pragma("unroll") for (int k = 0; k < 2; ++k) \
;         acc[ai][bj][m][n] = __builtin_amdgcn_mfma_f32_16x16x32_bf16(Bt[n][k], At[m][k], acc[ai][bj][m][n], 0, 0, 0); __builtin_amdgcn_s_setprio(0); } while (0)
; #define PG8_WAIT_V(n) asm volatile("s_waitcnt vmcnt(" #n ")" ::: "memory")
; #define PG8_WAIT_L(n) asm volatile("s_waitcnt lgkmcnt(" #n ")" ::: "memory")
; #define PG8_BAR __builtin_amdgcn_s_barrier()
; #define PG8_SCHED __builtin_amdgcn_sched_barrier(0)
; template <class Epi, class Sched, bool ALIGN_EPI = false, bool SP2 = false>
; __device__ __forceinline__ void gemm_phase(PG8_LAS unsigned char* lds, const Gemm g, const Sched& S, const Epi& E) {
;     ...
;             PG8_LDB(B0, 1, 0); PG8_LDB(B1, 1, 1); PG8_SCHED; PG8_LDA(At, 1, 0); PG8_STAGE(PG8_SA(0, 1), a2 + hstep, voffA);
;             PG8_WAIT_V(8); PG8_WAIT_L(0); PG8_BAR; PG8_MMA(0, 0, At, B0); PG8_MMA(0, 1, At, B1); PG8_BAR; PG8_SCHED;
	s_setprio 0
	s_add_i32 s52, 0, 0x18000
	v_add_u32_e32 v153, s52, v149
	s_add_i32 s53, 0, 0x1c000
	ds_read_b128 v[144:147], v153
	ds_read_b128 v[154:157], v153 offset:1024
	ds_read_b128 v[158:161], v153 offset:2048
	ds_read_b128 v[162:165], v153 offset:3072
	v_add_u32_e32 v153, s53, v149
	ds_read_b128 v[166:169], v153
	ds_read_b128 v[170:173], v153 offset:1024
	ds_read_b128 v[174:177], v153 offset:2048
	ds_read_b128 v[178:181], v153 offset:3072
	s_add_u32 s26, s26, 0x40000
	s_addc_u32 s27, s27, 0
	s_mov_b32 m0, s43
	v_lshl_add_u64 v[236:237], s[26:27], 0, v[130:131]
	ds_read_b128 v[182:185], v152 offset:32768
	ds_read_b128 v[186:189], v152 offset:33792
	ds_read_b128 v[190:193], v152 offset:34816
	ds_read_b128 v[194:197], v152 offset:35840
	ds_read_b128 v[198:201], v152 offset:36864
	ds_read_b128 v[202:205], v152 offset:37888
	ds_read_b128 v[224:227], v152 offset:38912
	ds_read_b128 v[228:231], v152 offset:39936
	global_load_lds_dwordx4 v[236:237], off
	v_lshl_add_u64 v[236:237], s[26:27], 0, v[132:133]
	s_mov_b32 m0, s44
	s_nop 0
	global_load_lds_dwordx4 v[236:237], off
	s_waitcnt vmcnt(8)
	s_waitcnt lgkmcnt(0)
	s_setprio 1
	s_barrier
	v_mfma_f32_16x16x32_bf16 v[126:129], v[144:147], v[182:185], v[126:129]
	v_mfma_f32_16x16x32_bf16 v[122:125], v[158:161], v[182:185], v[122:125]
	v_mfma_f32_16x16x32_bf16 v[110:113], v[144:147], v[190:193], v[110:113]
	v_mfma_f32_16x16x32_bf16 v[106:109], v[158:161], v[190:193], v[106:109]
	v_mfma_f32_16x16x32_bf16 v[94:97], v[144:147], v[198:201], v[94:97]
	v_mfma_f32_16x16x32_bf16 v[90:93], v[158:161], v[198:201], v[90:93]
	v_mfma_f32_16x16x32_bf16 v[78:81], v[144:147], v[224:227], v[78:81]
	v_mfma_f32_16x16x32_bf16 v[74:77], v[158:161], v[224:227], v[74:77]
	v_mfma_f32_16x16x32_bf16 v[126:129], v[154:157], v[186:189], v[126:129]
	v_mfma_f32_16x16x32_bf16 v[122:125], v[162:165], v[186:189], v[122:125]
	v_mfma_f32_16x16x32_bf16 v[110:113], v[154:157], v[194:197], v[110:113]
	v_mfma_f32_16x16x32_bf16 v[106:109], v[162:165], v[194:197], v[106:109]
	v_mfma_f32_16x16x32_bf16 v[94:97], v[154:157], v[202:205], v[94:97]
	v_mfma_f32_16x16x32_bf16 v[90:93], v[162:165], v[202:205], v[90:93]
	v_mfma_f32_16x16x32_bf16 v[78:81], v[154:157], v[228:231], v[78:81]
	v_mfma_f32_16x16x32_bf16 v[74:77], v[162:165], v[228:231], v[74:77]
	v_mfma_f32_16x16x32_bf16 v[118:121], v[166:169], v[182:185], v[118:121]
	v_mfma_f32_16x16x32_bf16 v[114:117], v[174:177], v[182:185], v[114:117]
	v_mfma_f32_16x16x32_bf16 v[102:105], v[166:169], v[190:193], v[102:105]
	v_mfma_f32_16x16x32_bf16 v[98:101], v[174:177], v[190:193], v[98:101]
	v_mfma_f32_16x16x32_bf16 v[86:89], v[166:169], v[198:201], v[86:89]
	v_mfma_f32_16x16x32_bf16 v[82:85], v[174:177], v[198:201], v[82:85]
	v_mfma_f32_16x16x32_bf16 v[70:73], v[166:169], v[224:227], v[70:73]
	v_mfma_f32_16x16x32_bf16 v[66:69], v[174:177], v[224:227], v[66:69]
	v_mfma_f32_16x16x32_bf16 v[118:121], v[170:173], v[186:189], v[118:121]
	v_mfma_f32_16x16x32_bf16 v[114:117], v[178:181], v[186:189], v[114:117]
	v_mfma_f32_16x16x32_bf16 v[102:105], v[170:173], v[194:197], v[102:105]
	v_mfma_f32_16x16x32_bf16 v[98:101], v[178:181], v[194:197], v[98:101]
	v_mfma_f32_16x16x32_bf16 v[86:89], v[170:173], v[202:205], v[86:89]
	v_mfma_f32_16x16x32_bf16 v[82:85], v[178:181], v[202:205], v[82:85]
	v_mfma_f32_16x16x32_bf16 v[70:73], v[170:173], v[228:231], v[70:73]
	v_mfma_f32_16x16x32_bf16 v[66:69], v[178:181], v[228:231], v[66:69]
	s_barrier
; #define PG8_STAGE(bufoff, gbase, voff) do { _Pragma("unroll") for (int _i = 0; _i < 2; ++_i) \
;         __builtin_amdgcn_global_load_lds((const unsigned*)((const char*)(gbase) + (voff)[_i]), (PG8_LAS unsigned*)(lds + (bufoff) + ldsw + _i * 8192), 16, 0, 0); } while (0)
; #define PG8_LDA(dst, b, h) do { _Pragma("unroll") for (int m = 0; m < 4; ++m) _Pragma("unroll") for (int k = 0; k < 2; ++k) dst[m][k] = *(const PG8_LAS bf16x8*)(lds + PG8_SA(b, h) + aoff + m * 2048 + k * 1024); } while (0)
; #define PG8_MMA(ai, bj, At, Bt) do { __builtin_amdgcn_s_setprio(1); _Pragma("unroll") for (int m = 0; m < 4; ++m) _Pragma("unroll") for (int n = 0; n < 2; ++n) _Pragma("unroll") for (int k = 0; k < 2; ++k) \
;         acc[ai][bj][m][n] = __builtin_amdgcn_mfma_f32_16x16x32_bf16(Bt[n][k], At[m][k], acc[ai][bj][m][n], 0, 0, 0); __builtin_amdgcn_s_setprio(0); } while (0)
; #define PG8_WAIT_V(n) asm volatile("s_waitcnt vmcnt(" #n ")" ::: "memory")
; #define PG8_WAIT_L(n) asm volatile("s_waitcnt lgkmcnt(" #n ")" ::: "memory")
; #define PG8_BAR __builtin_amdgcn_s_barrier()
; #define PG8_SCHED __builtin_amdgcn_sched_barrier(0)
; template <class Epi, class Sched, bool ALIGN_EPI = false, bool SP2 = false>
; __device__ __forceinline__ void gemm_phase(PG8_LAS unsigned char* lds, const Gemm g, const Sched& S, const Epi& E) {
;     ...
;             PG8_LDA(At, 1, 1); PG8_STAGE(PG8_SB(1, 0), b3, voffB); PG8_STAGE(PG8_SB(1, 1), b3 + hstep, voffB); PG8_STAGE(PG8_SA(1, 0), a3, voffA);
;             PG8_WAIT_V(8); PG8_WAIT_L(0); PG8_BAR; PG8_MMA(1, 0, At, B0); PG8_MMA(1, 1, At, B1); PG8_BAR; PG8_SCHED;
	s_setprio 0
	s_add_i32 s26, s52, s31
	v_lshl_add_u64 v[138:139], v[138:139], 0, s[86:87]
	s_mov_b32 m0, s26
	ds_read_b128 v[182:185], v152 offset:49152
	ds_read_b128 v[186:189], v152 offset:50176
	ds_read_b128 v[190:193], v152 offset:51200
	ds_read_b128 v[194:197], v152 offset:52224
	ds_read_b128 v[198:201], v152 offset:53248
	ds_read_b128 v[202:205], v152 offset:54272
	ds_read_b128 v[224:227], v152 offset:55296
	ds_read_b128 v[228:231], v152 offset:56320
	global_load_lds_dwordx4 v[138:139], off
	s_add_i32 m0, s26, 0x2000
	s_add_u32 s24, s24, 0x40080
	v_lshl_add_u64 v[138:139], v[140:141], 0, s[86:87]
	s_addc_u32 s25, s25, 0
	s_add_i32 s26, s53, s31
	global_load_lds_dwordx4 v[138:139], off
	v_lshl_add_u64 v[138:139], s[24:25], 0, v[0:1]
	s_mov_b32 m0, s26
	s_nop 0
	global_load_lds_dwordx4 v[138:139], off
	v_lshl_add_u64 v[138:139], s[24:25], 0, v[134:135]
	s_add_i32 m0, s26, 0x2000
	s_nop 0
	global_load_lds_dwordx4 v[138:139], off
	v_lshl_add_u64 v[138:139], v[232:233], 0, s[86:87]
	s_mov_b32 m0, s45
	s_nop 0
	global_load_lds_dwordx4 v[138:139], off
	v_lshl_add_u64 v[138:139], v[234:235], 0, s[86:87]
	s_mov_b32 m0, s46
	s_nop 0
	global_load_lds_dwordx4 v[138:139], off
	s_waitcnt vmcnt(8)
	s_waitcnt lgkmcnt(0)
	s_setprio 1
	s_barrier
	v_mfma_f32_16x16x32_bf16 v[62:65], v[144:147], v[182:185], v[62:65]
	v_mfma_f32_16x16x32_bf16 v[58:61], v[158:161], v[182:185], v[58:61]
	v_mfma_f32_16x16x32_bf16 v[46:49], v[144:147], v[190:193], v[46:49]
	v_mfma_f32_16x16x32_bf16 v[42:45], v[158:161], v[190:193], v[42:45]
	v_mfma_f32_16x16x32_bf16 v[30:33], v[144:147], v[198:201], v[30:33]
	v_mfma_f32_16x16x32_bf16 v[26:29], v[158:161], v[198:201], v[26:29]
	v_mfma_f32_16x16x32_bf16 v[14:17], v[144:147], v[224:227], v[14:17]
	v_mfma_f32_16x16x32_bf16 v[10:13], v[158:161], v[224:227], v[10:13]
	v_mfma_f32_16x16x32_bf16 v[62:65], v[154:157], v[186:189], v[62:65]
	v_mfma_f32_16x16x32_bf16 v[58:61], v[162:165], v[186:189], v[58:61]
	v_mfma_f32_16x16x32_bf16 v[46:49], v[154:157], v[194:197], v[46:49]
	v_mfma_f32_16x16x32_bf16 v[42:45], v[162:165], v[194:197], v[42:45]
	v_mfma_f32_16x16x32_bf16 v[30:33], v[154:157], v[202:205], v[30:33]
	v_mfma_f32_16x16x32_bf16 v[26:29], v[162:165], v[202:205], v[26:29]
	v_mfma_f32_16x16x32_bf16 v[14:17], v[154:157], v[228:231], v[14:17]
	v_mfma_f32_16x16x32_bf16 v[10:13], v[162:165], v[228:231], v[10:13]
	v_mfma_f32_16x16x32_bf16 v[54:57], v[166:169], v[182:185], v[54:57]
	v_mfma_f32_16x16x32_bf16 v[50:53], v[174:177], v[182:185], v[50:53]
	v_mfma_f32_16x16x32_bf16 v[38:41], v[166:169], v[190:193], v[38:41]
	v_mfma_f32_16x16x32_bf16 v[34:37], v[174:177], v[190:193], v[34:37]
	v_mfma_f32_16x16x32_bf16 v[22:25], v[166:169], v[198:201], v[22:25]
	v_mfma_f32_16x16x32_bf16 v[18:21], v[174:177], v[198:201], v[18:21]
	v_mfma_f32_16x16x32_bf16 v[6:9], v[166:169], v[224:227], v[6:9]
	v_mfma_f32_16x16x32_bf16 v[2:5], v[174:177], v[224:227], v[2:5]
	v_mfma_f32_16x16x32_bf16 v[54:57], v[170:173], v[186:189], v[54:57]
	v_mfma_f32_16x16x32_bf16 v[50:53], v[178:181], v[186:189], v[50:53]
	v_mfma_f32_16x16x32_bf16 v[38:41], v[170:173], v[194:197], v[38:41]
	v_mfma_f32_16x16x32_bf16 v[34:37], v[178:181], v[194:197], v[34:37]
	v_mfma_f32_16x16x32_bf16 v[22:25], v[170:173], v[202:205], v[22:25]
	v_mfma_f32_16x16x32_bf16 v[18:21], v[178:181], v[202:205], v[18:21]
	v_mfma_f32_16x16x32_bf16 v[6:9], v[170:173], v[228:231], v[6:9]
	v_mfma_f32_16x16x32_bf16 v[2:5], v[178:181], v[228:231], v[2:5]
	s_barrier
	s_setprio 0
	s_add_i32 s51, s51, 2
	s_add_u32 s22, s22, 0x100
	s_addc_u32 s23, s23, 0
	s_add_u32 s49, s49, 0x100
	s_addc_u32 s50, s50, 0
	s_cmp_gt_u32 s51, 13
	s_cbranch_scc0 .LBB0_225

; #define PG8_STAGE(bufoff, gbase, voff) do { _Pragma("unroll") for (int _i = 0; _i < 2; ++_i) \
;         __builtin_amdgcn_global_load_lds((const unsigned*)((const char*)(gbase) + (voff)[_i]), (PG8_LAS unsigned*)(lds + (bufoff) + ldsw + _i * 8192), 16, 0, 0); } while (0)
; #define PG8_LDA(dst, b, h) do { _Pragma("unroll") for (int m = 0; m < 4; ++m) _Pragma("unroll") for (int k = 0; k < 2; ++k) dst[m][k] = *(const PG8_LAS bf16x8*)(lds + PG8_SA(b, h) + aoff + m * 2048 + k * 1024); } while (0)
; #define PG8_LDB(dst, b, h) do { _Pragma("unroll") for (int n = 0; n < 2; ++n) _Pragma("unroll") for (int k = 0; k < 2; ++k) dst[n][k] = *(const PG8_LAS bf16x8*)(lds + PG8_SB(b, h) + boff + n * 2048 + k * 1024); } while (0)
; #define PG8_MMA(ai, bj, At, Bt) do { __builtin_amdgcn_s_setprio(1); _Pragma("unroll") for (int m = 0; m < 4; ++m) _Pragma("unroll") for (int n = 0; n < 2; ++n) _Pragma("unroll") for (int k = 0; k < 2; ++k) \
;         acc[ai][bj][m][n] = __builtin_amdgcn_mfma_f32_16x16x32_bf16(Bt[n][k], At[m][k], acc[ai][bj][m][n], 0, 0, 0); __builtin_amdgcn_s_setprio(0); } while (0)
; #define PG8_WAIT_V(n) asm volatile("s_waitcnt vmcnt(" #n ")" ::: "memory")
; #define PG8_WAIT_L(n) asm volatile("s_waitcnt lgkmcnt(" #n ")" ::: "memory")
; #define PG8_BAR __builtin_amdgcn_s_barrier()
; #define PG8_SCHED __builtin_amdgcn_sched_barrier(0)
; template <class Epi, class Sched, bool ALIGN_EPI = false, bool SP2 = false>
; __device__ __forceinline__ void gemm_phase(PG8_LAS unsigned char* lds, const Gemm g, const Sched& S, const Epi& E) {
;     ...
;             const bool last = (t == nt - 2);
;             const char* a1 = cA + (size_t)(t + 1) * kstep;
;             const char* a2 = last ? nA : cA + (size_t)(t + 2) * kstep; const char* b2 = last ? nB : cB + (size_t)(t + 2) * kstep;
;             const char* a3 = a2 + kstep; const char* b3 = b2 + kstep;
;             if (last && has_next) S.a_ready(nxt);
;             if constexpr (SP2) {
;             PG8_LDB(B0, 0, 0); PG8_LDB(B1, 0, 1); PG8_SCHED; PG8_LDA(At, 0, 0); PG8_STAGE(PG8_SA(1, 1), a1 + hstep, voffA);
;             PG8_WAIT_V(8); PG8_WAIT_L(0); PG8_BAR; PG8_MMA(0, 0, At, B0); PG8_MMA(0, 1, At, B1); PG8_BAR; PG8_SCHED;
;             PG8_LDA(At, 0, 1); PG8_STAGE(PG8_SB(0, 0), b2, voffB); PG8_STAGE(PG8_SB(0, 1), b2 + hstep, voffB); PG8_STAGE(PG8_SA(0, 0), a2, voffA);
.LBB0_362:
	s_add_u32 s16, s14, 0x100
	s_addc_u32 s17, s15, 0
	s_add_i32 s50, 0, 0x10000
	s_cmp_eq_u32 s49, 40
	s_cselect_b32 s21, s7, s17
	s_cselect_b32 s20, s6, s16
	v_add_u32_e32 v138, s50, v149
	s_cselect_b32 s19, s13, s48
	s_cselect_b32 s18, s12, s47
	s_add_i32 s51, 0, 0x14000
	ds_read_b128 v[144:147], v138
	ds_read_b128 v[152:155], v138 offset:1024
	ds_read_b128 v[156:159], v138 offset:2048
	ds_read_b128 v[160:163], v138 offset:3072
	v_add_u32_e32 v138, s51, v149
	ds_read_b128 v[164:167], v138
	ds_read_b128 v[168:171], v138 offset:1024
	ds_read_b128 v[172:175], v138 offset:2048
	ds_read_b128 v[176:179], v138 offset:3072
	v_lshl_add_u64 v[138:139], s[14:15], 0, v[136:137]
	s_add_i32 m0, s26, 0xc000
	ds_read_b128 v[180:183], v151
	ds_read_b128 v[184:187], v151 offset:1024
	ds_read_b128 v[188:191], v151 offset:2048
	ds_read_b128 v[192:195], v151 offset:3072
	ds_read_b128 v[196:199], v151 offset:4096
	ds_read_b128 v[200:203], v151 offset:5120
	ds_read_b128 v[224:227], v151 offset:6144
	ds_read_b128 v[228:231], v151 offset:7168
	global_load_lds_dwordx4 v[138:139], off
	v_lshl_add_u64 v[138:139], s[14:15], 0, v[142:143]
	s_add_i32 m0, s26, 0xe000
	s_nop 0
	global_load_lds_dwordx4 v[138:139], off
	s_waitcnt vmcnt(8)
	s_waitcnt lgkmcnt(0)
	s_setprio 1
	s_barrier
	v_mfma_f32_16x16x32_bf16 v[126:129], v[144:147], v[180:183], v[126:129]
	v_mfma_f32_16x16x32_bf16 v[122:125], v[156:159], v[180:183], v[122:125]
	v_mfma_f32_16x16x32_bf16 v[110:113], v[144:147], v[188:191], v[110:113]
	v_mfma_f32_16x16x32_bf16 v[106:109], v[156:159], v[188:191], v[106:109]
	v_mfma_f32_16x16x32_bf16 v[94:97], v[144:147], v[196:199], v[94:97]
	v_mfma_f32_16x16x32_bf16 v[90:93], v[156:159], v[196:199], v[90:93]
	v_mfma_f32_16x16x32_bf16 v[78:81], v[144:147], v[224:227], v[78:81]
	v_mfma_f32_16x16x32_bf16 v[74:77], v[156:159], v[224:227], v[74:77]
	v_mfma_f32_16x16x32_bf16 v[126:129], v[152:155], v[184:187], v[126:129]
	v_mfma_f32_16x16x32_bf16 v[122:125], v[160:163], v[184:187], v[122:125]
	v_mfma_f32_16x16x32_bf16 v[110:113], v[152:155], v[192:195], v[110:113]
	v_mfma_f32_16x16x32_bf16 v[106:109], v[160:163], v[192:195], v[106:109]
	v_mfma_f32_16x16x32_bf16 v[94:97], v[152:155], v[200:203], v[94:97]
	v_mfma_f32_16x16x32_bf16 v[90:93], v[160:163], v[200:203], v[90:93]
	v_mfma_f32_16x16x32_bf16 v[78:81], v[152:155], v[228:231], v[78:81]
	v_mfma_f32_16x16x32_bf16 v[74:77], v[160:163], v[228:231], v[74:77]
	v_mfma_f32_16x16x32_bf16 v[118:121], v[164:167], v[180:183], v[118:121]
	v_mfma_f32_16x16x32_bf16 v[114:117], v[172:175], v[180:183], v[114:117]
	v_mfma_f32_16x16x32_bf16 v[102:105], v[164:167], v[188:191], v[102:105]
	v_mfma_f32_16x16x32_bf16 v[98:101], v[172:175], v[188:191], v[98:101]
	v_mfma_f32_16x16x32_bf16 v[86:89], v[164:167], v[196:199], v[86:89]
	v_mfma_f32_16x16x32_bf16 v[82:85], v[172:175], v[196:199], v[82:85]
	v_mfma_f32_16x16x32_bf16 v[70:73], v[164:167], v[224:227], v[70:73]
	v_mfma_f32_16x16x32_bf16 v[66:69], v[172:175], v[224:227], v[66:69]
	v_mfma_f32_16x16x32_bf16 v[118:121], v[168:171], v[184:187], v[118:121]
	v_mfma_f32_16x16x32_bf16 v[114:117], v[176:179], v[184:187], v[114:117]
	v_mfma_f32_16x16x32_bf16 v[102:105], v[168:171], v[192:195], v[102:105]
	v_mfma_f32_16x16x32_bf16 v[98:101], v[176:179], v[192:195], v[98:101]
	v_mfma_f32_16x16x32_bf16 v[86:89], v[168:171], v[200:203], v[86:89]
	v_mfma_f32_16x16x32_bf16 v[82:85], v[176:179], v[200:203], v[82:85]
	v_mfma_f32_16x16x32_bf16 v[70:73], v[168:171], v[228:231], v[70:73]
	v_mfma_f32_16x16x32_bf16 v[66:69], v[176:179], v[228:231], v[66:69]
	s_barrier
	s_setprio 0
	s_add_i32 s14, s50, s23
	v_lshl_add_u64 v[138:139], s[18:19], 0, v[0:1]
	s_mov_b32 m0, s14
	ds_read_b128 v[180:183], v151 offset:16384
	ds_read_b128 v[184:187], v151 offset:17408
	ds_read_b128 v[188:191], v151 offset:18432
	ds_read_b128 v[192:195], v151 offset:19456
	ds_read_b128 v[196:199], v151 offset:20480
	ds_read_b128 v[200:203], v151 offset:21504
	ds_read_b128 v[224:227], v151 offset:22528
	ds_read_b128 v[228:231], v151 offset:23552
	global_load_lds_dwordx4 v[138:139], off
	s_add_i32 m0, s14, 0x2000
	s_add_u32 s14, s18, 0xb0000
	v_lshl_add_u64 v[140:141], s[18:19], 0, v[134:135]
	s_addc_u32 s15, s19, 0
	s_add_i32 s50, s51, s23
	global_load_lds_dwordx4 v[140:141], off
	v_lshl_add_u64 v[204:205], s[14:15], 0, v[0:1]
	s_mov_b32 m0, s50
	v_lshl_add_u64 v[232:233], s[20:21], 0, v[132:133]
	global_load_lds_dwordx4 v[204:205], off
	v_lshl_add_u64 v[204:205], s[14:15], 0, v[134:135]
	s_add_i32 m0, s50, 0x2000
	s_nop 0
	global_load_lds_dwordx4 v[204:205], off
	v_lshl_add_u64 v[204:205], s[20:21], 0, v[130:131]
	s_mov_b32 m0, s26
	s_nop 0
	global_load_lds_dwordx4 v[204:205], off
	s_mov_b32 m0, s27
	s_nop 0
	global_load_lds_dwordx4 v[232:233], off
	s_waitcnt vmcnt(8)
	s_waitcnt lgkmcnt(0)
	s_setprio 1
	s_barrier
; #define PG8_STAGE(bufoff, gbase, voff) do { _Pragma("unroll") for (int _i = 0; _i < 2; ++_i) \
;         __builtin_amdgcn_global_load_lds((const unsigned*)((const char*)(gbase) + (voff)[_i]), (PG8_LAS unsigned*)(lds + (bufoff) + ldsw + _i * 8192), 16, 0, 0); } while (0)
; #define PG8_LDA(dst, b, h) do { _Pragma("unroll") for (int m = 0; m < 4; ++m) _Pragma("unroll") for (int k = 0; k < 2; ++k) dst[m][k] = *(const PG8_LAS bf16x8*)(lds + PG8_SA(b, h) + aoff + m * 2048 + k * 1024); } while (0)
; #define PG8_LDB(dst, b, h) do { _Pragma("unroll") for (int n = 0; n < 2; ++n) _Pragma("unroll") for (int k = 0; k < 2; ++k) dst[n][k] = *(const PG8_LAS bf16x8*)(lds + PG8_SB(b, h) + boff + n * 2048 + k * 1024); } while (0)
; #define PG8_MMA(ai, bj, At, Bt) do { __builtin_amdgcn_s_setprio(1); _Pragma("unroll") for (int m = 0; m < 4; ++m) _Pragma("unroll") for (int n = 0; n < 2; ++n) _Pragma("unroll") for (int k = 0; k < 2; ++k) \
;         acc[ai][bj][m][n] = __builtin_amdgcn_mfma_f32_16x16x32_bf16(Bt[n][k], At[m][k], acc[ai][bj][m][n], 0, 0, 0); __builtin_amdgcn_s_setprio(0); } while (0)
; #define PG8_WAIT_V(n) asm volatile("s_waitcnt vmcnt(" #n ")" ::: "memory")
; #define PG8_WAIT_L(n) asm volatile("s_waitcnt lgkmcnt(" #n ")" ::: "memory")
; #define PG8_BAR __builtin_amdgcn_s_barrier()
; #define PG8_SCHED __builtin_amdgcn_sched_barrier(0)
; template <class Epi, class Sched, bool ALIGN_EPI = false, bool SP2 = false>
; __device__ __forceinline__ void gemm_phase(PG8_LAS unsigned char* lds, const Gemm g, const Sched& S, const Epi& E) {
;     ...
;             PG8_WAIT_V(8); PG8_WAIT_L(0); PG8_BAR; PG8_MMA(1, 0, At, B0); PG8_MMA(1, 1, At, B1); PG8_BAR; PG8_SCHED;
;             PG8_LDB(B0, 1, 0); PG8_LDB(B1, 1, 1); PG8_SCHED; PG8_LDA(At, 1, 0); PG8_STAGE(PG8_SA(0, 1), a2 + hstep, voffA);
;             PG8_WAIT_V(8); PG8_WAIT_L(0); PG8_BAR; PG8_MMA(0, 0, At, B0); PG8_MMA(0, 1, At, B1); PG8_BAR; PG8_SCHED;
	v_mfma_f32_16x16x32_bf16 v[62:65], v[144:147], v[180:183], v[62:65]
	v_mfma_f32_16x16x32_bf16 v[58:61], v[156:159], v[180:183], v[58:61]
	v_mfma_f32_16x16x32_bf16 v[46:49], v[144:147], v[188:191], v[46:49]
	v_mfma_f32_16x16x32_bf16 v[42:45], v[156:159], v[188:191], v[42:45]
	v_mfma_f32_16x16x32_bf16 v[30:33], v[144:147], v[196:199], v[30:33]
	v_mfma_f32_16x16x32_bf16 v[26:29], v[156:159], v[196:199], v[26:29]
	v_mfma_f32_16x16x32_bf16 v[14:17], v[144:147], v[224:227], v[14:17]
	v_mfma_f32_16x16x32_bf16 v[10:13], v[156:159], v[224:227], v[10:13]
	v_mfma_f32_16x16x32_bf16 v[62:65], v[152:155], v[184:187], v[62:65]
	v_mfma_f32_16x16x32_bf16 v[58:61], v[160:163], v[184:187], v[58:61]
	v_mfma_f32_16x16x32_bf16 v[46:49], v[152:155], v[192:195], v[46:49]
	v_mfma_f32_16x16x32_bf16 v[42:45], v[160:163], v[192:195], v[42:45]
	v_mfma_f32_16x16x32_bf16 v[30:33], v[152:155], v[200:203], v[30:33]
	v_mfma_f32_16x16x32_bf16 v[26:29], v[160:163], v[200:203], v[26:29]
	v_mfma_f32_16x16x32_bf16 v[14:17], v[152:155], v[228:231], v[14:17]
	v_mfma_f32_16x16x32_bf16 v[10:13], v[160:163], v[228:231], v[10:13]
	v_mfma_f32_16x16x32_bf16 v[54:57], v[164:167], v[180:183], v[54:57]
	v_mfma_f32_16x16x32_bf16 v[50:53], v[172:175], v[180:183], v[50:53]
	v_mfma_f32_16x16x32_bf16 v[38:41], v[164:167], v[188:191], v[38:41]
	v_mfma_f32_16x16x32_bf16 v[34:37], v[172:175], v[188:191], v[34:37]
	v_mfma_f32_16x16x32_bf16 v[22:25], v[164:167], v[196:199], v[22:25]
	v_mfma_f32_16x16x32_bf16 v[18:21], v[172:175], v[196:199], v[18:21]
	v_mfma_f32_16x16x32_bf16 v[6:9], v[164:167], v[224:227], v[6:9]
	v_mfma_f32_16x16x32_bf16 v[2:5], v[172:175], v[224:227], v[2:5]
	v_mfma_f32_16x16x32_bf16 v[54:57], v[168:171], v[184:187], v[54:57]
	v_mfma_f32_16x16x32_bf16 v[50:53], v[176:179], v[184:187], v[50:53]
	v_mfma_f32_16x16x32_bf16 v[38:41], v[168:171], v[192:195], v[38:41]
	v_mfma_f32_16x16x32_bf16 v[34:37], v[176:179], v[192:195], v[34:37]
	v_mfma_f32_16x16x32_bf16 v[22:25], v[168:171], v[200:203], v[22:25]
	v_mfma_f32_16x16x32_bf16 v[18:21], v[176:179], v[200:203], v[18:21]
	v_mfma_f32_16x16x32_bf16 v[6:9], v[168:171], v[228:231], v[6:9]
	v_mfma_f32_16x16x32_bf16 v[2:5], v[176:179], v[228:231], v[2:5]
	s_barrier
	s_setprio 0
	s_add_i32 s50, 0, 0x18000
	s_add_i32 s51, 0, 0x1c000
	v_add_u32_e32 v160, s50, v149
	v_add_u32_e32 v176, s51, v149
	ds_read_b128 v[144:147], v160
	ds_read_b128 v[152:155], v160 offset:1024
	ds_read_b128 v[156:159], v160 offset:2048
	ds_read_b128 v[160:163], v160 offset:3072
	ds_read_b128 v[164:167], v176
	ds_read_b128 v[168:171], v176 offset:1024
	ds_read_b128 v[172:175], v176 offset:2048
	ds_read_b128 v[176:179], v176 offset:3072
	s_add_u32 s14, s20, 0xb0000
	s_addc_u32 s15, s21, 0
	s_mov_b32 m0, s29
	v_lshl_add_u64 v[234:235], s[14:15], 0, v[130:131]
	ds_read_b128 v[180:183], v151 offset:32768
	ds_read_b128 v[184:187], v151 offset:33792
	ds_read_b128 v[188:191], v151 offset:34816
	ds_read_b128 v[192:195], v151 offset:35840
	ds_read_b128 v[196:199], v151 offset:36864
	ds_read_b128 v[200:203], v151 offset:37888
	ds_read_b128 v[224:227], v151 offset:38912
	ds_read_b128 v[228:231], v151 offset:39936
	global_load_lds_dwordx4 v[234:235], off
	v_lshl_add_u64 v[234:235], s[14:15], 0, v[132:133]
	s_mov_b32 m0, s30
	s_nop 0
	global_load_lds_dwordx4 v[234:235], off
	s_waitcnt vmcnt(8)
	s_waitcnt lgkmcnt(0)
	s_setprio 1
	s_barrier
	v_mfma_f32_16x16x32_bf16 v[126:129], v[144:147], v[180:183], v[126:129]
	v_mfma_f32_16x16x32_bf16 v[122:125], v[156:159], v[180:183], v[122:125]
	v_mfma_f32_16x16x32_bf16 v[110:113], v[144:147], v[188:191], v[110:113]
	v_mfma_f32_16x16x32_bf16 v[106:109], v[156:159], v[188:191], v[106:109]
	v_mfma_f32_16x16x32_bf16 v[94:97], v[144:147], v[196:199], v[94:97]
	v_mfma_f32_16x16x32_bf16 v[90:93], v[156:159], v[196:199], v[90:93]
	v_mfma_f32_16x16x32_bf16 v[78:81], v[144:147], v[224:227], v[78:81]
	v_mfma_f32_16x16x32_bf16 v[74:77], v[156:159], v[224:227], v[74:77]
	v_mfma_f32_16x16x32_bf16 v[126:129], v[152:155], v[184:187], v[126:129]
	v_mfma_f32_16x16x32_bf16 v[122:125], v[160:163], v[184:187], v[122:125]
	v_mfma_f32_16x16x32_bf16 v[110:113], v[152:155], v[192:195], v[110:113]
	v_mfma_f32_16x16x32_bf16 v[106:109], v[160:163], v[192:195], v[106:109]
	v_mfma_f32_16x16x32_bf16 v[94:97], v[152:155], v[200:203], v[94:97]
	v_mfma_f32_16x16x32_bf16 v[90:93], v[160:163], v[200:203], v[90:93]
	v_mfma_f32_16x16x32_bf16 v[78:81], v[152:155], v[228:231], v[78:81]
	v_mfma_f32_16x16x32_bf16 v[74:77], v[160:163], v[228:231], v[74:77]
	v_mfma_f32_16x16x32_bf16 v[118:121], v[164:167], v[180:183], v[118:121]
	v_mfma_f32_16x16x32_bf16 v[114:117], v[172:175], v[180:183], v[114:117]
	v_mfma_f32_16x16x32_bf16 v[102:105], v[164:167], v[188:191], v[102:105]
	v_mfma_f32_16x16x32_bf16 v[98:101], v[172:175], v[188:191], v[98:101]
	v_mfma_f32_16x16x32_bf16 v[86:89], v[164:167], v[196:199], v[86:89]
	v_mfma_f32_16x16x32_bf16 v[82:85], v[172:175], v[196:199], v[82:85]
	v_mfma_f32_16x16x32_bf16 v[70:73], v[164:167], v[224:227], v[70:73]
	v_mfma_f32_16x16x32_bf16 v[66:69], v[172:175], v[224:227], v[66:69]
	v_mfma_f32_16x16x32_bf16 v[118:121], v[168:171], v[184:187], v[118:121]
	v_mfma_f32_16x16x32_bf16 v[114:117], v[176:179], v[184:187], v[114:117]
	v_mfma_f32_16x16x32_bf16 v[102:105], v[168:171], v[192:195], v[102:105]
	v_mfma_f32_16x16x32_bf16 v[98:101], v[176:179], v[192:195], v[98:101]
	v_mfma_f32_16x16x32_bf16 v[86:89], v[168:171], v[200:203], v[86:89]
	v_mfma_f32_16x16x32_bf16 v[82:85], v[176:179], v[200:203], v[82:85]
	v_mfma_f32_16x16x32_bf16 v[70:73], v[168:171], v[228:231], v[70:73]
	v_mfma_f32_16x16x32_bf16 v[66:69], v[176:179], v[228:231], v[66:69]
	s_barrier
; #define PG8_STAGE(bufoff, gbase, voff) do { _Pragma("unroll") for (int _i = 0; _i < 2; ++_i) \
;         __builtin_amdgcn_global_load_lds((const unsigned*)((const char*)(gbase) + (voff)[_i]), (PG8_LAS unsigned*)(lds + (bufoff) + ldsw + _i * 8192), 16, 0, 0); } while (0)
; #define PG8_LDA(dst, b, h) do { _Pragma("unroll") for (int m = 0; m < 4; ++m) _Pragma("unroll") for (int k = 0; k < 2; ++k) dst[m][k] = *(const PG8_LAS bf16x8*)(lds + PG8_SA(b, h) + aoff + m * 2048 + k * 1024); } while (0)
; #define PG8_MMA(ai, bj, At, Bt) do { __builtin_amdgcn_s_setprio(1); _Pragma("unroll") for (int m = 0; m < 4; ++m) _Pragma("unroll") for (int n = 0; n < 2; ++n) _Pragma("unroll") for (int k = 0; k < 2; ++k) \
;         acc[ai][bj][m][n] = __builtin_amdgcn_mfma_f32_16x16x32_bf16(Bt[n][k], At[m][k], acc[ai][bj][m][n], 0, 0, 0); __builtin_amdgcn_s_setprio(0); } while (0)
; #define PG8_WAIT_V(n) asm volatile("s_waitcnt vmcnt(" #n ")" ::: "memory")
; #define PG8_WAIT_L(n) asm volatile("s_waitcnt lgkmcnt(" #n ")" ::: "memory")
; #define PG8_BAR __builtin_amdgcn_s_barrier()
; #define PG8_SCHED __builtin_amdgcn_sched_barrier(0)
; template <class Epi, class Sched, bool ALIGN_EPI = false, bool SP2 = false>
; __device__ __forceinline__ void gemm_phase(PG8_LAS unsigned char* lds, const Gemm g, const Sched& S, const Epi& E) {
;     ...
;             PG8_LDA(At, 1, 1); PG8_STAGE(PG8_SB(1, 0), b3, voffB); PG8_STAGE(PG8_SB(1, 1), b3 + hstep, voffB); PG8_STAGE(PG8_SA(1, 0), a3, voffA);
;             PG8_WAIT_V(8); PG8_WAIT_L(0); PG8_BAR; PG8_MMA(1, 0, At, B0); PG8_MMA(1, 1, At, B1); PG8_BAR; PG8_SCHED;
;     __device__ __forceinline__ void operator()(const f32x4 (&acc)[2][2][4][2], const Unit& u, int wr, int wc, int fr, int fq) const {
;     ...
;                 const int row = row0 + ai * 128 + m * 16; float p = 0.f;
; #pragma unroll
;                 for (int bj = 0; bj < 2; ++bj) {
;                     const size_t off = (size_t)row * D + col0 + bj * 128;
;                     const u32x4 xx = *(const u32x4*)(xb + off);
	s_setprio 0
	s_add_i32 s14, s50, s23
	v_lshl_add_u64 v[138:139], v[138:139], 0, s[86:87]
	s_mov_b32 m0, s14
	ds_read_b128 v[180:183], v151 offset:49152
	ds_read_b128 v[184:187], v151 offset:50176
	ds_read_b128 v[188:191], v151 offset:51200
	ds_read_b128 v[192:195], v151 offset:52224
	ds_read_b128 v[196:199], v151 offset:53248
	ds_read_b128 v[200:203], v151 offset:54272
	ds_read_b128 v[224:227], v151 offset:55296
	ds_read_b128 v[228:231], v151 offset:56320
	global_load_lds_dwordx4 v[138:139], off
	s_add_i32 m0, s14, 0x2000
	s_add_u32 s14, s18, 0xb0080
	v_lshl_add_u64 v[138:139], v[140:141], 0, s[86:87]
	s_addc_u32 s15, s19, 0
	s_add_i32 s18, s51, s23
	global_load_lds_dwordx4 v[138:139], off
	v_lshl_add_u64 v[138:139], s[14:15], 0, v[0:1]
	s_mov_b32 m0, s18
	s_nop 0
	global_load_lds_dwordx4 v[138:139], off
	v_lshl_add_u64 v[138:139], s[14:15], 0, v[134:135]
	s_add_i32 m0, s18, 0x2000
	s_nop 0
	global_load_lds_dwordx4 v[138:139], off
	v_lshl_add_u64 v[138:139], v[204:205], 0, s[86:87]
	s_mov_b32 m0, s38
	s_nop 0
	global_load_lds_dwordx4 v[138:139], off
	v_lshl_add_u64 v[138:139], v[232:233], 0, s[86:87]
	s_mov_b32 m0, s39
	s_nop 0
	global_load_lds_dwordx4 v[138:139], off
	s_waitcnt vmcnt(8)
	s_waitcnt lgkmcnt(0)
	s_setprio 1
	s_barrier
	v_mfma_f32_16x16x32_bf16 v[62:65], v[144:147], v[180:183], v[62:65]
	v_mfma_f32_16x16x32_bf16 v[58:61], v[156:159], v[180:183], v[58:61]
	v_mfma_f32_16x16x32_bf16 v[46:49], v[144:147], v[188:191], v[46:49]
	v_mfma_f32_16x16x32_bf16 v[42:45], v[156:159], v[188:191], v[42:45]
	v_mfma_f32_16x16x32_bf16 v[30:33], v[144:147], v[196:199], v[30:33]
	v_mfma_f32_16x16x32_bf16 v[26:29], v[156:159], v[196:199], v[26:29]
	v_mfma_f32_16x16x32_bf16 v[14:17], v[144:147], v[224:227], v[14:17]
	v_mfma_f32_16x16x32_bf16 v[10:13], v[156:159], v[224:227], v[10:13]
	v_mfma_f32_16x16x32_bf16 v[62:65], v[152:155], v[184:187], v[62:65]
	v_mfma_f32_16x16x32_bf16 v[58:61], v[160:163], v[184:187], v[58:61]
	v_mfma_f32_16x16x32_bf16 v[46:49], v[152:155], v[192:195], v[46:49]
	v_mfma_f32_16x16x32_bf16 v[42:45], v[160:163], v[192:195], v[42:45]
	v_mfma_f32_16x16x32_bf16 v[30:33], v[152:155], v[200:203], v[30:33]
	v_mfma_f32_16x16x32_bf16 v[26:29], v[160:163], v[200:203], v[26:29]
	v_mfma_f32_16x16x32_bf16 v[14:17], v[152:155], v[228:231], v[14:17]
	v_mfma_f32_16x16x32_bf16 v[10:13], v[160:163], v[228:231], v[10:13]
	v_mfma_f32_16x16x32_bf16 v[54:57], v[164:167], v[180:183], v[54:57]
	v_mfma_f32_16x16x32_bf16 v[50:53], v[172:175], v[180:183], v[50:53]
	v_mfma_f32_16x16x32_bf16 v[38:41], v[164:167], v[188:191], v[38:41]
	v_mfma_f32_16x16x32_bf16 v[34:37], v[172:175], v[188:191], v[34:37]
	v_mfma_f32_16x16x32_bf16 v[22:25], v[164:167], v[196:199], v[22:25]
	v_mfma_f32_16x16x32_bf16 v[18:21], v[172:175], v[196:199], v[18:21]
	v_mfma_f32_16x16x32_bf16 v[6:9], v[164:167], v[224:227], v[6:9]
	v_mfma_f32_16x16x32_bf16 v[2:5], v[172:175], v[224:227], v[2:5]
	v_mfma_f32_16x16x32_bf16 v[54:57], v[168:171], v[184:187], v[54:57]
	v_mfma_f32_16x16x32_bf16 v[50:53], v[176:179], v[184:187], v[50:53]
	v_mfma_f32_16x16x32_bf16 v[38:41], v[168:171], v[192:195], v[38:41]
	v_mfma_f32_16x16x32_bf16 v[34:37], v[176:179], v[192:195], v[34:37]
	v_mfma_f32_16x16x32_bf16 v[22:25], v[168:171], v[200:203], v[22:25]
	v_mfma_f32_16x16x32_bf16 v[18:21], v[176:179], v[200:203], v[18:21]
	v_mfma_f32_16x16x32_bf16 v[6:9], v[168:171], v[228:231], v[6:9]
	v_mfma_f32_16x16x32_bf16 v[2:5], v[176:179], v[228:231], v[2:5]
	s_barrier
	s_setprio 0
	s_add_i32 s49, s49, 2
	s_add_u32 s47, s47, 0x100
	s_addc_u32 s48, s48, 0
	s_cmp_gt_u32 s49, 41
	s_mov_b64 s[14:15], s[16:17]
	s_cbranch_scc0 .LBB0_362
	v_lshl_add_u32 v138, s46, 8, v148
	v_lshl_or_b32 v139, s45, 8, v150
	v_lshlrev_b32_e32 v138, 11, v138
	v_lshl_add_u32 v138, v139, 1, v138
	global_load_dwordx4 v[152:155], v138, s[34:35]
	global_load_dwordx4 v[156:159], v138, s[34:35] offset:256
	v_add_u32_e32 v139, 0x8000, v138
	global_load_dwordx4 v[160:163], v139, s[34:35]
	global_load_dwordx4 v[164:167], v139, s[34:35] offset:256
	v_add_u32_e32 v139, 0x10000, v138
	global_load_dwordx4 v[168:171], v139, s[34:35]
	global_load_dwordx4 v[172:175], v139, s[34:35] offset:256
	v_add_u32_e32 v139, 0x18000, v138
	global_load_dwordx4 v[176:179], v139, s[34:35]
	global_load_dwordx4 v[180:183], v139, s[34:35] offset:256
	v_add_u32_e32 v139, 0x40000, v138
	global_load_dwordx4 v[184:187], v139, s[34:35]
	global_load_dwordx4 v[188:191], v139, s[34:35] offset:256
	v_add_u32_e32 v139, 0x48000, v138
	global_load_dwordx4 v[192:195], v139, s[34:35]
	global_load_dwordx4 v[196:199], v139, s[34:35] offset:256
	v_add_u32_e32 v139, 0x50000, v138
	global_load_dwordx4 v[200:203], v139, s[34:35]
	global_load_dwordx4 v[224:227], v139, s[34:35] offset:256
	v_add_u32_e32 v139, 0x58000, v138
	global_load_dwordx4 v[228:231], v139, s[34:35]
	global_load_dwordx4 v[232:235], v139, s[34:35] offset:256
	s_and_b64 vcc, exec, s[10:11]
	s_cbranch_vccz .LBB0_365
	s_barrier

; #define PG8_STAGE(bufoff, gbase, voff) do { _Pragma("unroll") for (int _i = 0; _i < 2; ++_i) \
;         __builtin_amdgcn_global_load_lds((const unsigned*)((const char*)(gbase) + (voff)[_i]), (PG8_LAS unsigned*)(lds + (bufoff) + ldsw + _i * 8192), 16, 0, 0); } while (0)
; #define PG8_LDA(dst, b, h) do { _Pragma("unroll") for (int m = 0; m < 4; ++m) _Pragma("unroll") for (int k = 0; k < 2; ++k) dst[m][k] = *(const PG8_LAS bf16x8*)(lds + PG8_SA(b, h) + aoff + m * 2048 + k * 1024); } while (0)
; #define PG8_LDB(dst, b, h) do { _Pragma("unroll") for (int n = 0; n < 2; ++n) _Pragma("unroll") for (int k = 0; k < 2; ++k) dst[n][k] = *(const PG8_LAS bf16x8*)(lds + PG8_SB(b, h) + boff + n * 2048 + k * 1024); } while (0)
; #define PG8_MMA(ai, bj, At, Bt) do { __builtin_amdgcn_s_setprio(1); _Pragma("unroll") for (int m = 0; m < 4; ++m) _Pragma("unroll") for (int n = 0; n < 2; ++n) _Pragma("unroll") for (int k = 0; k < 2; ++k) \
;         acc[ai][bj][m][n] = __builtin_amdgcn_mfma_f32_16x16x32_bf16(Bt[n][k], At[m][k], acc[ai][bj][m][n], 0, 0, 0); __builtin_amdgcn_s_setprio(0); } while (0)
; #define PG8_BAR __builtin_amdgcn_s_barrier()
; template <class Epi, class Sched, bool ALIGN_EPI = false, bool SP2 = false>
; __device__ __forceinline__ void gemm_phase(PG8_LAS unsigned char* lds, const Gemm g, const Sched& S, const Epi& E) {
;     ...
;         const bool has_next = S.next(ui + 1, nxt);
;         const char* nA = has_next ? (const char*)g.A + (size_t)nxt.pm * tstep : cA; const char* nB = has_next ? (const char*)g.Bt + (size_t)nxt.pn * tstep : cB;
;         for (int t = 0; t < nt; t += 2) {
;             const bool last = (t == nt - 2);
;             const char* a1 = cA + (size_t)(t + 1) * kstep;
;             const char* a2 = last ? nA : cA + (size_t)(t + 2) * kstep; const char* b2 = last ? nB : cB + (size_t)(t + 2) * kstep;
;             const char* a3 = a2 + kstep; const char* b3 = b2 + kstep;
;             if (last && has_next) S.a_ready(nxt);
;             if constexpr (SP2) {
;             PG8_LDB(B0, 0, 0); PG8_LDB(B1, 0, 1); PG8_SCHED; PG8_LDA(At, 0, 0); PG8_STAGE(PG8_SA(1, 1), a1 + hstep, voffA);
;             PG8_WAIT_V(8); PG8_WAIT_L(0); PG8_BAR; PG8_MMA(0, 0, At, B0); PG8_MMA(0, 1, At, B1); PG8_BAR; PG8_SCHED;
;             PG8_LDA(At, 0, 1); PG8_STAGE(PG8_SB(0, 0), b2, voffB); PG8_STAGE(PG8_SB(0, 1), b2 + hstep, voffB); PG8_STAGE(PG8_SA(0, 0), a2, voffA);
.LBB0_491:
	s_ashr_i32 s15, s14, 31
	s_lshl_b64 s[16:17], s[14:15], 19
	s_add_u32 s16, s34, s16
	s_addc_u32 s17, s35, s17
	s_and_b64 s[18:19], s[2:3], exec
	s_cselect_b32 s5, s17, s9
	s_cselect_b32 s7, s16, s8
	s_ashr_i32 s13, s12, 31
	s_lshl_b64 s[18:19], s[12:13], 19
	s_add_u32 s18, s27, s18
	s_addc_u32 s19, s29, s19
	s_and_b64 s[22:23], s[2:3], exec
	s_cselect_b32 s13, s19, s21
	s_cselect_b32 s15, s18, s20
	s_add_u32 s8, s8, 0x40080
	s_addc_u32 s9, s9, 0
	s_add_u32 s45, s20, 0x100
	s_addc_u32 s46, s21, 0
	s_mov_b32 s47, -2
	s_add_u32 s20, s8, 0xfffc0080
	s_addc_u32 s21, s9, -1
	s_add_i32 s48, 0, 0x10000
	s_cmp_eq_u32 s47, 12
	s_cselect_b32 s23, s5, s21
	s_cselect_b32 s22, s7, s20
	v_add_u32_e32 v138, s48, v161
	s_cselect_b32 s21, s13, s46
	s_cselect_b32 s20, s15, s45
	s_add_i32 s50, 0, 0x14000
	ds_read_b128 v[144:147], v138
	ds_read_b128 v[148:151], v138 offset:1024
	ds_read_b128 v[152:155], v138 offset:2048
	ds_read_b128 v[156:159], v138 offset:3072
	v_add_u32_e32 v138, s50, v161
	ds_read_b128 v[166:169], v138
	ds_read_b128 v[170:173], v138 offset:1024
	ds_read_b128 v[174:177], v138 offset:2048
	ds_read_b128 v[178:181], v138 offset:3072
	v_lshl_add_u64 v[138:139], s[8:9], 0, v[136:137]
	s_add_i32 m0, s30, 0xc000
	ds_read_b128 v[182:185], v164
	ds_read_b128 v[186:189], v164 offset:1024
	ds_read_b128 v[190:193], v164 offset:2048
	ds_read_b128 v[194:197], v164 offset:3072
	ds_read_b128 v[198:201], v164 offset:4096
	ds_read_b128 v[202:205], v164 offset:5120
	ds_read_b128 v[224:227], v164 offset:6144
	ds_read_b128 v[228:231], v164 offset:7168
	global_load_lds_dwordx4 v[138:139], off
	v_lshl_add_u64 v[138:139], s[8:9], 0, v[142:143]
	s_add_i32 m0, s30, 0xe000
	s_nop 0
	global_load_lds_dwordx4 v[138:139], off
	s_waitcnt vmcnt(8)
	s_waitcnt lgkmcnt(0)
	s_setprio 1
	s_barrier
	v_mfma_f32_16x16x32_bf16 v[126:129], v[144:147], v[182:185], 0
	v_mfma_f32_16x16x32_bf16 v[122:125], v[152:155], v[182:185], 0
	v_mfma_f32_16x16x32_bf16 v[110:113], v[144:147], v[190:193], 0
	v_mfma_f32_16x16x32_bf16 v[106:109], v[152:155], v[190:193], 0
	v_mfma_f32_16x16x32_bf16 v[94:97], v[144:147], v[198:201], 0
	v_mfma_f32_16x16x32_bf16 v[90:93], v[152:155], v[198:201], 0
	v_mfma_f32_16x16x32_bf16 v[78:81], v[144:147], v[224:227], 0
	v_mfma_f32_16x16x32_bf16 v[74:77], v[152:155], v[224:227], 0
	v_mfma_f32_16x16x32_bf16 v[126:129], v[148:151], v[186:189], v[126:129]
	v_mfma_f32_16x16x32_bf16 v[122:125], v[156:159], v[186:189], v[122:125]
	v_mfma_f32_16x16x32_bf16 v[110:113], v[148:151], v[194:197], v[110:113]
	v_mfma_f32_16x16x32_bf16 v[106:109], v[156:159], v[194:197], v[106:109]
	v_mfma_f32_16x16x32_bf16 v[94:97], v[148:151], v[202:205], v[94:97]
	v_mfma_f32_16x16x32_bf16 v[90:93], v[156:159], v[202:205], v[90:93]
	v_mfma_f32_16x16x32_bf16 v[78:81], v[148:151], v[228:231], v[78:81]
	v_mfma_f32_16x16x32_bf16 v[74:77], v[156:159], v[228:231], v[74:77]
	v_mfma_f32_16x16x32_bf16 v[118:121], v[166:169], v[182:185], 0
	v_mfma_f32_16x16x32_bf16 v[114:117], v[174:177], v[182:185], 0
	v_mfma_f32_16x16x32_bf16 v[102:105], v[166:169], v[190:193], 0
	v_mfma_f32_16x16x32_bf16 v[98:101], v[174:177], v[190:193], 0
	v_mfma_f32_16x16x32_bf16 v[86:89], v[166:169], v[198:201], 0
	v_mfma_f32_16x16x32_bf16 v[82:85], v[174:177], v[198:201], 0
	v_mfma_f32_16x16x32_bf16 v[70:73], v[166:169], v[224:227], 0
	v_mfma_f32_16x16x32_bf16 v[66:69], v[174:177], v[224:227], 0
	v_mfma_f32_16x16x32_bf16 v[118:121], v[170:173], v[186:189], v[118:121]
	v_mfma_f32_16x16x32_bf16 v[114:117], v[178:181], v[186:189], v[114:117]
	v_mfma_f32_16x16x32_bf16 v[102:105], v[170:173], v[194:197], v[102:105]
	v_mfma_f32_16x16x32_bf16 v[98:101], v[178:181], v[194:197], v[98:101]
	v_mfma_f32_16x16x32_bf16 v[86:89], v[170:173], v[202:205], v[86:89]
	v_mfma_f32_16x16x32_bf16 v[82:85], v[178:181], v[202:205], v[82:85]
	v_mfma_f32_16x16x32_bf16 v[70:73], v[170:173], v[228:231], v[70:73]
	v_mfma_f32_16x16x32_bf16 v[66:69], v[178:181], v[228:231], v[66:69]
	s_barrier
	s_setprio 0
	s_add_i32 s48, s48, s26
	v_lshl_add_u64 v[138:139], s[20:21], 0, v[0:1]
	s_mov_b32 m0, s48
	ds_read_b128 v[182:185], v164 offset:16384
	ds_read_b128 v[186:189], v164 offset:17408
	ds_read_b128 v[190:193], v164 offset:18432
	ds_read_b128 v[194:197], v164 offset:19456
	ds_read_b128 v[198:201], v164 offset:20480
	ds_read_b128 v[202:205], v164 offset:21504
	ds_read_b128 v[224:227], v164 offset:22528
	ds_read_b128 v[228:231], v164 offset:23552
	global_load_lds_dwordx4 v[138:139], off
	s_add_i32 m0, s48, 0x2000
	s_add_u32 s48, s20, 0x40000
	v_lshl_add_u64 v[140:141], s[20:21], 0, v[134:135]
	s_addc_u32 s49, s21, 0
	s_add_i32 s50, s50, s26
	global_load_lds_dwordx4 v[140:141], off
	v_lshl_add_u64 v[232:233], s[48:49], 0, v[0:1]
	s_mov_b32 m0, s50
	v_lshl_add_u64 v[234:235], s[22:23], 0, v[132:133]
	global_load_lds_dwordx4 v[232:233], off
	v_lshl_add_u64 v[232:233], s[48:49], 0, v[134:135]
	s_add_i32 m0, s50, 0x2000
	s_nop 0
	global_load_lds_dwordx4 v[232:233], off
	v_lshl_add_u64 v[232:233], s[22:23], 0, v[130:131]
	s_mov_b32 m0, s30
	s_nop 0
	global_load_lds_dwordx4 v[232:233], off
	s_mov_b32 m0, s31
	s_nop 0
	global_load_lds_dwordx4 v[234:235], off
	s_waitcnt vmcnt(8)
	s_waitcnt lgkmcnt(0)
	s_setprio 1
	s_barrier
; #define PG8_STAGE(bufoff, gbase, voff) do { _Pragma("unroll") for (int _i = 0; _i < 2; ++_i) \
;         __builtin_amdgcn_global_load_lds((const unsigned*)((const char*)(gbase) + (voff)[_i]), (PG8_LAS unsigned*)(lds + (bufoff) + ldsw + _i * 8192), 16, 0, 0); } while (0)
; #define PG8_LDA(dst, b, h) do { _Pragma("unroll") for (int m = 0; m < 4; ++m) _Pragma("unroll") for (int k = 0; k < 2; ++k) dst[m][k] = *(const PG8_LAS bf16x8*)(lds + PG8_SA(b, h) + aoff + m * 2048 + k * 1024); } while (0)
; #define PG8_LDB(dst, b, h) do { _Pragma("unroll") for (int n = 0; n < 2; ++n) _Pragma("unroll") for (int k = 0; k < 2; ++k) dst[n][k] = *(const PG8_LAS bf16x8*)(lds + PG8_SB(b, h) + boff + n * 2048 + k * 1024); } while (0)
; #define PG8_MMA(ai, bj, At, Bt) do { __builtin_amdgcn_s_setprio(1); _Pragma("unroll") for (int m = 0; m < 4; ++m) _Pragma("unroll") for (int n = 0; n < 2; ++n) _Pragma("unroll") for (int k = 0; k < 2; ++k) \
;         acc[ai][bj][m][n] = __builtin_amdgcn_mfma_f32_16x16x32_bf16(Bt[n][k], At[m][k], acc[ai][bj][m][n], 0, 0, 0); __builtin_amdgcn_s_setprio(0); } while (0)
; #define PG8_WAIT_V(n) asm volatile("s_waitcnt vmcnt(" #n ")" ::: "memory")
; #define PG8_WAIT_L(n) asm volatile("s_waitcnt lgkmcnt(" #n ")" ::: "memory")
; #define PG8_BAR __builtin_amdgcn_s_barrier()
; #define PG8_SCHED __builtin_amdgcn_sched_barrier(0)
; template <class Epi, class Sched, bool ALIGN_EPI = false, bool SP2 = false>
; __device__ __forceinline__ void gemm_phase(PG8_LAS unsigned char* lds, const Gemm g, const Sched& S, const Epi& E) {
;     ...
;             PG8_LDA(At, 0, 1); PG8_STAGE(PG8_SB(0, 0), b2, voffB); PG8_STAGE(PG8_SB(0, 1), b2 + hstep, voffB); PG8_STAGE(PG8_SA(0, 0), a2, voffA);
;             PG8_WAIT_V(8); PG8_WAIT_L(0); PG8_BAR; PG8_MMA(1, 0, At, B0); PG8_MMA(1, 1, At, B1); PG8_BAR; PG8_SCHED;
;             PG8_LDB(B0, 1, 0); PG8_LDB(B1, 1, 1); PG8_SCHED; PG8_LDA(At, 1, 0); PG8_STAGE(PG8_SA(0, 1), a2 + hstep, voffA);
;             PG8_WAIT_V(8); PG8_WAIT_L(0); PG8_BAR; PG8_MMA(0, 0, At, B0); PG8_MMA(0, 1, At, B1); PG8_BAR; PG8_SCHED;
	v_mfma_f32_16x16x32_bf16 v[62:65], v[144:147], v[182:185], 0
	v_mfma_f32_16x16x32_bf16 v[58:61], v[152:155], v[182:185], 0
	v_mfma_f32_16x16x32_bf16 v[46:49], v[144:147], v[190:193], 0
	v_mfma_f32_16x16x32_bf16 v[42:45], v[152:155], v[190:193], 0
	v_mfma_f32_16x16x32_bf16 v[30:33], v[144:147], v[198:201], 0
	v_mfma_f32_16x16x32_bf16 v[26:29], v[152:155], v[198:201], 0
	v_mfma_f32_16x16x32_bf16 v[14:17], v[144:147], v[224:227], 0
	v_mfma_f32_16x16x32_bf16 v[10:13], v[152:155], v[224:227], 0
	v_mfma_f32_16x16x32_bf16 v[62:65], v[148:151], v[186:189], v[62:65]
	v_mfma_f32_16x16x32_bf16 v[58:61], v[156:159], v[186:189], v[58:61]
	v_mfma_f32_16x16x32_bf16 v[46:49], v[148:151], v[194:197], v[46:49]
	v_mfma_f32_16x16x32_bf16 v[42:45], v[156:159], v[194:197], v[42:45]
	v_mfma_f32_16x16x32_bf16 v[30:33], v[148:151], v[202:205], v[30:33]
	v_mfma_f32_16x16x32_bf16 v[26:29], v[156:159], v[202:205], v[26:29]
	v_mfma_f32_16x16x32_bf16 v[14:17], v[148:151], v[228:231], v[14:17]
	v_mfma_f32_16x16x32_bf16 v[10:13], v[156:159], v[228:231], v[10:13]
	v_mfma_f32_16x16x32_bf16 v[54:57], v[166:169], v[182:185], 0
	v_mfma_f32_16x16x32_bf16 v[50:53], v[174:177], v[182:185], 0
	v_mfma_f32_16x16x32_bf16 v[38:41], v[166:169], v[190:193], 0
	v_mfma_f32_16x16x32_bf16 v[34:37], v[174:177], v[190:193], 0
	v_mfma_f32_16x16x32_bf16 v[22:25], v[166:169], v[198:201], 0
	v_mfma_f32_16x16x32_bf16 v[18:21], v[174:177], v[198:201], 0
	v_mfma_f32_16x16x32_bf16 v[6:9], v[166:169], v[224:227], 0
	v_mfma_f32_16x16x32_bf16 v[2:5], v[174:177], v[224:227], 0
	v_mfma_f32_16x16x32_bf16 v[54:57], v[170:173], v[186:189], v[54:57]
	v_mfma_f32_16x16x32_bf16 v[50:53], v[178:181], v[186:189], v[50:53]
	v_mfma_f32_16x16x32_bf16 v[38:41], v[170:173], v[194:197], v[38:41]
	v_mfma_f32_16x16x32_bf16 v[34:37], v[178:181], v[194:197], v[34:37]
	v_mfma_f32_16x16x32_bf16 v[22:25], v[170:173], v[202:205], v[22:25]
	v_mfma_f32_16x16x32_bf16 v[18:21], v[178:181], v[202:205], v[18:21]
	v_mfma_f32_16x16x32_bf16 v[6:9], v[170:173], v[228:231], v[6:9]
	v_mfma_f32_16x16x32_bf16 v[2:5], v[178:181], v[228:231], v[2:5]
	s_barrier
	s_setprio 0
	s_add_i32 s48, 0, 0x18000
	s_add_i32 s49, 0, 0x1c000
	v_add_u32_e32 v156, s48, v161
	v_add_u32_e32 v165, s49, v161
	ds_read_b128 v[144:147], v156
	ds_read_b128 v[148:151], v156 offset:1024
	ds_read_b128 v[152:155], v156 offset:2048
	ds_read_b128 v[156:159], v156 offset:3072
	ds_read_b128 v[166:169], v165
	ds_read_b128 v[170:173], v165 offset:1024
	ds_read_b128 v[174:177], v165 offset:2048
	ds_read_b128 v[178:181], v165 offset:3072
	s_add_u32 s22, s22, 0x40000
	s_addc_u32 s23, s23, 0
	s_mov_b32 m0, s38
	v_lshl_add_u64 v[236:237], s[22:23], 0, v[130:131]
	ds_read_b128 v[182:185], v164 offset:32768
	ds_read_b128 v[186:189], v164 offset:33792
	ds_read_b128 v[190:193], v164 offset:34816
	ds_read_b128 v[194:197], v164 offset:35840
	ds_read_b128 v[198:201], v164 offset:36864
	ds_read_b128 v[202:205], v164 offset:37888
	ds_read_b128 v[224:227], v164 offset:38912
	ds_read_b128 v[228:231], v164 offset:39936
	global_load_lds_dwordx4 v[236:237], off
	v_lshl_add_u64 v[236:237], s[22:23], 0, v[132:133]
	s_mov_b32 m0, s39
	s_nop 0
	global_load_lds_dwordx4 v[236:237], off
	s_waitcnt vmcnt(8)
	s_waitcnt lgkmcnt(0)
	s_setprio 1
	s_barrier
	v_mfma_f32_16x16x32_bf16 v[126:129], v[144:147], v[182:185], v[126:129]
	v_mfma_f32_16x16x32_bf16 v[122:125], v[152:155], v[182:185], v[122:125]
	v_mfma_f32_16x16x32_bf16 v[110:113], v[144:147], v[190:193], v[110:113]
	v_mfma_f32_16x16x32_bf16 v[106:109], v[152:155], v[190:193], v[106:109]
	v_mfma_f32_16x16x32_bf16 v[94:97], v[144:147], v[198:201], v[94:97]
	v_mfma_f32_16x16x32_bf16 v[90:93], v[152:155], v[198:201], v[90:93]
	v_mfma_f32_16x16x32_bf16 v[78:81], v[144:147], v[224:227], v[78:81]
	v_mfma_f32_16x16x32_bf16 v[74:77], v[152:155], v[224:227], v[74:77]
	v_mfma_f32_16x16x32_bf16 v[126:129], v[148:151], v[186:189], v[126:129]
	v_mfma_f32_16x16x32_bf16 v[122:125], v[156:159], v[186:189], v[122:125]
	v_mfma_f32_16x16x32_bf16 v[110:113], v[148:151], v[194:197], v[110:113]
	v_mfma_f32_16x16x32_bf16 v[106:109], v[156:159], v[194:197], v[106:109]
	v_mfma_f32_16x16x32_bf16 v[94:97], v[148:151], v[202:205], v[94:97]
	v_mfma_f32_16x16x32_bf16 v[90:93], v[156:159], v[202:205], v[90:93]
	v_mfma_f32_16x16x32_bf16 v[78:81], v[148:151], v[228:231], v[78:81]
	v_mfma_f32_16x16x32_bf16 v[74:77], v[156:159], v[228:231], v[74:77]
	v_mfma_f32_16x16x32_bf16 v[118:121], v[166:169], v[182:185], v[118:121]
	v_mfma_f32_16x16x32_bf16 v[114:117], v[174:177], v[182:185], v[114:117]
	v_mfma_f32_16x16x32_bf16 v[102:105], v[166:169], v[190:193], v[102:105]
	v_mfma_f32_16x16x32_bf16 v[98:101], v[174:177], v[190:193], v[98:101]
	v_mfma_f32_16x16x32_bf16 v[86:89], v[166:169], v[198:201], v[86:89]
	v_mfma_f32_16x16x32_bf16 v[82:85], v[174:177], v[198:201], v[82:85]
	v_mfma_f32_16x16x32_bf16 v[70:73], v[166:169], v[224:227], v[70:73]
	v_mfma_f32_16x16x32_bf16 v[66:69], v[174:177], v[224:227], v[66:69]
	v_mfma_f32_16x16x32_bf16 v[118:121], v[170:173], v[186:189], v[118:121]
	v_mfma_f32_16x16x32_bf16 v[114:117], v[178:181], v[186:189], v[114:117]
	v_mfma_f32_16x16x32_bf16 v[102:105], v[170:173], v[194:197], v[102:105]
	v_mfma_f32_16x16x32_bf16 v[98:101], v[178:181], v[194:197], v[98:101]
	v_mfma_f32_16x16x32_bf16 v[86:89], v[170:173], v[202:205], v[86:89]
	v_mfma_f32_16x16x32_bf16 v[82:85], v[178:181], v[202:205], v[82:85]
	v_mfma_f32_16x16x32_bf16 v[70:73], v[170:173], v[228:231], v[70:73]
	v_mfma_f32_16x16x32_bf16 v[66:69], v[178:181], v[228:231], v[66:69]
	s_barrier
; #define PG8_STAGE(bufoff, gbase, voff) do { _Pragma("unroll") for (int _i = 0; _i < 2; ++_i) \
;         __builtin_amdgcn_global_load_lds((const unsigned*)((const char*)(gbase) + (voff)[_i]), (PG8_LAS unsigned*)(lds + (bufoff) + ldsw + _i * 8192), 16, 0, 0); } while (0)
; #define PG8_LDA(dst, b, h) do { _Pragma("unroll") for (int m = 0; m < 4; ++m) _Pragma("unroll") for (int k = 0; k < 2; ++k) dst[m][k] = *(const PG8_LAS bf16x8*)(lds + PG8_SA(b, h) + aoff + m * 2048 + k * 1024); } while (0)
; #define PG8_LDB(dst, b, h) do { _Pragma("unroll") for (int n = 0; n < 2; ++n) _Pragma("unroll") for (int k = 0; k < 2; ++k) dst[n][k] = *(const PG8_LAS bf16x8*)(lds + PG8_SB(b, h) + boff + n * 2048 + k * 1024); } while (0)
; template <class Epi, class Sched, bool ALIGN_EPI = false, bool SP2 = false>
; __device__ __forceinline__ void gemm_phase(PG8_LAS unsigned char* lds, const Gemm g, const Sched& S, const Epi& E) {
;     ...
;         for (int t = 0; t < nt; t += 2) {
;             const bool last = (t == nt - 2);
;             const char* a1 = cA + (size_t)(t + 1) * kstep;
;             const char* a2 = last ? nA : cA + (size_t)(t + 2) * kstep; const char* b2 = last ? nB : cB + (size_t)(t + 2) * kstep;
;             const char* a3 = a2 + kstep; const char* b3 = b2 + kstep;
;             if (last && has_next) S.a_ready(nxt);
;             if constexpr (SP2) {
;             PG8_LDB(B0, 0, 0); PG8_LDB(B1, 0, 1); PG8_SCHED; PG8_LDA(At, 0, 0); PG8_STAGE(PG8_SA(1, 1), a1 + hstep, voffA);
;             PG8_WAIT_V(8); PG8_WAIT_L(0); PG8_BAR; PG8_MMA(0, 0, At, B0); PG8_MMA(0, 1, At, B1); PG8_BAR; PG8_SCHED;
;             PG8_LDA(At, 0, 1); PG8_STAGE(PG8_SB(0, 0), b2, voffB); PG8_STAGE(PG8_SB(0, 1), b2 + hstep, voffB); PG8_STAGE(PG8_SA(0, 0), a2, voffA);
;             PG8_WAIT_V(8); PG8_WAIT_L(0); PG8_BAR; PG8_MMA(1, 0, At, B0); PG8_MMA(1, 1, At, B1); PG8_BAR; PG8_SCHED;
;             PG8_LDB(B0, 1, 0); PG8_LDB(B1, 1, 1); PG8_SCHED; PG8_LDA(At, 1, 0); PG8_STAGE(PG8_SA(0, 1), a2 + hstep, voffA);
;             PG8_WAIT_V(8); PG8_WAIT_L(0); PG8_BAR; PG8_MMA(0, 0, At, B0); PG8_MMA(0, 1, At, B1); PG8_BAR; PG8_SCHED;
;             PG8_LDA(At, 1, 1); PG8_STAGE(PG8_SB(1, 0), b3, voffB); PG8_STAGE(PG8_SB(1, 1), b3 + hstep, voffB); PG8_STAGE(PG8_SA(1, 0), a3, voffA);
;             PG8_WAIT_V(8); PG8_WAIT_L(0); PG8_BAR; PG8_MMA(1, 0, At, B0); PG8_MMA(1, 1, At, B1); PG8_BAR; PG8_SCHED;
	s_setprio 0
	s_add_i32 s22, s48, s26
	v_lshl_add_u64 v[138:139], v[138:139], 0, s[86:87]
	s_mov_b32 m0, s22
	ds_read_b128 v[182:185], v164 offset:49152
	ds_read_b128 v[186:189], v164 offset:50176
	ds_read_b128 v[190:193], v164 offset:51200
	ds_read_b128 v[194:197], v164 offset:52224
	ds_read_b128 v[198:201], v164 offset:53248
	ds_read_b128 v[202:205], v164 offset:54272
	ds_read_b128 v[224:227], v164 offset:55296
	ds_read_b128 v[228:231], v164 offset:56320
	global_load_lds_dwordx4 v[138:139], off
	s_add_i32 m0, s22, 0x2000
	s_add_u32 s20, s20, 0x40080
	v_lshl_add_u64 v[138:139], v[140:141], 0, s[86:87]
	s_addc_u32 s21, s21, 0
	s_add_i32 s22, s49, s26
	global_load_lds_dwordx4 v[138:139], off
	v_lshl_add_u64 v[138:139], s[20:21], 0, v[0:1]
	s_mov_b32 m0, s22
	s_nop 0
	global_load_lds_dwordx4 v[138:139], off
	v_lshl_add_u64 v[138:139], s[20:21], 0, v[134:135]
	s_add_i32 m0, s22, 0x2000
	s_nop 0
	global_load_lds_dwordx4 v[138:139], off
	v_lshl_add_u64 v[138:139], v[232:233], 0, s[86:87]
	s_mov_b32 m0, s41
	s_nop 0
	global_load_lds_dwordx4 v[138:139], off
	v_lshl_add_u64 v[138:139], v[234:235], 0, s[86:87]
	s_mov_b32 m0, s42
	s_nop 0
	global_load_lds_dwordx4 v[138:139], off
	s_waitcnt vmcnt(8)
	s_waitcnt lgkmcnt(0)
	s_setprio 1
	s_barrier
	v_mfma_f32_16x16x32_bf16 v[62:65], v[144:147], v[182:185], v[62:65]
	v_mfma_f32_16x16x32_bf16 v[58:61], v[152:155], v[182:185], v[58:61]
	v_mfma_f32_16x16x32_bf16 v[46:49], v[144:147], v[190:193], v[46:49]
	v_mfma_f32_16x16x32_bf16 v[42:45], v[152:155], v[190:193], v[42:45]
	v_mfma_f32_16x16x32_bf16 v[30:33], v[144:147], v[198:201], v[30:33]
	v_mfma_f32_16x16x32_bf16 v[26:29], v[152:155], v[198:201], v[26:29]
	v_mfma_f32_16x16x32_bf16 v[14:17], v[144:147], v[224:227], v[14:17]
	v_mfma_f32_16x16x32_bf16 v[10:13], v[152:155], v[224:227], v[10:13]
	v_mfma_f32_16x16x32_bf16 v[62:65], v[148:151], v[186:189], v[62:65]
	v_mfma_f32_16x16x32_bf16 v[58:61], v[156:159], v[186:189], v[58:61]
	v_mfma_f32_16x16x32_bf16 v[46:49], v[148:151], v[194:197], v[46:49]
	v_mfma_f32_16x16x32_bf16 v[42:45], v[156:159], v[194:197], v[42:45]
	v_mfma_f32_16x16x32_bf16 v[30:33], v[148:151], v[202:205], v[30:33]
	v_mfma_f32_16x16x32_bf16 v[26:29], v[156:159], v[202:205], v[26:29]
	v_mfma_f32_16x16x32_bf16 v[14:17], v[148:151], v[228:231], v[14:17]
	v_mfma_f32_16x16x32_bf16 v[10:13], v[156:159], v[228:231], v[10:13]
	v_mfma_f32_16x16x32_bf16 v[54:57], v[166:169], v[182:185], v[54:57]
	v_mfma_f32_16x16x32_bf16 v[50:53], v[174:177], v[182:185], v[50:53]
	v_mfma_f32_16x16x32_bf16 v[38:41], v[166:169], v[190:193], v[38:41]
	v_mfma_f32_16x16x32_bf16 v[34:37], v[174:177], v[190:193], v[34:37]
	v_mfma_f32_16x16x32_bf16 v[22:25], v[166:169], v[198:201], v[22:25]
	v_mfma_f32_16x16x32_bf16 v[18:21], v[174:177], v[198:201], v[18:21]
	v_mfma_f32_16x16x32_bf16 v[6:9], v[166:169], v[224:227], v[6:9]
	v_mfma_f32_16x16x32_bf16 v[2:5], v[174:177], v[224:227], v[2:5]
	v_mfma_f32_16x16x32_bf16 v[54:57], v[170:173], v[186:189], v[54:57]
	v_mfma_f32_16x16x32_bf16 v[50:53], v[178:181], v[186:189], v[50:53]
	v_mfma_f32_16x16x32_bf16 v[38:41], v[170:173], v[194:197], v[38:41]
	v_mfma_f32_16x16x32_bf16 v[34:37], v[178:181], v[194:197], v[34:37]
	v_mfma_f32_16x16x32_bf16 v[22:25], v[170:173], v[202:205], v[22:25]
	v_mfma_f32_16x16x32_bf16 v[18:21], v[178:181], v[202:205], v[18:21]
	v_mfma_f32_16x16x32_bf16 v[6:9], v[170:173], v[228:231], v[6:9]
	v_mfma_f32_16x16x32_bf16 v[2:5], v[178:181], v[228:231], v[2:5]
	s_barrier
	s_setprio 0
	s_add_i32 s47, s47, 2
	s_add_u32 s8, s8, 0x100
	s_addc_u32 s9, s9, 0
	s_add_u32 s45, s45, 0x100
	s_addc_u32 s46, s46, 0
	s_cmp_gt_u32 s47, 13
	s_cbranch_scc1 .Lpeel_exit_pj
.LBB0_492:
	s_add_u32 s20, s8, 0xfffc0080
	s_addc_u32 s21, s9, -1
	s_add_i32 s48, 0, 0x10000
	s_cmp_eq_u32 s47, 12
	s_cselect_b32 s23, s5, s21
	s_cselect_b32 s22, s7, s20
	v_add_u32_e32 v138, s48, v161
	s_cselect_b32 s21, s13, s46
	s_cselect_b32 s20, s15, s45
	s_add_i32 s50, 0, 0x14000
	ds_read_b128 v[144:147], v138
	ds_read_b128 v[148:151], v138 offset:1024
	ds_read_b128 v[152:155], v138 offset:2048
	ds_read_b128 v[156:159], v138 offset:3072
	v_add_u32_e32 v138, s50, v161
	ds_read_b128 v[166:169], v138
	ds_read_b128 v[170:173], v138 offset:1024
	ds_read_b128 v[174:177], v138 offset:2048
	ds_read_b128 v[178:181], v138 offset:3072
	v_lshl_add_u64 v[138:139], s[8:9], 0, v[136:137]
	s_add_i32 m0, s30, 0xc000
	ds_read_b128 v[182:185], v164
	ds_read_b128 v[186:189], v164 offset:1024
	ds_read_b128 v[190:193], v164 offset:2048
	ds_read_b128 v[194:197], v164 offset:3072
	ds_read_b128 v[198:201], v164 offset:4096
	ds_read_b128 v[202:205], v164 offset:5120
	ds_read_b128 v[224:227], v164 offset:6144
	ds_read_b128 v[228:231], v164 offset:7168
	global_load_lds_dwordx4 v[138:139], off
	v_lshl_add_u64 v[138:139], s[8:9], 0, v[142:143]
	s_add_i32 m0, s30, 0xe000
	s_nop 0
	global_load_lds_dwordx4 v[138:139], off
	s_waitcnt vmcnt(8)
	s_waitcnt lgkmcnt(0)
	s_setprio 1
	s_barrier
; #define PG8_STAGE(bufoff, gbase, voff) do { _Pragma("unroll") for (int _i = 0; _i < 2; ++_i) \
;         __builtin_amdgcn_global_load_lds((const unsigned*)((const char*)(gbase) + (voff)[_i]), (PG8_LAS unsigned*)(lds + (bufoff) + ldsw + _i * 8192), 16, 0, 0); } while (0)
; #define PG8_LDA(dst, b, h) do { _Pragma("unroll") for (int m = 0; m < 4; ++m) _Pragma("unroll") for (int k = 0; k < 2; ++k) dst[m][k] = *(const PG8_LAS bf16x8*)(lds + PG8_SA(b, h) + aoff + m * 2048 + k * 1024); } while (0)
; #define PG8_MMA(ai, bj, At, Bt) do { __builtin_amdgcn_s_setprio(1); _Pragma("unroll") for (int m = 0; m < 4; ++m) _Pragma("unroll") for (int n = 0; n < 2; ++n) _Pragma("unroll") for (int k = 0; k < 2; ++k) \
;         acc[ai][bj][m][n] = __builtin_amdgcn_mfma_f32_16x16x32_bf16(Bt[n][k], At[m][k], acc[ai][bj][m][n], 0, 0, 0); __builtin_amdgcn_s_setprio(0); } while (0)
; #define PG8_WAIT_V(n) asm volatile("s_waitcnt vmcnt(" #n ")" ::: "memory")
; #define PG8_WAIT_L(n) asm volatile("s_waitcnt lgkmcnt(" #n ")" ::: "memory")
; #define PG8_BAR __builtin_amdgcn_s_barrier()
; #define PG8_SCHED __builtin_amdgcn_sched_barrier(0)
; template <class Epi, class Sched, bool ALIGN_EPI = false, bool SP2 = false>
; __device__ __forceinline__ void gemm_phase(PG8_LAS unsigned char* lds, const Gemm g, const Sched& S, const Epi& E) {
;     ...
;             PG8_WAIT_V(8); PG8_WAIT_L(0); PG8_BAR; PG8_MMA(0, 0, At, B0); PG8_MMA(0, 1, At, B1); PG8_BAR; PG8_SCHED;
;             PG8_LDA(At, 0, 1); PG8_STAGE(PG8_SB(0, 0), b2, voffB); PG8_STAGE(PG8_SB(0, 1), b2 + hstep, voffB); PG8_STAGE(PG8_SA(0, 0), a2, voffA);
;             PG8_WAIT_V(8); PG8_WAIT_L(0); PG8_BAR; PG8_MMA(1, 0, At, B0); PG8_MMA(1, 1, At, B1); PG8_BAR; PG8_SCHED;
	v_mfma_f32_16x16x32_bf16 v[126:129], v[144:147], v[182:185], v[126:129]
	v_mfma_f32_16x16x32_bf16 v[122:125], v[152:155], v[182:185], v[122:125]
	v_mfma_f32_16x16x32_bf16 v[110:113], v[144:147], v[190:193], v[110:113]
	v_mfma_f32_16x16x32_bf16 v[106:109], v[152:155], v[190:193], v[106:109]
	v_mfma_f32_16x16x32_bf16 v[94:97], v[144:147], v[198:201], v[94:97]
	v_mfma_f32_16x16x32_bf16 v[90:93], v[152:155], v[198:201], v[90:93]
	v_mfma_f32_16x16x32_bf16 v[78:81], v[144:147], v[224:227], v[78:81]
	v_mfma_f32_16x16x32_bf16 v[74:77], v[152:155], v[224:227], v[74:77]
	v_mfma_f32_16x16x32_bf16 v[126:129], v[148:151], v[186:189], v[126:129]
	v_mfma_f32_16x16x32_bf16 v[122:125], v[156:159], v[186:189], v[122:125]
	v_mfma_f32_16x16x32_bf16 v[110:113], v[148:151], v[194:197], v[110:113]
	v_mfma_f32_16x16x32_bf16 v[106:109], v[156:159], v[194:197], v[106:109]
	v_mfma_f32_16x16x32_bf16 v[94:97], v[148:151], v[202:205], v[94:97]
	v_mfma_f32_16x16x32_bf16 v[90:93], v[156:159], v[202:205], v[90:93]
	v_mfma_f32_16x16x32_bf16 v[78:81], v[148:151], v[228:231], v[78:81]
	v_mfma_f32_16x16x32_bf16 v[74:77], v[156:159], v[228:231], v[74:77]
	v_mfma_f32_16x16x32_bf16 v[118:121], v[166:169], v[182:185], v[118:121]
	v_mfma_f32_16x16x32_bf16 v[114:117], v[174:177], v[182:185], v[114:117]
	v_mfma_f32_16x16x32_bf16 v[102:105], v[166:169], v[190:193], v[102:105]
	v_mfma_f32_16x16x32_bf16 v[98:101], v[174:177], v[190:193], v[98:101]
	v_mfma_f32_16x16x32_bf16 v[86:89], v[166:169], v[198:201], v[86:89]
	v_mfma_f32_16x16x32_bf16 v[82:85], v[174:177], v[198:201], v[82:85]
	v_mfma_f32_16x16x32_bf16 v[70:73], v[166:169], v[224:227], v[70:73]
	v_mfma_f32_16x16x32_bf16 v[66:69], v[174:177], v[224:227], v[66:69]
	v_mfma_f32_16x16x32_bf16 v[118:121], v[170:173], v[186:189], v[118:121]
	v_mfma_f32_16x16x32_bf16 v[114:117], v[178:181], v[186:189], v[114:117]
	v_mfma_f32_16x16x32_bf16 v[102:105], v[170:173], v[194:197], v[102:105]
	v_mfma_f32_16x16x32_bf16 v[98:101], v[178:181], v[194:197], v[98:101]
	v_mfma_f32_16x16x32_bf16 v[86:89], v[170:173], v[202:205], v[86:89]
	v_mfma_f32_16x16x32_bf16 v[82:85], v[178:181], v[202:205], v[82:85]
	v_mfma_f32_16x16x32_bf16 v[70:73], v[170:173], v[228:231], v[70:73]
	v_mfma_f32_16x16x32_bf16 v[66:69], v[178:181], v[228:231], v[66:69]
	s_barrier
	s_setprio 0
	s_add_i32 s48, s48, s26
	v_lshl_add_u64 v[138:139], s[20:21], 0, v[0:1]
	s_mov_b32 m0, s48
	ds_read_b128 v[182:185], v164 offset:16384
	ds_read_b128 v[186:189], v164 offset:17408
	ds_read_b128 v[190:193], v164 offset:18432
	ds_read_b128 v[194:197], v164 offset:19456
	ds_read_b128 v[198:201], v164 offset:20480
	ds_read_b128 v[202:205], v164 offset:21504
	ds_read_b128 v[224:227], v164 offset:22528
	ds_read_b128 v[228:231], v164 offset:23552
	global_load_lds_dwordx4 v[138:139], off
	s_add_i32 m0, s48, 0x2000
	s_add_u32 s48, s20, 0x40000
	v_lshl_add_u64 v[140:141], s[20:21], 0, v[134:135]
	s_addc_u32 s49, s21, 0
	s_add_i32 s50, s50, s26
	global_load_lds_dwordx4 v[140:141], off
	v_lshl_add_u64 v[232:233], s[48:49], 0, v[0:1]
	s_mov_b32 m0, s50
	v_lshl_add_u64 v[234:235], s[22:23], 0, v[132:133]
	global_load_lds_dwordx4 v[232:233], off
	v_lshl_add_u64 v[232:233], s[48:49], 0, v[134:135]
	s_add_i32 m0, s50, 0x2000
	s_nop 0
	global_load_lds_dwordx4 v[232:233], off
	v_lshl_add_u64 v[232:233], s[22:23], 0, v[130:131]
	s_mov_b32 m0, s30
	s_nop 0
	global_load_lds_dwordx4 v[232:233], off
	s_mov_b32 m0, s31
	s_nop 0
	global_load_lds_dwordx4 v[234:235], off
	s_waitcnt vmcnt(8)
	s_waitcnt lgkmcnt(0)
	s_setprio 1
	s_barrier
	v_mfma_f32_16x16x32_bf16 v[62:65], v[144:147], v[182:185], v[62:65]
	v_mfma_f32_16x16x32_bf16 v[58:61], v[152:155], v[182:185], v[58:61]
	v_mfma_f32_16x16x32_bf16 v[46:49], v[144:147], v[190:193], v[46:49]
	v_mfma_f32_16x16x32_bf16 v[42:45], v[152:155], v[190:193], v[42:45]
	v_mfma_f32_16x16x32_bf16 v[30:33], v[144:147], v[198:201], v[30:33]
	v_mfma_f32_16x16x32_bf16 v[26:29], v[152:155], v[198:201], v[26:29]
	v_mfma_f32_16x16x32_bf16 v[14:17], v[144:147], v[224:227], v[14:17]
	v_mfma_f32_16x16x32_bf16 v[10:13], v[152:155], v[224:227], v[10:13]
	v_mfma_f32_16x16x32_bf16 v[62:65], v[148:151], v[186:189], v[62:65]
	v_mfma_f32_16x16x32_bf16 v[58:61], v[156:159], v[186:189], v[58:61]
	v_mfma_f32_16x16x32_bf16 v[46:49], v[148:151], v[194:197], v[46:49]
	v_mfma_f32_16x16x32_bf16 v[42:45], v[156:159], v[194:197], v[42:45]
	v_mfma_f32_16x16x32_bf16 v[30:33], v[148:151], v[202:205], v[30:33]
	v_mfma_f32_16x16x32_bf16 v[26:29], v[156:159], v[202:205], v[26:29]
	v_mfma_f32_16x16x32_bf16 v[14:17], v[148:151], v[228:231], v[14:17]
	v_mfma_f32_16x16x32_bf16 v[10:13], v[156:159], v[228:231], v[10:13]
	v_mfma_f32_16x16x32_bf16 v[54:57], v[166:169], v[182:185], v[54:57]
	v_mfma_f32_16x16x32_bf16 v[50:53], v[174:177], v[182:185], v[50:53]
	v_mfma_f32_16x16x32_bf16 v[38:41], v[166:169], v[190:193], v[38:41]
	v_mfma_f32_16x16x32_bf16 v[34:37], v[174:177], v[190:193], v[34:37]
	v_mfma_f32_16x16x32_bf16 v[22:25], v[166:169], v[198:201], v[22:25]
	v_mfma_f32_16x16x32_bf16 v[18:21], v[174:177], v[198:201], v[18:21]
	v_mfma_f32_16x16x32_bf16 v[6:9], v[166:169], v[224:227], v[6:9]
	v_mfma_f32_16x16x32_bf16 v[2:5], v[174:177], v[224:227], v[2:5]
	v_mfma_f32_16x16x32_bf16 v[54:57], v[170:173], v[186:189], v[54:57]
	v_mfma_f32_16x16x32_bf16 v[50:53], v[178:181], v[186:189], v[50:53]
	v_mfma_f32_16x16x32_bf16 v[38:41], v[170:173], v[194:197], v[38:41]
	v_mfma_f32_16x16x32_bf16 v[34:37], v[178:181], v[194:197], v[34:37]
	v_mfma_f32_16x16x32_bf16 v[22:25], v[170:173], v[202:205], v[22:25]
	v_mfma_f32_16x16x32_bf16 v[18:21], v[178:181], v[202:205], v[18:21]
	v_mfma_f32_16x16x32_bf16 v[6:9], v[170:173], v[228:231], v[6:9]
	v_mfma_f32_16x16x32_bf16 v[2:5], v[178:181], v[228:231], v[2:5]
	s_barrier
; #define PG8_STAGE(bufoff, gbase, voff) do { _Pragma("unroll") for (int _i = 0; _i < 2; ++_i) \
;         __builtin_amdgcn_global_load_lds((const unsigned*)((const char*)(gbase) + (voff)[_i]), (PG8_LAS unsigned*)(lds + (bufoff) + ldsw + _i * 8192), 16, 0, 0); } while (0)
; #define PG8_LDA(dst, b, h) do { _Pragma("unroll") for (int m = 0; m < 4; ++m) _Pragma("unroll") for (int k = 0; k < 2; ++k) dst[m][k] = *(const PG8_LAS bf16x8*)(lds + PG8_SA(b, h) + aoff + m * 2048 + k * 1024); } while (0)
; #define PG8_LDB(dst, b, h) do { _Pragma("unroll") for (int n = 0; n < 2; ++n) _Pragma("unroll") for (int k = 0; k < 2; ++k) dst[n][k] = *(const PG8_LAS bf16x8*)(lds + PG8_SB(b, h) + boff + n * 2048 + k * 1024); } while (0)
; #define PG8_MMA(ai, bj, At, Bt) do { __builtin_amdgcn_s_setprio(1); _Pragma("unroll") for (int m = 0; m < 4; ++m) _Pragma("unroll") for (int n = 0; n < 2; ++n) _Pragma("unroll") for (int k = 0; k < 2; ++k) \
;         acc[ai][bj][m][n] = __builtin_amdgcn_mfma_f32_16x16x32_bf16(Bt[n][k], At[m][k], acc[ai][bj][m][n], 0, 0, 0); __builtin_amdgcn_s_setprio(0); } while (0)
; #define PG8_WAIT_V(n) asm volatile("s_waitcnt vmcnt(" #n ")" ::: "memory")
; #define PG8_WAIT_L(n) asm volatile("s_waitcnt lgkmcnt(" #n ")" ::: "memory")
; #define PG8_BAR __builtin_amdgcn_s_barrier()
; #define PG8_SCHED __builtin_amdgcn_sched_barrier(0)
; template <class Epi, class Sched, bool ALIGN_EPI = false, bool SP2 = false>
; __device__ __forceinline__ void gemm_phase(PG8_LAS unsigned char* lds, const Gemm g, const Sched& S, const Epi& E) {
;     ...
;             PG8_LDB(B0, 1, 0); PG8_LDB(B1, 1, 1); PG8_SCHED; PG8_LDA(At, 1, 0); PG8_STAGE(PG8_SA(0, 1), a2 + hstep, voffA);
;             PG8_WAIT_V(8); PG8_WAIT_L(0); PG8_BAR; PG8_MMA(0, 0, At, B0); PG8_MMA(0, 1, At, B1); PG8_BAR; PG8_SCHED;
	s_setprio 0
	s_add_i32 s48, 0, 0x18000
	s_add_i32 s49, 0, 0x1c000
	v_add_u32_e32 v156, s48, v161
	v_add_u32_e32 v165, s49, v161
	ds_read_b128 v[144:147], v156
	ds_read_b128 v[148:151], v156 offset:1024
	ds_read_b128 v[152:155], v156 offset:2048
	ds_read_b128 v[156:159], v156 offset:3072
	ds_read_b128 v[166:169], v165
	ds_read_b128 v[170:173], v165 offset:1024
	ds_read_b128 v[174:177], v165 offset:2048
	ds_read_b128 v[178:181], v165 offset:3072
	s_add_u32 s22, s22, 0x40000
	s_addc_u32 s23, s23, 0
	s_mov_b32 m0, s38
	v_lshl_add_u64 v[236:237], s[22:23], 0, v[130:131]
	ds_read_b128 v[182:185], v164 offset:32768
	ds_read_b128 v[186:189], v164 offset:33792
	ds_read_b128 v[190:193], v164 offset:34816
	ds_read_b128 v[194:197], v164 offset:35840
	ds_read_b128 v[198:201], v164 offset:36864
	ds_read_b128 v[202:205], v164 offset:37888
	ds_read_b128 v[224:227], v164 offset:38912
	ds_read_b128 v[228:231], v164 offset:39936
	global_load_lds_dwordx4 v[236:237], off
	v_lshl_add_u64 v[236:237], s[22:23], 0, v[132:133]
	s_mov_b32 m0, s39
	s_nop 0
	global_load_lds_dwordx4 v[236:237], off
	s_waitcnt vmcnt(8)
	s_waitcnt lgkmcnt(0)
	s_setprio 1
	s_barrier
	v_mfma_f32_16x16x32_bf16 v[126:129], v[144:147], v[182:185], v[126:129]
	v_mfma_f32_16x16x32_bf16 v[122:125], v[152:155], v[182:185], v[122:125]
	v_mfma_f32_16x16x32_bf16 v[110:113], v[144:147], v[190:193], v[110:113]
	v_mfma_f32_16x16x32_bf16 v[106:109], v[152:155], v[190:193], v[106:109]
	v_mfma_f32_16x16x32_bf16 v[94:97], v[144:147], v[198:201], v[94:97]
	v_mfma_f32_16x16x32_bf16 v[90:93], v[152:155], v[198:201], v[90:93]
	v_mfma_f32_16x16x32_bf16 v[78:81], v[144:147], v[224:227], v[78:81]
	v_mfma_f32_16x16x32_bf16 v[74:77], v[152:155], v[224:227], v[74:77]
	v_mfma_f32_16x16x32_bf16 v[126:129], v[148:151], v[186:189], v[126:129]
	v_mfma_f32_16x16x32_bf16 v[122:125], v[156:159], v[186:189], v[122:125]
	v_mfma_f32_16x16x32_bf16 v[110:113], v[148:151], v[194:197], v[110:113]
	v_mfma_f32_16x16x32_bf16 v[106:109], v[156:159], v[194:197], v[106:109]
	v_mfma_f32_16x16x32_bf16 v[94:97], v[148:151], v[202:205], v[94:97]
	v_mfma_f32_16x16x32_bf16 v[90:93], v[156:159], v[202:205], v[90:93]
	v_mfma_f32_16x16x32_bf16 v[78:81], v[148:151], v[228:231], v[78:81]
	v_mfma_f32_16x16x32_bf16 v[74:77], v[156:159], v[228:231], v[74:77]
	v_mfma_f32_16x16x32_bf16 v[118:121], v[166:169], v[182:185], v[118:121]
	v_mfma_f32_16x16x32_bf16 v[114:117], v[174:177], v[182:185], v[114:117]
	v_mfma_f32_16x16x32_bf16 v[102:105], v[166:169], v[190:193], v[102:105]
	v_mfma_f32_16x16x32_bf16 v[98:101], v[174:177], v[190:193], v[98:101]
	v_mfma_f32_16x16x32_bf16 v[86:89], v[166:169], v[198:201], v[86:89]
	v_mfma_f32_16x16x32_bf16 v[82:85], v[174:177], v[198:201], v[82:85]
	v_mfma_f32_16x16x32_bf16 v[70:73], v[166:169], v[224:227], v[70:73]
	v_mfma_f32_16x16x32_bf16 v[66:69], v[174:177], v[224:227], v[66:69]
	v_mfma_f32_16x16x32_bf16 v[118:121], v[170:173], v[186:189], v[118:121]
	v_mfma_f32_16x16x32_bf16 v[114:117], v[178:181], v[186:189], v[114:117]
	v_mfma_f32_16x16x32_bf16 v[102:105], v[170:173], v[194:197], v[102:105]
	v_mfma_f32_16x16x32_bf16 v[98:101], v[178:181], v[194:197], v[98:101]
	v_mfma_f32_16x16x32_bf16 v[86:89], v[170:173], v[202:205], v[86:89]
	v_mfma_f32_16x16x32_bf16 v[82:85], v[178:181], v[202:205], v[82:85]
	v_mfma_f32_16x16x32_bf16 v[70:73], v[170:173], v[228:231], v[70:73]
	v_mfma_f32_16x16x32_bf16 v[66:69], v[178:181], v[228:231], v[66:69]
	s_barrier
; #define PG8_STAGE(bufoff, gbase, voff) do { _Pragma("unroll") for (int _i = 0; _i < 2; ++_i) \
;         __builtin_amdgcn_global_load_lds((const unsigned*)((const char*)(gbase) + (voff)[_i]), (PG8_LAS unsigned*)(lds + (bufoff) + ldsw + _i * 8192), 16, 0, 0); } while (0)
; #define PG8_LDA(dst, b, h) do { _Pragma("unroll") for (int m = 0; m < 4; ++m) _Pragma("unroll") for (int k = 0; k < 2; ++k) dst[m][k] = *(const PG8_LAS bf16x8*)(lds + PG8_SA(b, h) + aoff + m * 2048 + k * 1024); } while (0)
; #define PG8_MMA(ai, bj, At, Bt) do { __builtin_amdgcn_s_setprio(1); _Pragma("unroll") for (int m = 0; m < 4; ++m) _Pragma("unroll") for (int n = 0; n < 2; ++n) _Pragma("unroll") for (int k = 0; k < 2; ++k) \
;         acc[ai][bj][m][n] = __builtin_amdgcn_mfma_f32_16x16x32_bf16(Bt[n][k], At[m][k], acc[ai][bj][m][n], 0, 0, 0); __builtin_amdgcn_s_setprio(0); } while (0)
; #define PG8_WAIT_V(n) asm volatile("s_waitcnt vmcnt(" #n ")" ::: "memory")
; #define PG8_WAIT_L(n) asm volatile("s_waitcnt lgkmcnt(" #n ")" ::: "memory")
; #define PG8_BAR __builtin_amdgcn_s_barrier()
; #define PG8_SCHED __builtin_amdgcn_sched_barrier(0)
; template <class Epi, class Sched, bool ALIGN_EPI = false, bool SP2 = false>
; __device__ __forceinline__ void gemm_phase(PG8_LAS unsigned char* lds, const Gemm g, const Sched& S, const Epi& E) {
;     ...
;             PG8_LDA(At, 1, 1); PG8_STAGE(PG8_SB(1, 0), b3, voffB); PG8_STAGE(PG8_SB(1, 1), b3 + hstep, voffB); PG8_STAGE(PG8_SA(1, 0), a3, voffA);
;             PG8_WAIT_V(8); PG8_WAIT_L(0); PG8_BAR; PG8_MMA(1, 0, At, B0); PG8_MMA(1, 1, At, B1); PG8_BAR; PG8_SCHED;
	s_setprio 0
	s_add_i32 s22, s48, s26
	v_lshl_add_u64 v[138:139], v[138:139], 0, s[86:87]
	s_mov_b32 m0, s22
	ds_read_b128 v[182:185], v164 offset:49152
	ds_read_b128 v[186:189], v164 offset:50176
	ds_read_b128 v[190:193], v164 offset:51200
	ds_read_b128 v[194:197], v164 offset:52224
	ds_read_b128 v[198:201], v164 offset:53248
	ds_read_b128 v[202:205], v164 offset:54272
	ds_read_b128 v[224:227], v164 offset:55296
	ds_read_b128 v[228:231], v164 offset:56320
	global_load_lds_dwordx4 v[138:139], off
	s_add_i32 m0, s22, 0x2000
	s_add_u32 s20, s20, 0x40080
	v_lshl_add_u64 v[138:139], v[140:141], 0, s[86:87]
	s_addc_u32 s21, s21, 0
	s_add_i32 s22, s49, s26
	global_load_lds_dwordx4 v[138:139], off
	v_lshl_add_u64 v[138:139], s[20:21], 0, v[0:1]
	s_mov_b32 m0, s22
	s_nop 0
	global_load_lds_dwordx4 v[138:139], off
	v_lshl_add_u64 v[138:139], s[20:21], 0, v[134:135]
	s_add_i32 m0, s22, 0x2000
	s_nop 0
	global_load_lds_dwordx4 v[138:139], off
	v_lshl_add_u64 v[138:139], v[232:233], 0, s[86:87]
	s_mov_b32 m0, s41
	s_nop 0
	global_load_lds_dwordx4 v[138:139], off
	v_lshl_add_u64 v[138:139], v[234:235], 0, s[86:87]
	s_mov_b32 m0, s42
	s_nop 0
	global_load_lds_dwordx4 v[138:139], off
	s_waitcnt vmcnt(8)
	s_waitcnt lgkmcnt(0)
	s_setprio 1
	s_barrier
	v_mfma_f32_16x16x32_bf16 v[62:65], v[144:147], v[182:185], v[62:65]
	v_mfma_f32_16x16x32_bf16 v[58:61], v[152:155], v[182:185], v[58:61]
	v_mfma_f32_16x16x32_bf16 v[46:49], v[144:147], v[190:193], v[46:49]
	v_mfma_f32_16x16x32_bf16 v[42:45], v[152:155], v[190:193], v[42:45]
	v_mfma_f32_16x16x32_bf16 v[30:33], v[144:147], v[198:201], v[30:33]
	v_mfma_f32_16x16x32_bf16 v[26:29], v[152:155], v[198:201], v[26:29]
	v_mfma_f32_16x16x32_bf16 v[14:17], v[144:147], v[224:227], v[14:17]
	v_mfma_f32_16x16x32_bf16 v[10:13], v[152:155], v[224:227], v[10:13]
	v_mfma_f32_16x16x32_bf16 v[62:65], v[148:151], v[186:189], v[62:65]
	v_mfma_f32_16x16x32_bf16 v[58:61], v[156:159], v[186:189], v[58:61]
	v_mfma_f32_16x16x32_bf16 v[46:49], v[148:151], v[194:197], v[46:49]
	v_mfma_f32_16x16x32_bf16 v[42:45], v[156:159], v[194:197], v[42:45]
	v_mfma_f32_16x16x32_bf16 v[30:33], v[148:151], v[202:205], v[30:33]
	v_mfma_f32_16x16x32_bf16 v[26:29], v[156:159], v[202:205], v[26:29]
	v_mfma_f32_16x16x32_bf16 v[14:17], v[148:151], v[228:231], v[14:17]
	v_mfma_f32_16x16x32_bf16 v[10:13], v[156:159], v[228:231], v[10:13]
	v_mfma_f32_16x16x32_bf16 v[54:57], v[166:169], v[182:185], v[54:57]
	v_mfma_f32_16x16x32_bf16 v[50:53], v[174:177], v[182:185], v[50:53]
	v_mfma_f32_16x16x32_bf16 v[38:41], v[166:169], v[190:193], v[38:41]
	v_mfma_f32_16x16x32_bf16 v[34:37], v[174:177], v[190:193], v[34:37]
	v_mfma_f32_16x16x32_bf16 v[22:25], v[166:169], v[198:201], v[22:25]
	v_mfma_f32_16x16x32_bf16 v[18:21], v[174:177], v[198:201], v[18:21]
	v_mfma_f32_16x16x32_bf16 v[6:9], v[166:169], v[224:227], v[6:9]
	v_mfma_f32_16x16x32_bf16 v[2:5], v[174:177], v[224:227], v[2:5]
	v_mfma_f32_16x16x32_bf16 v[54:57], v[170:173], v[186:189], v[54:57]
	v_mfma_f32_16x16x32_bf16 v[50:53], v[178:181], v[186:189], v[50:53]
	v_mfma_f32_16x16x32_bf16 v[38:41], v[170:173], v[194:197], v[38:41]
	v_mfma_f32_16x16x32_bf16 v[34:37], v[178:181], v[194:197], v[34:37]
	v_mfma_f32_16x16x32_bf16 v[22:25], v[170:173], v[202:205], v[22:25]
	v_mfma_f32_16x16x32_bf16 v[18:21], v[178:181], v[202:205], v[18:21]
	v_mfma_f32_16x16x32_bf16 v[6:9], v[170:173], v[228:231], v[6:9]
	v_mfma_f32_16x16x32_bf16 v[2:5], v[178:181], v[228:231], v[2:5]
	s_barrier
	s_setprio 0
	s_add_i32 s47, s47, 2
	s_add_u32 s8, s8, 0x100
	s_addc_u32 s9, s9, 0
	s_add_u32 s45, s45, 0x100
	s_addc_u32 s46, s46, 0
	s_cmp_gt_u32 s47, 13
	s_cbranch_scc0 .LBB0_492

; #define PG8_STAGE(bufoff, gbase, voff) do { _Pragma("unroll") for (int _i = 0; _i < 2; ++_i) \
;         __builtin_amdgcn_global_load_lds((const unsigned*)((const char*)(gbase) + (voff)[_i]), (PG8_LAS unsigned*)(lds + (bufoff) + ldsw + _i * 8192), 16, 0, 0); } while (0)
; #define PG8_LDA(dst, b, h) do { _Pragma("unroll") for (int m = 0; m < 4; ++m) _Pragma("unroll") for (int k = 0; k < 2; ++k) dst[m][k] = *(const PG8_LAS bf16x8*)(lds + PG8_SA(b, h) + aoff + m * 2048 + k * 1024); } while (0)
; #define PG8_LDB(dst, b, h) do { _Pragma("unroll") for (int n = 0; n < 2; ++n) _Pragma("unroll") for (int k = 0; k < 2; ++k) dst[n][k] = *(const PG8_LAS bf16x8*)(lds + PG8_SB(b, h) + boff + n * 2048 + k * 1024); } while (0)
; #define PG8_MMA(ai, bj, At, Bt) do { __builtin_amdgcn_s_setprio(1); _Pragma("unroll") for (int m = 0; m < 4; ++m) _Pragma("unroll") for (int n = 0; n < 2; ++n) _Pragma("unroll") for (int k = 0; k < 2; ++k) \
;         acc[ai][bj][m][n] = __builtin_amdgcn_mfma_f32_16x16x32_bf16(Bt[n][k], At[m][k], acc[ai][bj][m][n], 0, 0, 0); __builtin_amdgcn_s_setprio(0); } while (0)
; #define PG8_WAIT_V(n) asm volatile("s_waitcnt vmcnt(" #n ")" ::: "memory")
; #define PG8_WAIT_L(n) asm volatile("s_waitcnt lgkmcnt(" #n ")" ::: "memory")
; #define PG8_BAR __builtin_amdgcn_s_barrier()
; #define PG8_SCHED __builtin_amdgcn_sched_barrier(0)
; template <class Epi, class Sched, bool ALIGN_EPI = false, bool SP2 = false>
; __device__ __forceinline__ void gemm_phase(PG8_LAS unsigned char* lds, const Gemm g, const Sched& S, const Epi& E) {
;     ...
;         for (int t = 0; t < nt; t += 2) {
;             const bool last = (t == nt - 2);
;             const char* a1 = cA + (size_t)(t + 1) * kstep;
;             const char* a2 = last ? nA : cA + (size_t)(t + 2) * kstep; const char* b2 = last ? nB : cB + (size_t)(t + 2) * kstep;
;             const char* a3 = a2 + kstep; const char* b3 = b2 + kstep;
;             if (last && has_next) S.a_ready(nxt);
;             if constexpr (SP2) {
;             PG8_LDB(B0, 0, 0); PG8_LDB(B1, 0, 1); PG8_SCHED; PG8_LDA(At, 0, 0); PG8_STAGE(PG8_SA(1, 1), a1 + hstep, voffA);
;             PG8_WAIT_V(8); PG8_WAIT_L(0); PG8_BAR; PG8_MMA(0, 0, At, B0); PG8_MMA(0, 1, At, B1); PG8_BAR; PG8_SCHED;
;             PG8_LDA(At, 0, 1); PG8_STAGE(PG8_SB(0, 0), b2, voffB); PG8_STAGE(PG8_SB(0, 1), b2 + hstep, voffB); PG8_STAGE(PG8_SA(0, 0), a2, voffA);
.LBB0_891:
	s_add_u32 s18, s16, 0xfffe0080
	s_addc_u32 s19, s17, -1
	s_add_i32 s46, 0, 0x10000
	s_cmp_eq_u32 s45, 4
	s_cselect_b32 s21, s9, s19
	s_cselect_b32 s20, s41, s18
	v_add_u32_e32 v148, s46, v151
	s_cselect_b32 s19, s7, s44
	s_cselect_b32 s18, s42, s43
	s_add_i32 s48, 0, 0x14000
	ds_read_b128 v[138:141], v148
	ds_read_b128 v[144:147], v148 offset:1024
	ds_read_b128 v[154:157], v148 offset:2048
	ds_read_b128 v[158:161], v148 offset:3072
	v_add_u32_e32 v148, s48, v151
	ds_read_b128 v[162:165], v148
	ds_read_b128 v[166:169], v148 offset:1024
	ds_read_b128 v[170:173], v148 offset:2048
	ds_read_b128 v[174:177], v148 offset:3072
	v_lshl_add_u64 v[148:149], s[16:17], 0, v[136:137]
	s_add_i32 m0, s27, 0xc000
	ds_read_b128 v[178:181], v153
	ds_read_b128 v[182:185], v153 offset:1024
	ds_read_b128 v[186:189], v153 offset:2048
	ds_read_b128 v[190:193], v153 offset:3072
	ds_read_b128 v[194:197], v153 offset:4096
	ds_read_b128 v[198:201], v153 offset:5120
	ds_read_b128 v[202:205], v153 offset:6144
	ds_read_b128 v[224:227], v153 offset:7168
	global_load_lds_dwordx4 v[148:149], off
	v_lshl_add_u64 v[148:149], s[16:17], 0, v[142:143]
	s_add_i32 m0, s27, 0xe000
	s_nop 0
	global_load_lds_dwordx4 v[148:149], off
	s_waitcnt vmcnt(8)
	s_waitcnt lgkmcnt(0)
	s_setprio 1
	s_barrier
	v_mfma_f32_16x16x32_bf16 v[126:129], v[138:141], v[178:181], v[126:129]
	v_mfma_f32_16x16x32_bf16 v[122:125], v[154:157], v[178:181], v[122:125]
	v_mfma_f32_16x16x32_bf16 v[110:113], v[138:141], v[186:189], v[110:113]
	v_mfma_f32_16x16x32_bf16 v[106:109], v[154:157], v[186:189], v[106:109]
	v_mfma_f32_16x16x32_bf16 v[94:97], v[138:141], v[194:197], v[94:97]
	v_mfma_f32_16x16x32_bf16 v[90:93], v[154:157], v[194:197], v[90:93]
	v_mfma_f32_16x16x32_bf16 v[78:81], v[138:141], v[202:205], v[78:81]
	v_mfma_f32_16x16x32_bf16 v[74:77], v[154:157], v[202:205], v[74:77]
	v_mfma_f32_16x16x32_bf16 v[126:129], v[144:147], v[182:185], v[126:129]
	v_mfma_f32_16x16x32_bf16 v[122:125], v[158:161], v[182:185], v[122:125]
	v_mfma_f32_16x16x32_bf16 v[110:113], v[144:147], v[190:193], v[110:113]
	v_mfma_f32_16x16x32_bf16 v[106:109], v[158:161], v[190:193], v[106:109]
	v_mfma_f32_16x16x32_bf16 v[94:97], v[144:147], v[198:201], v[94:97]
	v_mfma_f32_16x16x32_bf16 v[90:93], v[158:161], v[198:201], v[90:93]
	v_mfma_f32_16x16x32_bf16 v[78:81], v[144:147], v[224:227], v[78:81]
	v_mfma_f32_16x16x32_bf16 v[74:77], v[158:161], v[224:227], v[74:77]
	v_mfma_f32_16x16x32_bf16 v[118:121], v[162:165], v[178:181], v[118:121]
	v_mfma_f32_16x16x32_bf16 v[114:117], v[170:173], v[178:181], v[114:117]
	v_mfma_f32_16x16x32_bf16 v[102:105], v[162:165], v[186:189], v[102:105]
	v_mfma_f32_16x16x32_bf16 v[98:101], v[170:173], v[186:189], v[98:101]
	v_mfma_f32_16x16x32_bf16 v[86:89], v[162:165], v[194:197], v[86:89]
	v_mfma_f32_16x16x32_bf16 v[82:85], v[170:173], v[194:197], v[82:85]
	v_mfma_f32_16x16x32_bf16 v[70:73], v[162:165], v[202:205], v[70:73]
	v_mfma_f32_16x16x32_bf16 v[66:69], v[170:173], v[202:205], v[66:69]
	v_mfma_f32_16x16x32_bf16 v[118:121], v[166:169], v[182:185], v[118:121]
	v_mfma_f32_16x16x32_bf16 v[114:117], v[174:177], v[182:185], v[114:117]
	v_mfma_f32_16x16x32_bf16 v[102:105], v[166:169], v[190:193], v[102:105]
	v_mfma_f32_16x16x32_bf16 v[98:101], v[174:177], v[190:193], v[98:101]
	v_mfma_f32_16x16x32_bf16 v[86:89], v[166:169], v[198:201], v[86:89]
	v_mfma_f32_16x16x32_bf16 v[82:85], v[174:177], v[198:201], v[82:85]
	v_mfma_f32_16x16x32_bf16 v[70:73], v[166:169], v[224:227], v[70:73]
	v_mfma_f32_16x16x32_bf16 v[66:69], v[174:177], v[224:227], v[66:69]
	s_barrier
	s_setprio 0
	s_add_i32 s46, s46, s26
	v_lshl_add_u64 v[148:149], s[18:19], 0, v[0:1]
	s_mov_b32 m0, s46
	ds_read_b128 v[178:181], v153 offset:16384
	ds_read_b128 v[182:185], v153 offset:17408
	ds_read_b128 v[186:189], v153 offset:18432
	ds_read_b128 v[190:193], v153 offset:19456
	ds_read_b128 v[194:197], v153 offset:20480
	ds_read_b128 v[198:201], v153 offset:21504
	ds_read_b128 v[202:205], v153 offset:22528
	ds_read_b128 v[224:227], v153 offset:23552
	global_load_lds_dwordx4 v[148:149], off
	s_add_i32 m0, s46, 0x2000
	s_add_u32 s46, s18, 0x20000
	v_lshl_add_u64 v[228:229], s[18:19], 0, v[134:135]
	s_addc_u32 s47, s19, 0
	s_add_i32 s48, s48, s26
	global_load_lds_dwordx4 v[228:229], off
	v_lshl_add_u64 v[230:231], s[46:47], 0, v[0:1]
	s_mov_b32 m0, s48
	v_lshl_add_u64 v[232:233], s[20:21], 0, v[132:133]
	global_load_lds_dwordx4 v[230:231], off
	v_lshl_add_u64 v[230:231], s[46:47], 0, v[134:135]
	s_add_i32 m0, s48, 0x2000
	s_nop 0
	global_load_lds_dwordx4 v[230:231], off
	v_lshl_add_u64 v[230:231], s[20:21], 0, v[130:131]
	s_mov_b32 m0, s27
	s_nop 0
	global_load_lds_dwordx4 v[230:231], off
	s_mov_b32 m0, s28
	s_nop 0
	global_load_lds_dwordx4 v[232:233], off
	s_waitcnt vmcnt(8)
	s_waitcnt lgkmcnt(0)
	s_setprio 1
	s_barrier
; #define PG8_STAGE(bufoff, gbase, voff) do { _Pragma("unroll") for (int _i = 0; _i < 2; ++_i) \
;         __builtin_amdgcn_global_load_lds((const unsigned*)((const char*)(gbase) + (voff)[_i]), (PG8_LAS unsigned*)(lds + (bufoff) + ldsw + _i * 8192), 16, 0, 0); } while (0)
; #define PG8_LDA(dst, b, h) do { _Pragma("unroll") for (int m = 0; m < 4; ++m) _Pragma("unroll") for (int k = 0; k < 2; ++k) dst[m][k] = *(const PG8_LAS bf16x8*)(lds + PG8_SA(b, h) + aoff + m * 2048 + k * 1024); } while (0)
; #define PG8_LDB(dst, b, h) do { _Pragma("unroll") for (int n = 0; n < 2; ++n) _Pragma("unroll") for (int k = 0; k < 2; ++k) dst[n][k] = *(const PG8_LAS bf16x8*)(lds + PG8_SB(b, h) + boff + n * 2048 + k * 1024); } while (0)
; #define PG8_MMA(ai, bj, At, Bt) do { __builtin_amdgcn_s_setprio(1); _Pragma("unroll") for (int m = 0; m < 4; ++m) _Pragma("unroll") for (int n = 0; n < 2; ++n) _Pragma("unroll") for (int k = 0; k < 2; ++k) \
;         acc[ai][bj][m][n] = __builtin_amdgcn_mfma_f32_16x16x32_bf16(Bt[n][k], At[m][k], acc[ai][bj][m][n], 0, 0, 0); __builtin_amdgcn_s_setprio(0); } while (0)
; #define PG8_WAIT_V(n) asm volatile("s_waitcnt vmcnt(" #n ")" ::: "memory")
; #define PG8_WAIT_L(n) asm volatile("s_waitcnt lgkmcnt(" #n ")" ::: "memory")
; #define PG8_BAR __builtin_amdgcn_s_barrier()
; #define PG8_SCHED __builtin_amdgcn_sched_barrier(0)
; template <class Epi, class Sched, bool ALIGN_EPI = false, bool SP2 = false>
; __device__ __forceinline__ void gemm_phase(PG8_LAS unsigned char* lds, const Gemm g, const Sched& S, const Epi& E) {
;     ...
;             PG8_WAIT_V(8); PG8_WAIT_L(0); PG8_BAR; PG8_MMA(1, 0, At, B0); PG8_MMA(1, 1, At, B1); PG8_BAR; PG8_SCHED;
;             PG8_LDB(B0, 1, 0); PG8_LDB(B1, 1, 1); PG8_SCHED; PG8_LDA(At, 1, 0); PG8_STAGE(PG8_SA(0, 1), a2 + hstep, voffA);
;             PG8_WAIT_V(8); PG8_WAIT_L(0); PG8_BAR; PG8_MMA(0, 0, At, B0); PG8_MMA(0, 1, At, B1); PG8_BAR; PG8_SCHED;
	v_mfma_f32_16x16x32_bf16 v[62:65], v[138:141], v[178:181], v[62:65]
	v_mfma_f32_16x16x32_bf16 v[58:61], v[154:157], v[178:181], v[58:61]
	v_mfma_f32_16x16x32_bf16 v[46:49], v[138:141], v[186:189], v[46:49]
	v_mfma_f32_16x16x32_bf16 v[42:45], v[154:157], v[186:189], v[42:45]
	v_mfma_f32_16x16x32_bf16 v[30:33], v[138:141], v[194:197], v[30:33]
	v_mfma_f32_16x16x32_bf16 v[26:29], v[154:157], v[194:197], v[26:29]
	v_mfma_f32_16x16x32_bf16 v[14:17], v[138:141], v[202:205], v[14:17]
	v_mfma_f32_16x16x32_bf16 v[10:13], v[154:157], v[202:205], v[10:13]
	v_mfma_f32_16x16x32_bf16 v[62:65], v[144:147], v[182:185], v[62:65]
	v_mfma_f32_16x16x32_bf16 v[58:61], v[158:161], v[182:185], v[58:61]
	v_mfma_f32_16x16x32_bf16 v[46:49], v[144:147], v[190:193], v[46:49]
	v_mfma_f32_16x16x32_bf16 v[42:45], v[158:161], v[190:193], v[42:45]
	v_mfma_f32_16x16x32_bf16 v[30:33], v[144:147], v[198:201], v[30:33]
	v_mfma_f32_16x16x32_bf16 v[26:29], v[158:161], v[198:201], v[26:29]
	v_mfma_f32_16x16x32_bf16 v[14:17], v[144:147], v[224:227], v[14:17]
	v_mfma_f32_16x16x32_bf16 v[10:13], v[158:161], v[224:227], v[10:13]
	v_mfma_f32_16x16x32_bf16 v[54:57], v[162:165], v[178:181], v[54:57]
	v_mfma_f32_16x16x32_bf16 v[50:53], v[170:173], v[178:181], v[50:53]
	v_mfma_f32_16x16x32_bf16 v[38:41], v[162:165], v[186:189], v[38:41]
	v_mfma_f32_16x16x32_bf16 v[34:37], v[170:173], v[186:189], v[34:37]
	v_mfma_f32_16x16x32_bf16 v[22:25], v[162:165], v[194:197], v[22:25]
	v_mfma_f32_16x16x32_bf16 v[18:21], v[170:173], v[194:197], v[18:21]
	v_mfma_f32_16x16x32_bf16 v[6:9], v[162:165], v[202:205], v[6:9]
	v_mfma_f32_16x16x32_bf16 v[2:5], v[170:173], v[202:205], v[2:5]
	v_mfma_f32_16x16x32_bf16 v[54:57], v[166:169], v[182:185], v[54:57]
	v_mfma_f32_16x16x32_bf16 v[50:53], v[174:177], v[182:185], v[50:53]
	v_mfma_f32_16x16x32_bf16 v[38:41], v[166:169], v[190:193], v[38:41]
	v_mfma_f32_16x16x32_bf16 v[34:37], v[174:177], v[190:193], v[34:37]
	v_mfma_f32_16x16x32_bf16 v[22:25], v[166:169], v[198:201], v[22:25]
	v_mfma_f32_16x16x32_bf16 v[18:21], v[174:177], v[198:201], v[18:21]
	v_mfma_f32_16x16x32_bf16 v[6:9], v[166:169], v[224:227], v[6:9]
	v_mfma_f32_16x16x32_bf16 v[2:5], v[174:177], v[224:227], v[2:5]
	s_barrier
	s_setprio 0
	s_add_i32 s46, 0, 0x18000
	s_add_i32 s47, 0, 0x1c000
	v_add_u32_e32 v158, s46, v151
	v_add_u32_e32 v174, s47, v151
	ds_read_b128 v[138:141], v158
	ds_read_b128 v[144:147], v158 offset:1024
	ds_read_b128 v[154:157], v158 offset:2048
	ds_read_b128 v[158:161], v158 offset:3072
	ds_read_b128 v[162:165], v174
	ds_read_b128 v[166:169], v174 offset:1024
	ds_read_b128 v[170:173], v174 offset:2048
	ds_read_b128 v[174:177], v174 offset:3072
	s_add_u32 s20, s20, 0x20000
	s_addc_u32 s21, s21, 0
	s_mov_b32 m0, s29
	v_lshl_add_u64 v[234:235], s[20:21], 0, v[130:131]
	ds_read_b128 v[178:181], v153 offset:32768
	ds_read_b128 v[182:185], v153 offset:33792
	ds_read_b128 v[186:189], v153 offset:34816
	ds_read_b128 v[190:193], v153 offset:35840
	ds_read_b128 v[194:197], v153 offset:36864
	ds_read_b128 v[198:201], v153 offset:37888
	ds_read_b128 v[202:205], v153 offset:38912
	ds_read_b128 v[224:227], v153 offset:39936
	global_load_lds_dwordx4 v[234:235], off
	v_lshl_add_u64 v[234:235], s[20:21], 0, v[132:133]
	s_mov_b32 m0, s30
	s_nop 0
	global_load_lds_dwordx4 v[234:235], off
	s_waitcnt vmcnt(8)
	s_waitcnt lgkmcnt(0)
	s_setprio 1
	s_barrier
	v_mfma_f32_16x16x32_bf16 v[126:129], v[138:141], v[178:181], v[126:129]
	v_mfma_f32_16x16x32_bf16 v[122:125], v[154:157], v[178:181], v[122:125]
	v_mfma_f32_16x16x32_bf16 v[110:113], v[138:141], v[186:189], v[110:113]
	v_mfma_f32_16x16x32_bf16 v[106:109], v[154:157], v[186:189], v[106:109]
	v_mfma_f32_16x16x32_bf16 v[94:97], v[138:141], v[194:197], v[94:97]
	v_mfma_f32_16x16x32_bf16 v[90:93], v[154:157], v[194:197], v[90:93]
	v_mfma_f32_16x16x32_bf16 v[78:81], v[138:141], v[202:205], v[78:81]
	v_mfma_f32_16x16x32_bf16 v[74:77], v[154:157], v[202:205], v[74:77]
	v_mfma_f32_16x16x32_bf16 v[126:129], v[144:147], v[182:185], v[126:129]
	v_mfma_f32_16x16x32_bf16 v[122:125], v[158:161], v[182:185], v[122:125]
	v_mfma_f32_16x16x32_bf16 v[110:113], v[144:147], v[190:193], v[110:113]
	v_mfma_f32_16x16x32_bf16 v[106:109], v[158:161], v[190:193], v[106:109]
	v_mfma_f32_16x16x32_bf16 v[94:97], v[144:147], v[198:201], v[94:97]
	v_mfma_f32_16x16x32_bf16 v[90:93], v[158:161], v[198:201], v[90:93]
	v_mfma_f32_16x16x32_bf16 v[78:81], v[144:147], v[224:227], v[78:81]
	v_mfma_f32_16x16x32_bf16 v[74:77], v[158:161], v[224:227], v[74:77]
	v_mfma_f32_16x16x32_bf16 v[118:121], v[162:165], v[178:181], v[118:121]
	v_mfma_f32_16x16x32_bf16 v[114:117], v[170:173], v[178:181], v[114:117]
	v_mfma_f32_16x16x32_bf16 v[102:105], v[162:165], v[186:189], v[102:105]
	v_mfma_f32_16x16x32_bf16 v[98:101], v[170:173], v[186:189], v[98:101]
	v_mfma_f32_16x16x32_bf16 v[86:89], v[162:165], v[194:197], v[86:89]
	v_mfma_f32_16x16x32_bf16 v[82:85], v[170:173], v[194:197], v[82:85]
	v_mfma_f32_16x16x32_bf16 v[70:73], v[162:165], v[202:205], v[70:73]
	v_mfma_f32_16x16x32_bf16 v[66:69], v[170:173], v[202:205], v[66:69]
	v_mfma_f32_16x16x32_bf16 v[118:121], v[166:169], v[182:185], v[118:121]
	v_mfma_f32_16x16x32_bf16 v[114:117], v[174:177], v[182:185], v[114:117]
	v_mfma_f32_16x16x32_bf16 v[102:105], v[166:169], v[190:193], v[102:105]
	v_mfma_f32_16x16x32_bf16 v[98:101], v[174:177], v[190:193], v[98:101]
	v_mfma_f32_16x16x32_bf16 v[86:89], v[166:169], v[198:201], v[86:89]
	v_mfma_f32_16x16x32_bf16 v[82:85], v[174:177], v[198:201], v[82:85]
	v_mfma_f32_16x16x32_bf16 v[70:73], v[166:169], v[224:227], v[70:73]
	v_mfma_f32_16x16x32_bf16 v[66:69], v[174:177], v[224:227], v[66:69]
	s_barrier
; #define PG8_STAGE(bufoff, gbase, voff) do { _Pragma("unroll") for (int _i = 0; _i < 2; ++_i) \
;         __builtin_amdgcn_global_load_lds((const unsigned*)((const char*)(gbase) + (voff)[_i]), (PG8_LAS unsigned*)(lds + (bufoff) + ldsw + _i * 8192), 16, 0, 0); } while (0)
; #define PG8_LDA(dst, b, h) do { _Pragma("unroll") for (int m = 0; m < 4; ++m) _Pragma("unroll") for (int k = 0; k < 2; ++k) dst[m][k] = *(const PG8_LAS bf16x8*)(lds + PG8_SA(b, h) + aoff + m * 2048 + k * 1024); } while (0)
; #define PG8_MMA(ai, bj, At, Bt) do { __builtin_amdgcn_s_setprio(1); _Pragma("unroll") for (int m = 0; m < 4; ++m) _Pragma("unroll") for (int n = 0; n < 2; ++n) _Pragma("unroll") for (int k = 0; k < 2; ++k) \
;         acc[ai][bj][m][n] = __builtin_amdgcn_mfma_f32_16x16x32_bf16(Bt[n][k], At[m][k], acc[ai][bj][m][n], 0, 0, 0); __builtin_amdgcn_s_setprio(0); } while (0)
; #define PG8_WAIT_V(n) asm volatile("s_waitcnt vmcnt(" #n ")" ::: "memory")
; #define PG8_WAIT_L(n) asm volatile("s_waitcnt lgkmcnt(" #n ")" ::: "memory")
; #define PG8_BAR __builtin_amdgcn_s_barrier()
; #define PG8_SCHED __builtin_amdgcn_sched_barrier(0)
; template <class Epi, class Sched, bool ALIGN_EPI = false, bool SP2 = false>
; __device__ __forceinline__ void gemm_phase(PG8_LAS unsigned char* lds, const Gemm g, const Sched& S, const Epi& E) {
;     ...
;             PG8_LDA(At, 1, 1); PG8_STAGE(PG8_SB(1, 0), b3, voffB); PG8_STAGE(PG8_SB(1, 1), b3 + hstep, voffB); PG8_STAGE(PG8_SA(1, 0), a3, voffA);
;             PG8_WAIT_V(8); PG8_WAIT_L(0); PG8_BAR; PG8_MMA(1, 0, At, B0); PG8_MMA(1, 1, At, B1); PG8_BAR; PG8_SCHED;
;     __device__ __forceinline__ void operator()(const f32x4 (&acc)[2][2][4][2], const Unit& u, int wr, int wc, int fr, int fq) const {
;     ...
;             for (int m = 0; m < 4; ++m) {
;                 const int row = row0 + ai * 128 + m * 16;
; #pragma unroll
;                 for (int bj = 0; bj < 2; ++bj) {
;                     const int c = col0 + bj * 128;
;                     const u32x4 g = *(const u32x4*)(G + (size_t)row * P2W + c);
	s_setprio 0
	s_add_i32 s20, s46, s26
	v_lshl_add_u64 v[148:149], v[148:149], 0, s[86:87]
	s_mov_b32 m0, s20
	ds_read_b128 v[178:181], v153 offset:49152
	ds_read_b128 v[182:185], v153 offset:50176
	ds_read_b128 v[186:189], v153 offset:51200
	ds_read_b128 v[190:193], v153 offset:52224
	ds_read_b128 v[194:197], v153 offset:53248
	ds_read_b128 v[198:201], v153 offset:54272
	ds_read_b128 v[202:205], v153 offset:55296
	ds_read_b128 v[224:227], v153 offset:56320
	global_load_lds_dwordx4 v[148:149], off
	s_add_i32 m0, s20, 0x2000
	s_add_u32 s18, s18, 0x20080
	v_lshl_add_u64 v[148:149], v[228:229], 0, s[86:87]
	s_addc_u32 s19, s19, 0
	s_add_i32 s20, s47, s26
	global_load_lds_dwordx4 v[148:149], off
	v_lshl_add_u64 v[148:149], s[18:19], 0, v[0:1]
	s_mov_b32 m0, s20
	s_nop 0
	global_load_lds_dwordx4 v[148:149], off
	v_lshl_add_u64 v[148:149], s[18:19], 0, v[134:135]
	s_add_i32 m0, s20, 0x2000
	s_nop 0
	global_load_lds_dwordx4 v[148:149], off
	v_lshl_add_u64 v[148:149], v[230:231], 0, s[86:87]
	s_mov_b32 m0, s31
	s_nop 0
	global_load_lds_dwordx4 v[148:149], off
	v_lshl_add_u64 v[148:149], v[232:233], 0, s[86:87]
	s_mov_b32 m0, s38
	s_nop 0
	global_load_lds_dwordx4 v[148:149], off
	s_waitcnt vmcnt(8)
	s_waitcnt lgkmcnt(0)
	s_setprio 1
	s_barrier
	v_mfma_f32_16x16x32_bf16 v[62:65], v[138:141], v[178:181], v[62:65]
	v_mfma_f32_16x16x32_bf16 v[58:61], v[154:157], v[178:181], v[58:61]
	v_mfma_f32_16x16x32_bf16 v[46:49], v[138:141], v[186:189], v[46:49]
	v_mfma_f32_16x16x32_bf16 v[42:45], v[154:157], v[186:189], v[42:45]
	v_mfma_f32_16x16x32_bf16 v[30:33], v[138:141], v[194:197], v[30:33]
	v_mfma_f32_16x16x32_bf16 v[26:29], v[154:157], v[194:197], v[26:29]
	v_mfma_f32_16x16x32_bf16 v[14:17], v[138:141], v[202:205], v[14:17]
	v_mfma_f32_16x16x32_bf16 v[10:13], v[154:157], v[202:205], v[10:13]
	v_mfma_f32_16x16x32_bf16 v[62:65], v[144:147], v[182:185], v[62:65]
	v_mfma_f32_16x16x32_bf16 v[58:61], v[158:161], v[182:185], v[58:61]
	v_mfma_f32_16x16x32_bf16 v[46:49], v[144:147], v[190:193], v[46:49]
	v_mfma_f32_16x16x32_bf16 v[42:45], v[158:161], v[190:193], v[42:45]
	v_mfma_f32_16x16x32_bf16 v[30:33], v[144:147], v[198:201], v[30:33]
	v_mfma_f32_16x16x32_bf16 v[26:29], v[158:161], v[198:201], v[26:29]
	v_mfma_f32_16x16x32_bf16 v[14:17], v[144:147], v[224:227], v[14:17]
	v_mfma_f32_16x16x32_bf16 v[10:13], v[158:161], v[224:227], v[10:13]
	v_mfma_f32_16x16x32_bf16 v[54:57], v[162:165], v[178:181], v[54:57]
	v_mfma_f32_16x16x32_bf16 v[50:53], v[170:173], v[178:181], v[50:53]
	v_mfma_f32_16x16x32_bf16 v[38:41], v[162:165], v[186:189], v[38:41]
	v_mfma_f32_16x16x32_bf16 v[34:37], v[170:173], v[186:189], v[34:37]
	v_mfma_f32_16x16x32_bf16 v[22:25], v[162:165], v[194:197], v[22:25]
	v_mfma_f32_16x16x32_bf16 v[18:21], v[170:173], v[194:197], v[18:21]
	v_mfma_f32_16x16x32_bf16 v[6:9], v[162:165], v[202:205], v[6:9]
	v_mfma_f32_16x16x32_bf16 v[2:5], v[170:173], v[202:205], v[2:5]
	v_mfma_f32_16x16x32_bf16 v[54:57], v[166:169], v[182:185], v[54:57]
	v_mfma_f32_16x16x32_bf16 v[50:53], v[174:177], v[182:185], v[50:53]
	v_mfma_f32_16x16x32_bf16 v[38:41], v[166:169], v[190:193], v[38:41]
	v_mfma_f32_16x16x32_bf16 v[34:37], v[174:177], v[190:193], v[34:37]
	v_mfma_f32_16x16x32_bf16 v[22:25], v[166:169], v[198:201], v[22:25]
	v_mfma_f32_16x16x32_bf16 v[18:21], v[174:177], v[198:201], v[18:21]
	v_mfma_f32_16x16x32_bf16 v[6:9], v[166:169], v[224:227], v[6:9]
	v_mfma_f32_16x16x32_bf16 v[2:5], v[174:177], v[224:227], v[2:5]
	s_barrier
	s_setprio 0
	s_add_i32 s45, s45, 2
	s_add_u32 s16, s16, 0x100
	s_addc_u32 s17, s17, 0
	s_add_u32 s43, s43, 0x100
	s_addc_u32 s44, s44, 0
	s_cmp_gt_u32 s45, 5
	s_cbranch_scc0 .LBB0_891
	v_lshl_add_u32 v140, s14, 8, v150
	v_lshl_or_b32 v141, s15, 8, v152
	v_mul_lo_u32 v138, v140, s83
	v_lshlrev_b32_e32 v139, 11, v140
	v_lshl_add_u32 v138, v141, 1, v138
	v_lshl_add_u32 v139, v141, 1, v139
	global_load_dwordx4 v[144:147], v138, s[74:75]
	global_load_dwordx4 v[156:159], v138, s[74:75] offset:256
	v_add_u32_e32 v140, 0x1a000, v138
	global_load_dwordx4 v[160:163], v140, s[74:75]
	global_load_dwordx4 v[164:167], v140, s[74:75] offset:256
	v_add_u32_e32 v140, 0x34000, v138
	global_load_dwordx4 v[168:171], v140, s[74:75]
	global_load_dwordx4 v[172:175], v140, s[74:75] offset:256
	v_add_u32_e32 v140, 0x4e000, v138
	global_load_dwordx4 v[176:179], v140, s[74:75]
	global_load_dwordx4 v[180:183], v140, s[74:75] offset:256
	v_add_u32_e32 v140, 0xd0000, v138
	global_load_dwordx4 v[184:187], v140, s[74:75]
	global_load_dwordx4 v[188:191], v140, s[74:75] offset:256
	v_add_u32_e32 v140, 0xea000, v138
	global_load_dwordx4 v[192:195], v140, s[74:75]
	global_load_dwordx4 v[196:199], v140, s[74:75] offset:256
	v_add_u32_e32 v140, 0x104000, v138
	global_load_dwordx4 v[200:203], v140, s[74:75]
	global_load_dwordx4 v[224:227], v140, s[74:75] offset:256
	v_add_u32_e32 v140, 0x11e000, v138
	global_load_dwordx4 v[228:231], v140, s[74:75]
	global_load_dwordx4 v[232:235], v140, s[74:75] offset:256
	s_and_b64 vcc, exec, s[4:5]
	s_cbranch_vccz .LBB0_894
	s_barrier

; #define PG8_STAGE(bufoff, gbase, voff) do { _Pragma("unroll") for (int _i = 0; _i < 2; ++_i) \
;         __builtin_amdgcn_global_load_lds((const unsigned*)((const char*)(gbase) + (voff)[_i]), (PG8_LAS unsigned*)(lds + (bufoff) + ldsw + _i * 8192), 16, 0, 0); } while (0)
; #define PG8_LDA(dst, b, h) do { _Pragma("unroll") for (int m = 0; m < 4; ++m) _Pragma("unroll") for (int k = 0; k < 2; ++k) dst[m][k] = *(const PG8_LAS bf16x8*)(lds + PG8_SA(b, h) + aoff + m * 2048 + k * 1024); } while (0)
; #define PG8_LDB(dst, b, h) do { _Pragma("unroll") for (int n = 0; n < 2; ++n) _Pragma("unroll") for (int k = 0; k < 2; ++k) dst[n][k] = *(const PG8_LAS bf16x8*)(lds + PG8_SB(b, h) + boff + n * 2048 + k * 1024); } while (0)
; #define PG8_MMA(ai, bj, At, Bt) do { __builtin_amdgcn_s_setprio(1); _Pragma("unroll") for (int m = 0; m < 4; ++m) _Pragma("unroll") for (int n = 0; n < 2; ++n) _Pragma("unroll") for (int k = 0; k < 2; ++k) \
;         acc[ai][bj][m][n] = __builtin_amdgcn_mfma_f32_16x16x32_bf16(Bt[n][k], At[m][k], acc[ai][bj][m][n], 0, 0, 0); __builtin_amdgcn_s_setprio(0); } while (0)
; #define PG8_WAIT_V(n) asm volatile("s_waitcnt vmcnt(" #n ")" ::: "memory")
; #define PG8_WAIT_L(n) asm volatile("s_waitcnt lgkmcnt(" #n ")" ::: "memory")
; #define PG8_BAR __builtin_amdgcn_s_barrier()
; #define PG8_SCHED __builtin_amdgcn_sched_barrier(0)
; template <class Epi, class Sched, bool ALIGN_EPI = false, bool SP2 = false>
; __device__ __forceinline__ void gemm_phase(PG8_LAS unsigned char* lds, const Gemm g, const Sched& S, const Epi& E) {
;     ...
;         for (int t = 0; t < nt; t += 2) {
;             const bool last = (t == nt - 2);
;             const char* a1 = cA + (size_t)(t + 1) * kstep;
;             const char* a2 = last ? nA : cA + (size_t)(t + 2) * kstep; const char* b2 = last ? nB : cB + (size_t)(t + 2) * kstep;
;             const char* a3 = a2 + kstep; const char* b3 = b2 + kstep;
;             if (last && has_next) S.a_ready(nxt);
;             if constexpr (SP2) {
;             PG8_LDB(B0, 0, 0); PG8_LDB(B1, 0, 1); PG8_SCHED; PG8_LDA(At, 0, 0); PG8_STAGE(PG8_SA(1, 1), a1 + hstep, voffA);
;             PG8_WAIT_V(8); PG8_WAIT_L(0); PG8_BAR; PG8_MMA(0, 0, At, B0); PG8_MMA(0, 1, At, B1); PG8_BAR; PG8_SCHED;
;             PG8_LDA(At, 0, 1); PG8_STAGE(PG8_SB(0, 0), b2, voffB); PG8_STAGE(PG8_SB(0, 1), b2 + hstep, voffB); PG8_STAGE(PG8_SA(0, 0), a2, voffA);
.LBB0_919:
	s_add_u32 s12, s10, 0x100
	s_addc_u32 s13, s11, 0
	s_add_i32 s44, 0, 0x10000
	s_cmp_eq_u32 s43, 16
	s_cselect_b32 s17, s5, s13
	s_cselect_b32 s16, s4, s12
	v_add_u32_e32 v148, s44, v151
	s_cselect_b32 s15, s9, s42
	s_cselect_b32 s14, s8, s41
	s_add_i32 s45, 0, 0x14000
	ds_read_b128 v[138:141], v148
	ds_read_b128 v[144:147], v148 offset:1024
	ds_read_b128 v[154:157], v148 offset:2048
	ds_read_b128 v[158:161], v148 offset:3072
	v_add_u32_e32 v148, s45, v151
	ds_read_b128 v[162:165], v148
	ds_read_b128 v[166:169], v148 offset:1024
	ds_read_b128 v[170:173], v148 offset:2048
	ds_read_b128 v[174:177], v148 offset:3072
	v_lshl_add_u64 v[148:149], s[10:11], 0, v[136:137]
	s_add_i32 m0, s23, 0xc000
	ds_read_b128 v[178:181], v153
	ds_read_b128 v[182:185], v153 offset:1024
	ds_read_b128 v[186:189], v153 offset:2048
	ds_read_b128 v[190:193], v153 offset:3072
	ds_read_b128 v[194:197], v153 offset:4096
	ds_read_b128 v[198:201], v153 offset:5120
	ds_read_b128 v[202:205], v153 offset:6144
	ds_read_b128 v[224:227], v153 offset:7168
	global_load_lds_dwordx4 v[148:149], off
	v_lshl_add_u64 v[148:149], s[10:11], 0, v[142:143]
	s_add_i32 m0, s23, 0xe000
	s_nop 0
	global_load_lds_dwordx4 v[148:149], off
	s_waitcnt vmcnt(8)
	s_waitcnt lgkmcnt(0)
	s_setprio 1
	s_barrier
	v_mfma_f32_16x16x32_bf16 v[126:129], v[138:141], v[178:181], v[126:129]
	v_mfma_f32_16x16x32_bf16 v[122:125], v[154:157], v[178:181], v[122:125]
	v_mfma_f32_16x16x32_bf16 v[110:113], v[138:141], v[186:189], v[110:113]
	v_mfma_f32_16x16x32_bf16 v[106:109], v[154:157], v[186:189], v[106:109]
	v_mfma_f32_16x16x32_bf16 v[94:97], v[138:141], v[194:197], v[94:97]
	v_mfma_f32_16x16x32_bf16 v[90:93], v[154:157], v[194:197], v[90:93]
	v_mfma_f32_16x16x32_bf16 v[78:81], v[138:141], v[202:205], v[78:81]
	v_mfma_f32_16x16x32_bf16 v[74:77], v[154:157], v[202:205], v[74:77]
	v_mfma_f32_16x16x32_bf16 v[126:129], v[144:147], v[182:185], v[126:129]
	v_mfma_f32_16x16x32_bf16 v[122:125], v[158:161], v[182:185], v[122:125]
	v_mfma_f32_16x16x32_bf16 v[110:113], v[144:147], v[190:193], v[110:113]
	v_mfma_f32_16x16x32_bf16 v[106:109], v[158:161], v[190:193], v[106:109]
	v_mfma_f32_16x16x32_bf16 v[94:97], v[144:147], v[198:201], v[94:97]
	v_mfma_f32_16x16x32_bf16 v[90:93], v[158:161], v[198:201], v[90:93]
	v_mfma_f32_16x16x32_bf16 v[78:81], v[144:147], v[224:227], v[78:81]
	v_mfma_f32_16x16x32_bf16 v[74:77], v[158:161], v[224:227], v[74:77]
	v_mfma_f32_16x16x32_bf16 v[118:121], v[162:165], v[178:181], v[118:121]
	v_mfma_f32_16x16x32_bf16 v[114:117], v[170:173], v[178:181], v[114:117]
	v_mfma_f32_16x16x32_bf16 v[102:105], v[162:165], v[186:189], v[102:105]
	v_mfma_f32_16x16x32_bf16 v[98:101], v[170:173], v[186:189], v[98:101]
	v_mfma_f32_16x16x32_bf16 v[86:89], v[162:165], v[194:197], v[86:89]
	v_mfma_f32_16x16x32_bf16 v[82:85], v[170:173], v[194:197], v[82:85]
	v_mfma_f32_16x16x32_bf16 v[70:73], v[162:165], v[202:205], v[70:73]
	v_mfma_f32_16x16x32_bf16 v[66:69], v[170:173], v[202:205], v[66:69]
	v_mfma_f32_16x16x32_bf16 v[118:121], v[166:169], v[182:185], v[118:121]
	v_mfma_f32_16x16x32_bf16 v[114:117], v[174:177], v[182:185], v[114:117]
	v_mfma_f32_16x16x32_bf16 v[102:105], v[166:169], v[190:193], v[102:105]
	v_mfma_f32_16x16x32_bf16 v[98:101], v[174:177], v[190:193], v[98:101]
	v_mfma_f32_16x16x32_bf16 v[86:89], v[166:169], v[198:201], v[86:89]
	v_mfma_f32_16x16x32_bf16 v[82:85], v[174:177], v[198:201], v[82:85]
	v_mfma_f32_16x16x32_bf16 v[70:73], v[166:169], v[224:227], v[70:73]
	v_mfma_f32_16x16x32_bf16 v[66:69], v[174:177], v[224:227], v[66:69]
	s_barrier
	s_setprio 0
	s_add_i32 s10, s44, s20
	v_lshl_add_u64 v[148:149], s[14:15], 0, v[0:1]
	s_mov_b32 m0, s10
	ds_read_b128 v[178:181], v153 offset:16384
	ds_read_b128 v[182:185], v153 offset:17408
	ds_read_b128 v[186:189], v153 offset:18432
	ds_read_b128 v[190:193], v153 offset:19456
	ds_read_b128 v[194:197], v153 offset:20480
	ds_read_b128 v[198:201], v153 offset:21504
	ds_read_b128 v[202:205], v153 offset:22528
	ds_read_b128 v[224:227], v153 offset:23552
	global_load_lds_dwordx4 v[148:149], off
	s_add_i32 m0, s10, 0x2000
	s_add_u32 s10, s14, 0x50000
	v_lshl_add_u64 v[228:229], s[14:15], 0, v[134:135]
	s_addc_u32 s11, s15, 0
	s_add_i32 s44, s45, s20
	global_load_lds_dwordx4 v[228:229], off
	v_lshl_add_u64 v[230:231], s[10:11], 0, v[0:1]
	s_mov_b32 m0, s44
	v_lshl_add_u64 v[232:233], s[16:17], 0, v[132:133]
	global_load_lds_dwordx4 v[230:231], off
	v_lshl_add_u64 v[230:231], s[10:11], 0, v[134:135]
	s_add_i32 m0, s44, 0x2000
	s_nop 0
	global_load_lds_dwordx4 v[230:231], off
	v_lshl_add_u64 v[230:231], s[16:17], 0, v[130:131]
	s_mov_b32 m0, s23
	s_nop 0
	global_load_lds_dwordx4 v[230:231], off
	s_mov_b32 m0, s24
	s_nop 0
	global_load_lds_dwordx4 v[232:233], off
	s_waitcnt vmcnt(8)
	s_waitcnt lgkmcnt(0)
	s_setprio 1
	s_barrier
; #define PG8_STAGE(bufoff, gbase, voff) do { _Pragma("unroll") for (int _i = 0; _i < 2; ++_i) \
;         __builtin_amdgcn_global_load_lds((const unsigned*)((const char*)(gbase) + (voff)[_i]), (PG8_LAS unsigned*)(lds + (bufoff) + ldsw + _i * 8192), 16, 0, 0); } while (0)
; #define PG8_LDA(dst, b, h) do { _Pragma("unroll") for (int m = 0; m < 4; ++m) _Pragma("unroll") for (int k = 0; k < 2; ++k) dst[m][k] = *(const PG8_LAS bf16x8*)(lds + PG8_SA(b, h) + aoff + m * 2048 + k * 1024); } while (0)
; #define PG8_LDB(dst, b, h) do { _Pragma("unroll") for (int n = 0; n < 2; ++n) _Pragma("unroll") for (int k = 0; k < 2; ++k) dst[n][k] = *(const PG8_LAS bf16x8*)(lds + PG8_SB(b, h) + boff + n * 2048 + k * 1024); } while (0)
; #define PG8_MMA(ai, bj, At, Bt) do { __builtin_amdgcn_s_setprio(1); _Pragma("unroll") for (int m = 0; m < 4; ++m) _Pragma("unroll") for (int n = 0; n < 2; ++n) _Pragma("unroll") for (int k = 0; k < 2; ++k) \
;         acc[ai][bj][m][n] = __builtin_amdgcn_mfma_f32_16x16x32_bf16(Bt[n][k], At[m][k], acc[ai][bj][m][n], 0, 0, 0); __builtin_amdgcn_s_setprio(0); } while (0)
; #define PG8_WAIT_V(n) asm volatile("s_waitcnt vmcnt(" #n ")" ::: "memory")
; #define PG8_WAIT_L(n) asm volatile("s_waitcnt lgkmcnt(" #n ")" ::: "memory")
; #define PG8_BAR __builtin_amdgcn_s_barrier()
; #define PG8_SCHED __builtin_amdgcn_sched_barrier(0)
; template <class Epi, class Sched, bool ALIGN_EPI = false, bool SP2 = false>
; __device__ __forceinline__ void gemm_phase(PG8_LAS unsigned char* lds, const Gemm g, const Sched& S, const Epi& E) {
;     ...
;             PG8_WAIT_V(8); PG8_WAIT_L(0); PG8_BAR; PG8_MMA(1, 0, At, B0); PG8_MMA(1, 1, At, B1); PG8_BAR; PG8_SCHED;
;             PG8_LDB(B0, 1, 0); PG8_LDB(B1, 1, 1); PG8_SCHED; PG8_LDA(At, 1, 0); PG8_STAGE(PG8_SA(0, 1), a2 + hstep, voffA);
;             PG8_WAIT_V(8); PG8_WAIT_L(0); PG8_BAR; PG8_MMA(0, 0, At, B0); PG8_MMA(0, 1, At, B1); PG8_BAR; PG8_SCHED;
	v_mfma_f32_16x16x32_bf16 v[62:65], v[138:141], v[178:181], v[62:65]
	v_mfma_f32_16x16x32_bf16 v[58:61], v[154:157], v[178:181], v[58:61]
	v_mfma_f32_16x16x32_bf16 v[46:49], v[138:141], v[186:189], v[46:49]
	v_mfma_f32_16x16x32_bf16 v[42:45], v[154:157], v[186:189], v[42:45]
	v_mfma_f32_16x16x32_bf16 v[30:33], v[138:141], v[194:197], v[30:33]
	v_mfma_f32_16x16x32_bf16 v[26:29], v[154:157], v[194:197], v[26:29]
	v_mfma_f32_16x16x32_bf16 v[14:17], v[138:141], v[202:205], v[14:17]
	v_mfma_f32_16x16x32_bf16 v[10:13], v[154:157], v[202:205], v[10:13]
	v_mfma_f32_16x16x32_bf16 v[62:65], v[144:147], v[182:185], v[62:65]
	v_mfma_f32_16x16x32_bf16 v[58:61], v[158:161], v[182:185], v[58:61]
	v_mfma_f32_16x16x32_bf16 v[46:49], v[144:147], v[190:193], v[46:49]
	v_mfma_f32_16x16x32_bf16 v[42:45], v[158:161], v[190:193], v[42:45]
	v_mfma_f32_16x16x32_bf16 v[30:33], v[144:147], v[198:201], v[30:33]
	v_mfma_f32_16x16x32_bf16 v[26:29], v[158:161], v[198:201], v[26:29]
	v_mfma_f32_16x16x32_bf16 v[14:17], v[144:147], v[224:227], v[14:17]
	v_mfma_f32_16x16x32_bf16 v[10:13], v[158:161], v[224:227], v[10:13]
	v_mfma_f32_16x16x32_bf16 v[54:57], v[162:165], v[178:181], v[54:57]
	v_mfma_f32_16x16x32_bf16 v[50:53], v[170:173], v[178:181], v[50:53]
	v_mfma_f32_16x16x32_bf16 v[38:41], v[162:165], v[186:189], v[38:41]
	v_mfma_f32_16x16x32_bf16 v[34:37], v[170:173], v[186:189], v[34:37]
	v_mfma_f32_16x16x32_bf16 v[22:25], v[162:165], v[194:197], v[22:25]
	v_mfma_f32_16x16x32_bf16 v[18:21], v[170:173], v[194:197], v[18:21]
	v_mfma_f32_16x16x32_bf16 v[6:9], v[162:165], v[202:205], v[6:9]
	v_mfma_f32_16x16x32_bf16 v[2:5], v[170:173], v[202:205], v[2:5]
	v_mfma_f32_16x16x32_bf16 v[54:57], v[166:169], v[182:185], v[54:57]
	v_mfma_f32_16x16x32_bf16 v[50:53], v[174:177], v[182:185], v[50:53]
	v_mfma_f32_16x16x32_bf16 v[38:41], v[166:169], v[190:193], v[38:41]
	v_mfma_f32_16x16x32_bf16 v[34:37], v[174:177], v[190:193], v[34:37]
	v_mfma_f32_16x16x32_bf16 v[22:25], v[166:169], v[198:201], v[22:25]
	v_mfma_f32_16x16x32_bf16 v[18:21], v[174:177], v[198:201], v[18:21]
	v_mfma_f32_16x16x32_bf16 v[6:9], v[166:169], v[224:227], v[6:9]
	v_mfma_f32_16x16x32_bf16 v[2:5], v[174:177], v[224:227], v[2:5]
	s_barrier
	s_setprio 0
	s_add_i32 s44, 0, 0x18000
	s_add_i32 s45, 0, 0x1c000
	v_add_u32_e32 v158, s44, v151
	v_add_u32_e32 v174, s45, v151
	ds_read_b128 v[138:141], v158
	ds_read_b128 v[144:147], v158 offset:1024
	ds_read_b128 v[154:157], v158 offset:2048
	ds_read_b128 v[158:161], v158 offset:3072
	ds_read_b128 v[162:165], v174
	ds_read_b128 v[166:169], v174 offset:1024
	ds_read_b128 v[170:173], v174 offset:2048
	ds_read_b128 v[174:177], v174 offset:3072
	s_add_u32 s10, s16, 0x50000
	s_addc_u32 s11, s17, 0
	s_mov_b32 m0, s25
	v_lshl_add_u64 v[234:235], s[10:11], 0, v[130:131]
	ds_read_b128 v[178:181], v153 offset:32768
	ds_read_b128 v[182:185], v153 offset:33792
	ds_read_b128 v[186:189], v153 offset:34816
	ds_read_b128 v[190:193], v153 offset:35840
	ds_read_b128 v[194:197], v153 offset:36864
	ds_read_b128 v[198:201], v153 offset:37888
	ds_read_b128 v[202:205], v153 offset:38912
	ds_read_b128 v[224:227], v153 offset:39936
	global_load_lds_dwordx4 v[234:235], off
	v_lshl_add_u64 v[234:235], s[10:11], 0, v[132:133]
	s_mov_b32 m0, s26
	s_nop 0
	global_load_lds_dwordx4 v[234:235], off
	s_waitcnt vmcnt(8)
	s_waitcnt lgkmcnt(0)
	s_setprio 1
	s_barrier
	v_mfma_f32_16x16x32_bf16 v[126:129], v[138:141], v[178:181], v[126:129]
	v_mfma_f32_16x16x32_bf16 v[122:125], v[154:157], v[178:181], v[122:125]
	v_mfma_f32_16x16x32_bf16 v[110:113], v[138:141], v[186:189], v[110:113]
	v_mfma_f32_16x16x32_bf16 v[106:109], v[154:157], v[186:189], v[106:109]
	v_mfma_f32_16x16x32_bf16 v[94:97], v[138:141], v[194:197], v[94:97]
	v_mfma_f32_16x16x32_bf16 v[90:93], v[154:157], v[194:197], v[90:93]
	v_mfma_f32_16x16x32_bf16 v[78:81], v[138:141], v[202:205], v[78:81]
	v_mfma_f32_16x16x32_bf16 v[74:77], v[154:157], v[202:205], v[74:77]
	v_mfma_f32_16x16x32_bf16 v[126:129], v[144:147], v[182:185], v[126:129]
	v_mfma_f32_16x16x32_bf16 v[122:125], v[158:161], v[182:185], v[122:125]
	v_mfma_f32_16x16x32_bf16 v[110:113], v[144:147], v[190:193], v[110:113]
	v_mfma_f32_16x16x32_bf16 v[106:109], v[158:161], v[190:193], v[106:109]
	v_mfma_f32_16x16x32_bf16 v[94:97], v[144:147], v[198:201], v[94:97]
	v_mfma_f32_16x16x32_bf16 v[90:93], v[158:161], v[198:201], v[90:93]
	v_mfma_f32_16x16x32_bf16 v[78:81], v[144:147], v[224:227], v[78:81]
	v_mfma_f32_16x16x32_bf16 v[74:77], v[158:161], v[224:227], v[74:77]
	v_mfma_f32_16x16x32_bf16 v[118:121], v[162:165], v[178:181], v[118:121]
	v_mfma_f32_16x16x32_bf16 v[114:117], v[170:173], v[178:181], v[114:117]
	v_mfma_f32_16x16x32_bf16 v[102:105], v[162:165], v[186:189], v[102:105]
	v_mfma_f32_16x16x32_bf16 v[98:101], v[170:173], v[186:189], v[98:101]
	v_mfma_f32_16x16x32_bf16 v[86:89], v[162:165], v[194:197], v[86:89]
	v_mfma_f32_16x16x32_bf16 v[82:85], v[170:173], v[194:197], v[82:85]
	v_mfma_f32_16x16x32_bf16 v[70:73], v[162:165], v[202:205], v[70:73]
	v_mfma_f32_16x16x32_bf16 v[66:69], v[170:173], v[202:205], v[66:69]
	v_mfma_f32_16x16x32_bf16 v[118:121], v[166:169], v[182:185], v[118:121]
	v_mfma_f32_16x16x32_bf16 v[114:117], v[174:177], v[182:185], v[114:117]
	v_mfma_f32_16x16x32_bf16 v[102:105], v[166:169], v[190:193], v[102:105]
	v_mfma_f32_16x16x32_bf16 v[98:101], v[174:177], v[190:193], v[98:101]
	v_mfma_f32_16x16x32_bf16 v[86:89], v[166:169], v[198:201], v[86:89]
	v_mfma_f32_16x16x32_bf16 v[82:85], v[174:177], v[198:201], v[82:85]
	v_mfma_f32_16x16x32_bf16 v[70:73], v[166:169], v[224:227], v[70:73]
	v_mfma_f32_16x16x32_bf16 v[66:69], v[174:177], v[224:227], v[66:69]
	s_barrier
; #define PG8_STAGE(bufoff, gbase, voff) do { _Pragma("unroll") for (int _i = 0; _i < 2; ++_i) \
;         __builtin_amdgcn_global_load_lds((const unsigned*)((const char*)(gbase) + (voff)[_i]), (PG8_LAS unsigned*)(lds + (bufoff) + ldsw + _i * 8192), 16, 0, 0); } while (0)
; #define PG8_LDA(dst, b, h) do { _Pragma("unroll") for (int m = 0; m < 4; ++m) _Pragma("unroll") for (int k = 0; k < 2; ++k) dst[m][k] = *(const PG8_LAS bf16x8*)(lds + PG8_SA(b, h) + aoff + m * 2048 + k * 1024); } while (0)
; #define PG8_MMA(ai, bj, At, Bt) do { __builtin_amdgcn_s_setprio(1); _Pragma("unroll") for (int m = 0; m < 4; ++m) _Pragma("unroll") for (int n = 0; n < 2; ++n) _Pragma("unroll") for (int k = 0; k < 2; ++k) \
;         acc[ai][bj][m][n] = __builtin_amdgcn_mfma_f32_16x16x32_bf16(Bt[n][k], At[m][k], acc[ai][bj][m][n], 0, 0, 0); __builtin_amdgcn_s_setprio(0); } while (0)
; #define PG8_WAIT_V(n) asm volatile("s_waitcnt vmcnt(" #n ")" ::: "memory")
; #define PG8_WAIT_L(n) asm volatile("s_waitcnt lgkmcnt(" #n ")" ::: "memory")
; #define PG8_BAR __builtin_amdgcn_s_barrier()
; #define PG8_SCHED __builtin_amdgcn_sched_barrier(0)
; template <class Epi, class Sched, bool ALIGN_EPI = false, bool SP2 = false>
; __device__ __forceinline__ void gemm_phase(PG8_LAS unsigned char* lds, const Gemm g, const Sched& S, const Epi& E) {
;     ...
;             PG8_LDA(At, 1, 1); PG8_STAGE(PG8_SB(1, 0), b3, voffB); PG8_STAGE(PG8_SB(1, 1), b3 + hstep, voffB); PG8_STAGE(PG8_SA(1, 0), a3, voffA);
;             PG8_WAIT_V(8); PG8_WAIT_L(0); PG8_BAR; PG8_MMA(1, 0, At, B0); PG8_MMA(1, 1, At, B1); PG8_BAR; PG8_SCHED;
;     __device__ __forceinline__ void operator()(const f32x4 (&acc)[2][2][4][2], const Unit& u, int wr, int wc, int fr, int fq) const {
;     ...
;                 const int row = row0 + ai * 128 + m * 16;
; #pragma unroll
;                 for (int bj = 0; bj < 2; ++bj) {
;                     const int c = col0 + bj * 128;
;                     const u32x4 g = *(const u32x4*)(G + (size_t)row * P2W + c);
;                     const u32x4 t = *(const u32x4*)(T + (size_t)row * D + c);
	s_setprio 0
	s_add_i32 s10, s44, s20
	v_lshl_add_u64 v[148:149], v[148:149], 0, s[86:87]
	s_mov_b32 m0, s10
	ds_read_b128 v[178:181], v153 offset:49152
	ds_read_b128 v[182:185], v153 offset:50176
	ds_read_b128 v[186:189], v153 offset:51200
	ds_read_b128 v[190:193], v153 offset:52224
	ds_read_b128 v[194:197], v153 offset:53248
	ds_read_b128 v[198:201], v153 offset:54272
	ds_read_b128 v[202:205], v153 offset:55296
	ds_read_b128 v[224:227], v153 offset:56320
	global_load_lds_dwordx4 v[148:149], off
	s_add_i32 m0, s10, 0x2000
	s_add_u32 s10, s14, 0x50080
	v_lshl_add_u64 v[148:149], v[228:229], 0, s[86:87]
	s_addc_u32 s11, s15, 0
	s_add_i32 s14, s45, s20
	global_load_lds_dwordx4 v[148:149], off
	v_lshl_add_u64 v[148:149], s[10:11], 0, v[0:1]
	s_mov_b32 m0, s14
	s_nop 0
	global_load_lds_dwordx4 v[148:149], off
	v_lshl_add_u64 v[148:149], s[10:11], 0, v[134:135]
	s_add_i32 m0, s14, 0x2000
	s_nop 0
	global_load_lds_dwordx4 v[148:149], off
	v_lshl_add_u64 v[148:149], v[230:231], 0, s[86:87]
	s_mov_b32 m0, s27
	s_nop 0
	global_load_lds_dwordx4 v[148:149], off
	v_lshl_add_u64 v[148:149], v[232:233], 0, s[86:87]
	s_mov_b32 m0, s28
	s_nop 0
	global_load_lds_dwordx4 v[148:149], off
	s_waitcnt vmcnt(8)
	s_waitcnt lgkmcnt(0)
	s_setprio 1
	s_barrier
	v_mfma_f32_16x16x32_bf16 v[62:65], v[138:141], v[178:181], v[62:65]
	v_mfma_f32_16x16x32_bf16 v[58:61], v[154:157], v[178:181], v[58:61]
	v_mfma_f32_16x16x32_bf16 v[46:49], v[138:141], v[186:189], v[46:49]
	v_mfma_f32_16x16x32_bf16 v[42:45], v[154:157], v[186:189], v[42:45]
	v_mfma_f32_16x16x32_bf16 v[30:33], v[138:141], v[194:197], v[30:33]
	v_mfma_f32_16x16x32_bf16 v[26:29], v[154:157], v[194:197], v[26:29]
	v_mfma_f32_16x16x32_bf16 v[14:17], v[138:141], v[202:205], v[14:17]
	v_mfma_f32_16x16x32_bf16 v[10:13], v[154:157], v[202:205], v[10:13]
	v_mfma_f32_16x16x32_bf16 v[62:65], v[144:147], v[182:185], v[62:65]
	v_mfma_f32_16x16x32_bf16 v[58:61], v[158:161], v[182:185], v[58:61]
	v_mfma_f32_16x16x32_bf16 v[46:49], v[144:147], v[190:193], v[46:49]
	v_mfma_f32_16x16x32_bf16 v[42:45], v[158:161], v[190:193], v[42:45]
	v_mfma_f32_16x16x32_bf16 v[30:33], v[144:147], v[198:201], v[30:33]
	v_mfma_f32_16x16x32_bf16 v[26:29], v[158:161], v[198:201], v[26:29]
	v_mfma_f32_16x16x32_bf16 v[14:17], v[144:147], v[224:227], v[14:17]
	v_mfma_f32_16x16x32_bf16 v[10:13], v[158:161], v[224:227], v[10:13]
	v_mfma_f32_16x16x32_bf16 v[54:57], v[162:165], v[178:181], v[54:57]
	v_mfma_f32_16x16x32_bf16 v[50:53], v[170:173], v[178:181], v[50:53]
	v_mfma_f32_16x16x32_bf16 v[38:41], v[162:165], v[186:189], v[38:41]
	v_mfma_f32_16x16x32_bf16 v[34:37], v[170:173], v[186:189], v[34:37]
	v_mfma_f32_16x16x32_bf16 v[22:25], v[162:165], v[194:197], v[22:25]
	v_mfma_f32_16x16x32_bf16 v[18:21], v[170:173], v[194:197], v[18:21]
	v_mfma_f32_16x16x32_bf16 v[6:9], v[162:165], v[202:205], v[6:9]
	v_mfma_f32_16x16x32_bf16 v[2:5], v[170:173], v[202:205], v[2:5]
	v_mfma_f32_16x16x32_bf16 v[54:57], v[166:169], v[182:185], v[54:57]
	v_mfma_f32_16x16x32_bf16 v[50:53], v[174:177], v[182:185], v[50:53]
	v_mfma_f32_16x16x32_bf16 v[38:41], v[166:169], v[190:193], v[38:41]
	v_mfma_f32_16x16x32_bf16 v[34:37], v[174:177], v[190:193], v[34:37]
	v_mfma_f32_16x16x32_bf16 v[22:25], v[166:169], v[198:201], v[22:25]
	v_mfma_f32_16x16x32_bf16 v[18:21], v[174:177], v[198:201], v[18:21]
	v_mfma_f32_16x16x32_bf16 v[6:9], v[166:169], v[224:227], v[6:9]
	v_mfma_f32_16x16x32_bf16 v[2:5], v[174:177], v[224:227], v[2:5]
	s_barrier
	s_setprio 0
	s_add_i32 s43, s43, 2
	s_add_u32 s41, s41, 0x100
	s_addc_u32 s42, s42, 0
	s_cmp_gt_u32 s43, 17
	s_mov_b64 s[10:11], s[12:13]
	s_cbranch_scc0 .LBB0_919
	v_lshl_add_u32 v140, s38, 8, v150
	v_lshl_or_b32 v141, s39, 8, v152
	v_mul_lo_u32 v138, v140, s83
	v_lshlrev_b32_e32 v139, 11, v140
	v_lshl_add_u32 v138, v141, 1, v138
	v_lshl_add_u32 v139, v141, 1, v139
	global_load_dwordx4 v[144:147], v138, s[72:73]
	global_load_dwordx4 v[156:159], v139, s[36:37]
	global_load_dwordx4 v[160:163], v138, s[72:73] offset:256
	global_load_dwordx4 v[164:167], v139, s[36:37] offset:256
	v_add_u32_e32 v140, 0x1a000, v138
	v_add_u32_e32 v141, 0x8000, v139
	global_load_dwordx4 v[168:171], v140, s[72:73]
	global_load_dwordx4 v[172:175], v141, s[36:37]
	global_load_dwordx4 v[176:179], v140, s[72:73] offset:256
	global_load_dwordx4 v[180:183], v141, s[36:37] offset:256
	v_add_u32_e32 v140, 0x34000, v138
	v_add_u32_e32 v141, 0x10000, v139
	global_load_dwordx4 v[184:187], v140, s[72:73]
	global_load_dwordx4 v[188:191], v141, s[36:37]
	global_load_dwordx4 v[192:195], v140, s[72:73] offset:256
	global_load_dwordx4 v[196:199], v141, s[36:37] offset:256
	v_add_u32_e32 v140, 0x4e000, v138
	v_add_u32_e32 v141, 0x18000, v139
	global_load_dwordx4 v[200:203], v140, s[72:73]
	global_load_dwordx4 v[224:227], v141, s[36:37]
	global_load_dwordx4 v[228:231], v140, s[72:73] offset:256
	global_load_dwordx4 v[232:235], v141, s[36:37] offset:256
	s_and_b64 vcc, exec, s[6:7]
	s_cbranch_vccz .LBB0_922
	s_barrier

; #define PG8_STAGE(bufoff, gbase, voff) do { _Pragma("unroll") for (int _i = 0; _i < 2; ++_i) \
;         __builtin_amdgcn_global_load_lds((const unsigned*)((const char*)(gbase) + (voff)[_i]), (PG8_LAS unsigned*)(lds + (bufoff) + ldsw + _i * 8192), 16, 0, 0); } while (0)
; #define PG8_LDA(dst, b, h) do { _Pragma("unroll") for (int m = 0; m < 4; ++m) _Pragma("unroll") for (int k = 0; k < 2; ++k) dst[m][k] = *(const PG8_LAS bf16x8*)(lds + PG8_SA(b, h) + aoff + m * 2048 + k * 1024); } while (0)
; #define PG8_LDB(dst, b, h) do { _Pragma("unroll") for (int n = 0; n < 2; ++n) _Pragma("unroll") for (int k = 0; k < 2; ++k) dst[n][k] = *(const PG8_LAS bf16x8*)(lds + PG8_SB(b, h) + boff + n * 2048 + k * 1024); } while (0)
; #define PG8_MMA(ai, bj, At, Bt) do { __builtin_amdgcn_s_setprio(1); _Pragma("unroll") for (int m = 0; m < 4; ++m) _Pragma("unroll") for (int n = 0; n < 2; ++n) _Pragma("unroll") for (int k = 0; k < 2; ++k) \
;         acc[ai][bj][m][n] = __builtin_amdgcn_mfma_f32_16x16x32_bf16(Bt[n][k], At[m][k], acc[ai][bj][m][n], 0, 0, 0); __builtin_amdgcn_s_setprio(0); } while (0)
; #define PG8_WAIT_V(n) asm volatile("s_waitcnt vmcnt(" #n ")" ::: "memory")
; #define PG8_WAIT_L(n) asm volatile("s_waitcnt lgkmcnt(" #n ")" ::: "memory")
; #define PG8_BAR __builtin_amdgcn_s_barrier()
; #define PG8_SCHED __builtin_amdgcn_sched_barrier(0)
; template <class Epi, class Sched, bool ALIGN_EPI = false, bool SP2 = false>
; __device__ __forceinline__ void gemm_phase(PG8_LAS unsigned char* lds, const Gemm g, const Sched& S, const Epi& E) {
;     ...
;         for (int t = 0; t < nt; t += 2) {
;             const bool last = (t == nt - 2);
;             const char* a1 = cA + (size_t)(t + 1) * kstep;
;             const char* a2 = last ? nA : cA + (size_t)(t + 2) * kstep; const char* b2 = last ? nB : cB + (size_t)(t + 2) * kstep;
;             const char* a3 = a2 + kstep; const char* b3 = b2 + kstep;
;             if (last && has_next) S.a_ready(nxt);
;             if constexpr (SP2) {
;             PG8_LDB(B0, 0, 0); PG8_LDB(B1, 0, 1); PG8_SCHED; PG8_LDA(At, 0, 0); PG8_STAGE(PG8_SA(1, 1), a1 + hstep, voffA);
;             PG8_WAIT_V(8); PG8_WAIT_L(0); PG8_BAR; PG8_MMA(0, 0, At, B0); PG8_MMA(0, 1, At, B1); PG8_BAR; PG8_SCHED;
;             PG8_LDA(At, 0, 1); PG8_STAGE(PG8_SB(0, 0), b2, voffB); PG8_STAGE(PG8_SB(0, 1), b2 + hstep, voffB); PG8_STAGE(PG8_SA(0, 0), a2, voffA);
.LBB0_1050:
	s_add_u32 s24, s22, 0xfffc0080
	s_addc_u32 s25, s23, -1
	s_add_i32 s51, 0, 0x10000
	s_cmp_eq_u32 s50, 12
	s_cselect_b32 s27, s13, s25
	s_cselect_b32 s26, s19, s24
	s_cselect_b32 s25, s11, s49
	s_cselect_b32 s24, s21, s48
	s_add_i32 s55, 0, 0x14000
	v_add_u32_e32 v156, s51, v149
	v_add_u32_e32 v172, s55, v149
	ds_read_b128 v[138:141], v156
	ds_read_b128 v[144:147], v156 offset:1024
	ds_read_b128 v[152:155], v156 offset:2048
	ds_read_b128 v[156:159], v156 offset:3072
	ds_read_b128 v[160:163], v172
	ds_read_b128 v[164:167], v172 offset:1024
	ds_read_b128 v[168:171], v172 offset:2048
	ds_read_b128 v[172:175], v172 offset:3072
	v_lshl_add_u64 v[204:205], s[22:23], 0, v[136:137]
	s_add_i32 m0, s38, 0xc000
	ds_read_b128 v[176:179], v151
	ds_read_b128 v[180:183], v151 offset:1024
	ds_read_b128 v[184:187], v151 offset:2048
	ds_read_b128 v[188:191], v151 offset:3072
	ds_read_b128 v[192:195], v151 offset:4096
	ds_read_b128 v[196:199], v151 offset:5120
	ds_read_b128 v[200:203], v151 offset:6144
	ds_read_b128 v[224:227], v151 offset:7168
	global_load_lds_dwordx4 v[204:205], off
	v_lshl_add_u64 v[204:205], s[22:23], 0, v[142:143]
	s_add_i32 m0, s38, 0xe000
	s_nop 0
	global_load_lds_dwordx4 v[204:205], off
	s_waitcnt vmcnt(8)
	s_waitcnt lgkmcnt(0)
	s_setprio 1
	s_barrier
	v_mfma_f32_16x16x32_bf16 v[126:129], v[138:141], v[176:179], v[126:129]
	v_mfma_f32_16x16x32_bf16 v[122:125], v[152:155], v[176:179], v[122:125]
	v_mfma_f32_16x16x32_bf16 v[110:113], v[138:141], v[184:187], v[110:113]
	v_mfma_f32_16x16x32_bf16 v[106:109], v[152:155], v[184:187], v[106:109]
	v_mfma_f32_16x16x32_bf16 v[94:97], v[138:141], v[192:195], v[94:97]
	v_mfma_f32_16x16x32_bf16 v[90:93], v[152:155], v[192:195], v[90:93]
	v_mfma_f32_16x16x32_bf16 v[78:81], v[138:141], v[200:203], v[78:81]
	v_mfma_f32_16x16x32_bf16 v[74:77], v[152:155], v[200:203], v[74:77]
	v_mfma_f32_16x16x32_bf16 v[126:129], v[144:147], v[180:183], v[126:129]
	v_mfma_f32_16x16x32_bf16 v[122:125], v[156:159], v[180:183], v[122:125]
	v_mfma_f32_16x16x32_bf16 v[110:113], v[144:147], v[188:191], v[110:113]
	v_mfma_f32_16x16x32_bf16 v[106:109], v[156:159], v[188:191], v[106:109]
	v_mfma_f32_16x16x32_bf16 v[94:97], v[144:147], v[196:199], v[94:97]
	v_mfma_f32_16x16x32_bf16 v[90:93], v[156:159], v[196:199], v[90:93]
	v_mfma_f32_16x16x32_bf16 v[78:81], v[144:147], v[224:227], v[78:81]
	v_mfma_f32_16x16x32_bf16 v[74:77], v[156:159], v[224:227], v[74:77]
	v_mfma_f32_16x16x32_bf16 v[118:121], v[160:163], v[176:179], v[118:121]
	v_mfma_f32_16x16x32_bf16 v[114:117], v[168:171], v[176:179], v[114:117]
	v_mfma_f32_16x16x32_bf16 v[102:105], v[160:163], v[184:187], v[102:105]
	v_mfma_f32_16x16x32_bf16 v[98:101], v[168:171], v[184:187], v[98:101]
	v_mfma_f32_16x16x32_bf16 v[86:89], v[160:163], v[192:195], v[86:89]
	v_mfma_f32_16x16x32_bf16 v[82:85], v[168:171], v[192:195], v[82:85]
	v_mfma_f32_16x16x32_bf16 v[70:73], v[160:163], v[200:203], v[70:73]
	v_mfma_f32_16x16x32_bf16 v[66:69], v[168:171], v[200:203], v[66:69]
	v_mfma_f32_16x16x32_bf16 v[118:121], v[164:167], v[180:183], v[118:121]
	v_mfma_f32_16x16x32_bf16 v[114:117], v[172:175], v[180:183], v[114:117]
	v_mfma_f32_16x16x32_bf16 v[102:105], v[164:167], v[188:191], v[102:105]
	v_mfma_f32_16x16x32_bf16 v[98:101], v[172:175], v[188:191], v[98:101]
	v_mfma_f32_16x16x32_bf16 v[86:89], v[164:167], v[196:199], v[86:89]
	v_mfma_f32_16x16x32_bf16 v[82:85], v[172:175], v[196:199], v[82:85]
	v_mfma_f32_16x16x32_bf16 v[70:73], v[164:167], v[224:227], v[70:73]
	v_mfma_f32_16x16x32_bf16 v[66:69], v[172:175], v[224:227], v[66:69]
	s_barrier
	s_setprio 0
	s_add_i32 s51, s51, s31
	v_lshl_add_u64 v[204:205], s[24:25], 0, v[0:1]
	s_mov_b32 m0, s51
	ds_read_b128 v[176:179], v151 offset:16384
	ds_read_b128 v[180:183], v151 offset:17408
	ds_read_b128 v[184:187], v151 offset:18432
	ds_read_b128 v[188:191], v151 offset:19456
	ds_read_b128 v[192:195], v151 offset:20480
	ds_read_b128 v[196:199], v151 offset:21504
	ds_read_b128 v[200:203], v151 offset:22528
	ds_read_b128 v[224:227], v151 offset:23552
	global_load_lds_dwordx4 v[204:205], off
	s_add_i32 m0, s51, 0x2000
	s_add_u32 s52, s24, 0x40000
	v_lshl_add_u64 v[228:229], s[24:25], 0, v[134:135]
	s_addc_u32 s53, s25, 0
	s_add_i32 s51, s55, s31
	global_load_lds_dwordx4 v[228:229], off
	v_lshl_add_u64 v[230:231], s[52:53], 0, v[0:1]
	s_mov_b32 m0, s51
	v_lshl_add_u64 v[232:233], s[26:27], 0, v[132:133]
	global_load_lds_dwordx4 v[230:231], off
	v_lshl_add_u64 v[230:231], s[52:53], 0, v[134:135]
	s_add_i32 m0, s51, 0x2000
	s_nop 0
	global_load_lds_dwordx4 v[230:231], off
	v_lshl_add_u64 v[230:231], s[26:27], 0, v[130:131]
	s_mov_b32 m0, s38
	s_nop 0
	global_load_lds_dwordx4 v[230:231], off
	s_mov_b32 m0, s39
	s_nop 0
	global_load_lds_dwordx4 v[232:233], off
	s_waitcnt vmcnt(8)
	s_waitcnt lgkmcnt(0)
	s_setprio 1
	s_barrier
; #define PG8_STAGE(bufoff, gbase, voff) do { _Pragma("unroll") for (int _i = 0; _i < 2; ++_i) \
;         __builtin_amdgcn_global_load_lds((const unsigned*)((const char*)(gbase) + (voff)[_i]), (PG8_LAS unsigned*)(lds + (bufoff) + ldsw + _i * 8192), 16, 0, 0); } while (0)
; #define PG8_LDA(dst, b, h) do { _Pragma("unroll") for (int m = 0; m < 4; ++m) _Pragma("unroll") for (int k = 0; k < 2; ++k) dst[m][k] = *(const PG8_LAS bf16x8*)(lds + PG8_SA(b, h) + aoff + m * 2048 + k * 1024); } while (0)
; #define PG8_LDB(dst, b, h) do { _Pragma("unroll") for (int n = 0; n < 2; ++n) _Pragma("unroll") for (int k = 0; k < 2; ++k) dst[n][k] = *(const PG8_LAS bf16x8*)(lds + PG8_SB(b, h) + boff + n * 2048 + k * 1024); } while (0)
; #define PG8_MMA(ai, bj, At, Bt) do { __builtin_amdgcn_s_setprio(1); _Pragma("unroll") for (int m = 0; m < 4; ++m) _Pragma("unroll") for (int n = 0; n < 2; ++n) _Pragma("unroll") for (int k = 0; k < 2; ++k) \
;         acc[ai][bj][m][n] = __builtin_amdgcn_mfma_f32_16x16x32_bf16(Bt[n][k], At[m][k], acc[ai][bj][m][n], 0, 0, 0); __builtin_amdgcn_s_setprio(0); } while (0)
; #define PG8_WAIT_V(n) asm volatile("s_waitcnt vmcnt(" #n ")" ::: "memory")
; #define PG8_WAIT_L(n) asm volatile("s_waitcnt lgkmcnt(" #n ")" ::: "memory")
; #define PG8_BAR __builtin_amdgcn_s_barrier()
; #define PG8_SCHED __builtin_amdgcn_sched_barrier(0)
; template <class Epi, class Sched, bool ALIGN_EPI = false, bool SP2 = false>
; __device__ __forceinline__ void gemm_phase(PG8_LAS unsigned char* lds, const Gemm g, const Sched& S, const Epi& E) {
;     ...
;             PG8_WAIT_V(8); PG8_WAIT_L(0); PG8_BAR; PG8_MMA(1, 0, At, B0); PG8_MMA(1, 1, At, B1); PG8_BAR; PG8_SCHED;
;             PG8_LDB(B0, 1, 0); PG8_LDB(B1, 1, 1); PG8_SCHED; PG8_LDA(At, 1, 0); PG8_STAGE(PG8_SA(0, 1), a2 + hstep, voffA);
;             PG8_WAIT_V(8); PG8_WAIT_L(0); PG8_BAR; PG8_MMA(0, 0, At, B0); PG8_MMA(0, 1, At, B1); PG8_BAR; PG8_SCHED;
	v_mfma_f32_16x16x32_bf16 v[62:65], v[138:141], v[176:179], v[62:65]
	v_mfma_f32_16x16x32_bf16 v[58:61], v[152:155], v[176:179], v[58:61]
	v_mfma_f32_16x16x32_bf16 v[46:49], v[138:141], v[184:187], v[46:49]
	v_mfma_f32_16x16x32_bf16 v[42:45], v[152:155], v[184:187], v[42:45]
	v_mfma_f32_16x16x32_bf16 v[30:33], v[138:141], v[192:195], v[30:33]
	v_mfma_f32_16x16x32_bf16 v[26:29], v[152:155], v[192:195], v[26:29]
	v_mfma_f32_16x16x32_bf16 v[14:17], v[138:141], v[200:203], v[14:17]
	v_mfma_f32_16x16x32_bf16 v[10:13], v[152:155], v[200:203], v[10:13]
	v_mfma_f32_16x16x32_bf16 v[62:65], v[144:147], v[180:183], v[62:65]
	v_mfma_f32_16x16x32_bf16 v[58:61], v[156:159], v[180:183], v[58:61]
	v_mfma_f32_16x16x32_bf16 v[46:49], v[144:147], v[188:191], v[46:49]
	v_mfma_f32_16x16x32_bf16 v[42:45], v[156:159], v[188:191], v[42:45]
	v_mfma_f32_16x16x32_bf16 v[30:33], v[144:147], v[196:199], v[30:33]
	v_mfma_f32_16x16x32_bf16 v[26:29], v[156:159], v[196:199], v[26:29]
	v_mfma_f32_16x16x32_bf16 v[14:17], v[144:147], v[224:227], v[14:17]
	v_mfma_f32_16x16x32_bf16 v[10:13], v[156:159], v[224:227], v[10:13]
	v_mfma_f32_16x16x32_bf16 v[54:57], v[160:163], v[176:179], v[54:57]
	v_mfma_f32_16x16x32_bf16 v[50:53], v[168:171], v[176:179], v[50:53]
	v_mfma_f32_16x16x32_bf16 v[38:41], v[160:163], v[184:187], v[38:41]
	v_mfma_f32_16x16x32_bf16 v[34:37], v[168:171], v[184:187], v[34:37]
	v_mfma_f32_16x16x32_bf16 v[22:25], v[160:163], v[192:195], v[22:25]
	v_mfma_f32_16x16x32_bf16 v[18:21], v[168:171], v[192:195], v[18:21]
	v_mfma_f32_16x16x32_bf16 v[6:9], v[160:163], v[200:203], v[6:9]
	v_mfma_f32_16x16x32_bf16 v[2:5], v[168:171], v[200:203], v[2:5]
	v_mfma_f32_16x16x32_bf16 v[54:57], v[164:167], v[180:183], v[54:57]
	v_mfma_f32_16x16x32_bf16 v[50:53], v[172:175], v[180:183], v[50:53]
	v_mfma_f32_16x16x32_bf16 v[38:41], v[164:167], v[188:191], v[38:41]
	v_mfma_f32_16x16x32_bf16 v[34:37], v[172:175], v[188:191], v[34:37]
	v_mfma_f32_16x16x32_bf16 v[22:25], v[164:167], v[196:199], v[22:25]
	v_mfma_f32_16x16x32_bf16 v[18:21], v[172:175], v[196:199], v[18:21]
	v_mfma_f32_16x16x32_bf16 v[6:9], v[164:167], v[224:227], v[6:9]
	v_mfma_f32_16x16x32_bf16 v[2:5], v[172:175], v[224:227], v[2:5]
	s_barrier
	s_setprio 0
	s_add_i32 s51, 0, 0x18000
	s_add_i32 s52, 0, 0x1c000
	v_add_u32_e32 v156, s51, v149
	v_add_u32_e32 v172, s52, v149
	ds_read_b128 v[138:141], v156
	ds_read_b128 v[144:147], v156 offset:1024
	ds_read_b128 v[152:155], v156 offset:2048
	ds_read_b128 v[156:159], v156 offset:3072
	ds_read_b128 v[160:163], v172
	ds_read_b128 v[164:167], v172 offset:1024
	ds_read_b128 v[168:171], v172 offset:2048
	ds_read_b128 v[172:175], v172 offset:3072
	s_add_u32 s26, s26, 0x40000
	s_addc_u32 s27, s27, 0
	s_mov_b32 m0, s41
	v_lshl_add_u64 v[234:235], s[26:27], 0, v[130:131]
	ds_read_b128 v[176:179], v151 offset:32768
	ds_read_b128 v[180:183], v151 offset:33792
	ds_read_b128 v[184:187], v151 offset:34816
	ds_read_b128 v[188:191], v151 offset:35840
	ds_read_b128 v[192:195], v151 offset:36864
	ds_read_b128 v[196:199], v151 offset:37888
	ds_read_b128 v[200:203], v151 offset:38912
	ds_read_b128 v[224:227], v151 offset:39936
	global_load_lds_dwordx4 v[234:235], off
	v_lshl_add_u64 v[234:235], s[26:27], 0, v[132:133]
	s_mov_b32 m0, s42
	s_nop 0
	global_load_lds_dwordx4 v[234:235], off
	s_waitcnt vmcnt(8)
	s_waitcnt lgkmcnt(0)
	s_setprio 1
	s_barrier
	v_mfma_f32_16x16x32_bf16 v[126:129], v[138:141], v[176:179], v[126:129]
	v_mfma_f32_16x16x32_bf16 v[122:125], v[152:155], v[176:179], v[122:125]
	v_mfma_f32_16x16x32_bf16 v[110:113], v[138:141], v[184:187], v[110:113]
	v_mfma_f32_16x16x32_bf16 v[106:109], v[152:155], v[184:187], v[106:109]
	v_mfma_f32_16x16x32_bf16 v[94:97], v[138:141], v[192:195], v[94:97]
	v_mfma_f32_16x16x32_bf16 v[90:93], v[152:155], v[192:195], v[90:93]
	v_mfma_f32_16x16x32_bf16 v[78:81], v[138:141], v[200:203], v[78:81]
	v_mfma_f32_16x16x32_bf16 v[74:77], v[152:155], v[200:203], v[74:77]
	v_mfma_f32_16x16x32_bf16 v[126:129], v[144:147], v[180:183], v[126:129]
	v_mfma_f32_16x16x32_bf16 v[122:125], v[156:159], v[180:183], v[122:125]
	v_mfma_f32_16x16x32_bf16 v[110:113], v[144:147], v[188:191], v[110:113]
	v_mfma_f32_16x16x32_bf16 v[106:109], v[156:159], v[188:191], v[106:109]
	v_mfma_f32_16x16x32_bf16 v[94:97], v[144:147], v[196:199], v[94:97]
	v_mfma_f32_16x16x32_bf16 v[90:93], v[156:159], v[196:199], v[90:93]
	v_mfma_f32_16x16x32_bf16 v[78:81], v[144:147], v[224:227], v[78:81]
	v_mfma_f32_16x16x32_bf16 v[74:77], v[156:159], v[224:227], v[74:77]
	v_mfma_f32_16x16x32_bf16 v[118:121], v[160:163], v[176:179], v[118:121]
	v_mfma_f32_16x16x32_bf16 v[114:117], v[168:171], v[176:179], v[114:117]
	v_mfma_f32_16x16x32_bf16 v[102:105], v[160:163], v[184:187], v[102:105]
	v_mfma_f32_16x16x32_bf16 v[98:101], v[168:171], v[184:187], v[98:101]
	v_mfma_f32_16x16x32_bf16 v[86:89], v[160:163], v[192:195], v[86:89]
	v_mfma_f32_16x16x32_bf16 v[82:85], v[168:171], v[192:195], v[82:85]
	v_mfma_f32_16x16x32_bf16 v[70:73], v[160:163], v[200:203], v[70:73]
	v_mfma_f32_16x16x32_bf16 v[66:69], v[168:171], v[200:203], v[66:69]
	v_mfma_f32_16x16x32_bf16 v[118:121], v[164:167], v[180:183], v[118:121]
	v_mfma_f32_16x16x32_bf16 v[114:117], v[172:175], v[180:183], v[114:117]
	v_mfma_f32_16x16x32_bf16 v[102:105], v[164:167], v[188:191], v[102:105]
	v_mfma_f32_16x16x32_bf16 v[98:101], v[172:175], v[188:191], v[98:101]
	v_mfma_f32_16x16x32_bf16 v[86:89], v[164:167], v[196:199], v[86:89]
	v_mfma_f32_16x16x32_bf16 v[82:85], v[172:175], v[196:199], v[82:85]
	v_mfma_f32_16x16x32_bf16 v[70:73], v[164:167], v[224:227], v[70:73]
	v_mfma_f32_16x16x32_bf16 v[66:69], v[172:175], v[224:227], v[66:69]
	s_barrier
; #define PG8_STAGE(bufoff, gbase, voff) do { _Pragma("unroll") for (int _i = 0; _i < 2; ++_i) \
;         __builtin_amdgcn_global_load_lds((const unsigned*)((const char*)(gbase) + (voff)[_i]), (PG8_LAS unsigned*)(lds + (bufoff) + ldsw + _i * 8192), 16, 0, 0); } while (0)
; #define PG8_LDA(dst, b, h) do { _Pragma("unroll") for (int m = 0; m < 4; ++m) _Pragma("unroll") for (int k = 0; k < 2; ++k) dst[m][k] = *(const PG8_LAS bf16x8*)(lds + PG8_SA(b, h) + aoff + m * 2048 + k * 1024); } while (0)
; #define PG8_MMA(ai, bj, At, Bt) do { __builtin_amdgcn_s_setprio(1); _Pragma("unroll") for (int m = 0; m < 4; ++m) _Pragma("unroll") for (int n = 0; n < 2; ++n) _Pragma("unroll") for (int k = 0; k < 2; ++k) \
;         acc[ai][bj][m][n] = __builtin_amdgcn_mfma_f32_16x16x32_bf16(Bt[n][k], At[m][k], acc[ai][bj][m][n], 0, 0, 0); __builtin_amdgcn_s_setprio(0); } while (0)
; #define PG8_WAIT_V(n) asm volatile("s_waitcnt vmcnt(" #n ")" ::: "memory")
; #define PG8_WAIT_L(n) asm volatile("s_waitcnt lgkmcnt(" #n ")" ::: "memory")
; #define PG8_BAR __builtin_amdgcn_s_barrier()
; #define PG8_SCHED __builtin_amdgcn_sched_barrier(0)
; template <class Epi, class Sched, bool ALIGN_EPI = false, bool SP2 = false>
; __device__ __forceinline__ void gemm_phase(PG8_LAS unsigned char* lds, const Gemm g, const Sched& S, const Epi& E) {
;     ...
;             PG8_LDA(At, 1, 1); PG8_STAGE(PG8_SB(1, 0), b3, voffB); PG8_STAGE(PG8_SB(1, 1), b3 + hstep, voffB); PG8_STAGE(PG8_SA(1, 0), a3, voffA);
;             PG8_WAIT_V(8); PG8_WAIT_L(0); PG8_BAR; PG8_MMA(1, 0, At, B0); PG8_MMA(1, 1, At, B1); PG8_BAR; PG8_SCHED;
;     __device__ __forceinline__ void operator()(const f32x4 (&acc)[2][2][4][2], const Unit& u, int wr, int wc, int fr, int fq) const {
;     ...
;                 const int row = row0 + ai * 128 + m * 16; float p = 0.f;
; #pragma unroll
;                 for (int bj = 0; bj < 2; ++bj) {
;                     const size_t off = (size_t)row * D + col0 + bj * 128;
;                     const u32x4 xx = *(const u32x4*)(xb + off);
	s_setprio 0
	s_add_i32 s26, s51, s31
	v_lshl_add_u64 v[204:205], v[204:205], 0, s[86:87]
	s_mov_b32 m0, s26
	ds_read_b128 v[176:179], v151 offset:49152
	ds_read_b128 v[180:183], v151 offset:50176
	ds_read_b128 v[184:187], v151 offset:51200
	ds_read_b128 v[188:191], v151 offset:52224
	ds_read_b128 v[192:195], v151 offset:53248
	ds_read_b128 v[196:199], v151 offset:54272
	ds_read_b128 v[200:203], v151 offset:55296
	ds_read_b128 v[224:227], v151 offset:56320
	global_load_lds_dwordx4 v[204:205], off
	s_add_i32 m0, s26, 0x2000
	s_add_u32 s24, s24, 0x40080
	v_lshl_add_u64 v[204:205], v[228:229], 0, s[86:87]
	s_addc_u32 s25, s25, 0
	s_add_i32 s26, s52, s31
	global_load_lds_dwordx4 v[204:205], off
	v_lshl_add_u64 v[204:205], s[24:25], 0, v[0:1]
	s_mov_b32 m0, s26
	s_nop 0
	global_load_lds_dwordx4 v[204:205], off
	v_lshl_add_u64 v[204:205], s[24:25], 0, v[134:135]
	s_add_i32 m0, s26, 0x2000
	s_nop 0
	global_load_lds_dwordx4 v[204:205], off
	v_lshl_add_u64 v[204:205], v[230:231], 0, s[86:87]
	s_mov_b32 m0, s44
	s_nop 0
	global_load_lds_dwordx4 v[204:205], off
	v_lshl_add_u64 v[204:205], v[232:233], 0, s[86:87]
	s_mov_b32 m0, s45
	s_nop 0
	global_load_lds_dwordx4 v[204:205], off
	s_waitcnt vmcnt(8)
	s_waitcnt lgkmcnt(0)
	s_setprio 1
	s_barrier
	v_mfma_f32_16x16x32_bf16 v[62:65], v[138:141], v[176:179], v[62:65]
	v_mfma_f32_16x16x32_bf16 v[58:61], v[152:155], v[176:179], v[58:61]
	v_mfma_f32_16x16x32_bf16 v[46:49], v[138:141], v[184:187], v[46:49]
	v_mfma_f32_16x16x32_bf16 v[42:45], v[152:155], v[184:187], v[42:45]
	v_mfma_f32_16x16x32_bf16 v[30:33], v[138:141], v[192:195], v[30:33]
	v_mfma_f32_16x16x32_bf16 v[26:29], v[152:155], v[192:195], v[26:29]
	v_mfma_f32_16x16x32_bf16 v[14:17], v[138:141], v[200:203], v[14:17]
	v_mfma_f32_16x16x32_bf16 v[10:13], v[152:155], v[200:203], v[10:13]
	v_mfma_f32_16x16x32_bf16 v[62:65], v[144:147], v[180:183], v[62:65]
	v_mfma_f32_16x16x32_bf16 v[58:61], v[156:159], v[180:183], v[58:61]
	v_mfma_f32_16x16x32_bf16 v[46:49], v[144:147], v[188:191], v[46:49]
	v_mfma_f32_16x16x32_bf16 v[42:45], v[156:159], v[188:191], v[42:45]
	v_mfma_f32_16x16x32_bf16 v[30:33], v[144:147], v[196:199], v[30:33]
	v_mfma_f32_16x16x32_bf16 v[26:29], v[156:159], v[196:199], v[26:29]
	v_mfma_f32_16x16x32_bf16 v[14:17], v[144:147], v[224:227], v[14:17]
	v_mfma_f32_16x16x32_bf16 v[10:13], v[156:159], v[224:227], v[10:13]
	v_mfma_f32_16x16x32_bf16 v[54:57], v[160:163], v[176:179], v[54:57]
	v_mfma_f32_16x16x32_bf16 v[50:53], v[168:171], v[176:179], v[50:53]
	v_mfma_f32_16x16x32_bf16 v[38:41], v[160:163], v[184:187], v[38:41]
	v_mfma_f32_16x16x32_bf16 v[34:37], v[168:171], v[184:187], v[34:37]
	v_mfma_f32_16x16x32_bf16 v[22:25], v[160:163], v[192:195], v[22:25]
	v_mfma_f32_16x16x32_bf16 v[18:21], v[168:171], v[192:195], v[18:21]
	v_mfma_f32_16x16x32_bf16 v[6:9], v[160:163], v[200:203], v[6:9]
	v_mfma_f32_16x16x32_bf16 v[2:5], v[168:171], v[200:203], v[2:5]
	v_mfma_f32_16x16x32_bf16 v[54:57], v[164:167], v[180:183], v[54:57]
	v_mfma_f32_16x16x32_bf16 v[50:53], v[172:175], v[180:183], v[50:53]
	v_mfma_f32_16x16x32_bf16 v[38:41], v[164:167], v[188:191], v[38:41]
	v_mfma_f32_16x16x32_bf16 v[34:37], v[172:175], v[188:191], v[34:37]
	v_mfma_f32_16x16x32_bf16 v[22:25], v[164:167], v[196:199], v[22:25]
	v_mfma_f32_16x16x32_bf16 v[18:21], v[172:175], v[196:199], v[18:21]
	v_mfma_f32_16x16x32_bf16 v[6:9], v[164:167], v[224:227], v[6:9]
	v_mfma_f32_16x16x32_bf16 v[2:5], v[172:175], v[224:227], v[2:5]
	s_barrier
	s_setprio 0
	s_add_i32 s50, s50, 2
	s_add_u32 s22, s22, 0x100
	s_addc_u32 s23, s23, 0
	s_add_u32 s48, s48, 0x100
	s_addc_u32 s49, s49, 0
	s_cmp_gt_u32 s50, 13
	s_cbranch_scc0 .LBB0_1050
	v_lshl_add_u32 v138, s20, 8, v148
	v_lshl_or_b32 v139, s18, 8, v150
	v_lshlrev_b32_e32 v138, 11, v138
	v_lshl_add_u32 v138, v139, 1, v138
	global_load_dwordx4 v[152:155], v138, s[34:35]
	global_load_dwordx4 v[156:159], v138, s[34:35] offset:256
	v_add_u32_e32 v139, 0x8000, v138
	global_load_dwordx4 v[160:163], v139, s[34:35]
	global_load_dwordx4 v[164:167], v139, s[34:35] offset:256
	v_add_u32_e32 v139, 0x10000, v138
	global_load_dwordx4 v[168:171], v139, s[34:35]
	global_load_dwordx4 v[172:175], v139, s[34:35] offset:256
	v_add_u32_e32 v139, 0x18000, v138
	global_load_dwordx4 v[176:179], v139, s[34:35]
	global_load_dwordx4 v[180:183], v139, s[34:35] offset:256
	v_add_u32_e32 v139, 0x40000, v138
	global_load_dwordx4 v[184:187], v139, s[34:35]
	global_load_dwordx4 v[188:191], v139, s[34:35] offset:256
	v_add_u32_e32 v139, 0x48000, v138
	global_load_dwordx4 v[192:195], v139, s[34:35]
	global_load_dwordx4 v[196:199], v139, s[34:35] offset:256
	v_add_u32_e32 v139, 0x50000, v138
	global_load_dwordx4 v[200:203], v139, s[34:35]
	global_load_dwordx4 v[224:227], v139, s[34:35] offset:256
	v_add_u32_e32 v139, 0x58000, v138
	global_load_dwordx4 v[228:231], v139, s[34:35]
	global_load_dwordx4 v[232:235], v139, s[34:35] offset:256
	s_and_b64 vcc, exec, s[8:9]
	s_cbranch_vccz .LBB0_1053
	s_barrier
